# v12 + MFMA snake order without accumulator pairing (srcA strictly held for 4 MFMAs)
# baseline (speedup 1.0000x reference)
; #define PG8_STAGE(bufoff, gbase, voff) do { _Pragma("unroll") for (int _i = 0; _i < 2; ++_i) \
;         __builtin_amdgcn_global_load_lds((const unsigned*)((const char*)(gbase) + (voff)[_i]), (PG8_LAS unsigned*)(lds + (bufoff) + ldsw + _i * 8192), 16, 0, 0); } while (0)
; #define PG8_LDA(dst, b, h) do { _Pragma("unroll") for (int m = 0; m < 4; ++m) _Pragma("unroll") for (int k = 0; k < 2; ++k) dst[m][k] = *(const PG8_LAS bf16x8*)(lds + PG8_SA(b, h) + aoff + m * 2048 + k * 1024); } while (0)
; #define PG8_LDB(dst, b, h) do { _Pragma("unroll") for (int n = 0; n < 2; ++n) _Pragma("unroll") for (int k = 0; k < 2; ++k) dst[n][k] = *(const PG8_LAS bf16x8*)(lds + PG8_SB(b, h) + boff + n * 2048 + k * 1024); } while (0)
; #define PG8_MMA(ai, bj, At, Bt) do { __builtin_amdgcn_s_setprio(1); _Pragma("unroll") for (int m = 0; m < 4; ++m) _Pragma("unroll") for (int n = 0; n < 2; ++n) _Pragma("unroll") for (int k = 0; k < 2; ++k) \
;         acc[ai][bj][m][n] = __builtin_amdgcn_mfma_f32_16x16x32_bf16(Bt[n][k], At[m][k], acc[ai][bj][m][n], 0, 0, 0); __builtin_amdgcn_s_setprio(0); } while (0)
; #define PG8_WAIT_V(n) asm volatile("s_waitcnt vmcnt(" #n ")" ::: "memory")
; #define PG8_WAIT_L(n) asm volatile("s_waitcnt lgkmcnt(" #n ")" ::: "memory")
; template <class Epi, class Sched, bool ALIGN_EPI = false, bool SP2 = false>
; __device__ __forceinline__ void gemm_phase(PG8_LAS unsigned char* lds, const Gemm g, const Sched& S, const Epi& E) {
;     ...
;             const bool last = (t == nt - 2);
;             const char* a1 = cA + (size_t)(t + 1) * kstep;
;             const char* a2 = last ? nA : cA + (size_t)(t + 2) * kstep; const char* b2 = last ? nB : cB + (size_t)(t + 2) * kstep;
;             const char* a3 = a2 + kstep; const char* b3 = b2 + kstep;
;             if (last && has_next) S.a_ready(nxt);
;             if constexpr (SP2) {
;             PG8_LDB(B0, 0, 0); PG8_LDB(B1, 0, 1); PG8_SCHED; PG8_LDA(At, 0, 0); PG8_STAGE(PG8_SA(1, 1), a1 + hstep, voffA);
;             PG8_WAIT_V(8); PG8_WAIT_L(0); PG8_BAR; PG8_MMA(0, 0, At, B0); PG8_MMA(0, 1, At, B1); PG8_BAR; PG8_SCHED;
;             PG8_LDA(At, 0, 1); PG8_STAGE(PG8_SB(0, 0), b2, voffB); PG8_STAGE(PG8_SB(0, 1), b2 + hstep, voffB); PG8_STAGE(PG8_SA(0, 0), a2, voffA);
;             PG8_WAIT_V(8); PG8_WAIT_L(0); PG8_BAR; PG8_MMA(1, 0, At, B0); PG8_MMA(1, 1, At, B1); PG8_BAR; PG8_SCHED;
.LBB0_202:
	s_add_i32 s78, s38, 2
	s_add_u32 s79, s22, 0x80
	s_addc_u32 s39, s23, 0
	s_cmp_eq_u32 s33, s38
	s_cselect_b32 s39, s7, s39
	s_cselect_b32 s38, s6, s79
	v_add_u32_e32 v0, s19, v150
	s_cselect_b32 s81, s17, s77
	s_cselect_b32 s80, s16, s76
	s_add_i32 s79, 0, 0x14000
	ds_read_b128 v[152:155], v0
	ds_read_b128 v[156:159], v0 offset:1024
	ds_read_b128 v[160:163], v0 offset:2048
	ds_read_b128 v[164:167], v0 offset:3072
	v_add_u32_e32 v0, s79, v150
	ds_read_b128 v[168:171], v0
	ds_read_b128 v[172:175], v0 offset:1024
	ds_read_b128 v[176:179], v0 offset:2048
	ds_read_b128 v[184:187], v0 offset:3072
	v_lshl_add_u64 v[2:3], s[22:23], 0, v[144:145]
	s_add_i32 m0, s42, 0xc000
	ds_read_b128 v[188:191], v151
	ds_read_b128 v[192:195], v151 offset:1024
	ds_read_b128 v[196:199], v151 offset:2048
	ds_read_b128 v[200:203], v151 offset:3072
	ds_read_b128 v[204:207], v151 offset:4096
	ds_read_b128 v[230:233], v151 offset:5120
	ds_read_b128 v[234:237], v151 offset:6144
	ds_read_b128 v[238:241], v151 offset:7168
	global_load_lds_dwordx4 v[2:3], off
	v_lshl_add_u64 v[2:3], s[22:23], 0, v[146:147]
	s_add_i32 m0, s42, 0xe000
	s_nop 0
	global_load_lds_dwordx4 v[2:3], off
	s_waitcnt vmcnt(8)
	s_waitcnt lgkmcnt(0)
	s_barrier
	s_setprio 1
	s_waitcnt lgkmcnt(0)
	v_mfma_f32_16x16x32_bf16 v[132:135], v[152:155], v[188:191], v[132:135]
	v_mfma_f32_16x16x32_bf16 v[116:119], v[152:155], v[196:199], v[116:119]
	v_mfma_f32_16x16x32_bf16 v[100:103], v[152:155], v[204:207], v[100:103]
	v_mfma_f32_16x16x32_bf16 v[84:87], v[152:155], v[234:237], v[84:87]
	v_mfma_f32_16x16x32_bf16 v[80:83], v[160:163], v[234:237], v[80:83]
	v_mfma_f32_16x16x32_bf16 v[96:99], v[160:163], v[204:207], v[96:99]
	v_mfma_f32_16x16x32_bf16 v[112:115], v[160:163], v[196:199], v[112:115]
	v_mfma_f32_16x16x32_bf16 v[128:131], v[160:163], v[188:191], v[128:131]
	v_mfma_f32_16x16x32_bf16 v[132:135], v[156:159], v[192:195], v[132:135]
	v_mfma_f32_16x16x32_bf16 v[116:119], v[156:159], v[200:203], v[116:119]
	v_mfma_f32_16x16x32_bf16 v[100:103], v[156:159], v[230:233], v[100:103]
	v_mfma_f32_16x16x32_bf16 v[84:87], v[156:159], v[238:241], v[84:87]
	v_mfma_f32_16x16x32_bf16 v[80:83], v[164:167], v[238:241], v[80:83]
	v_mfma_f32_16x16x32_bf16 v[96:99], v[164:167], v[230:233], v[96:99]
	v_mfma_f32_16x16x32_bf16 v[112:115], v[164:167], v[200:203], v[112:115]
	v_mfma_f32_16x16x32_bf16 v[128:131], v[164:167], v[192:195], v[128:131]
	s_setprio 0
	s_setprio 1
	v_mfma_f32_16x16x32_bf16 v[124:127], v[168:171], v[188:191], v[124:127]
	v_mfma_f32_16x16x32_bf16 v[108:111], v[168:171], v[196:199], v[108:111]
	v_mfma_f32_16x16x32_bf16 v[92:95], v[168:171], v[204:207], v[92:95]
	v_mfma_f32_16x16x32_bf16 v[76:79], v[168:171], v[234:237], v[76:79]
	v_mfma_f32_16x16x32_bf16 v[72:75], v[176:179], v[234:237], v[72:75]
	v_mfma_f32_16x16x32_bf16 v[88:91], v[176:179], v[204:207], v[88:91]
	v_mfma_f32_16x16x32_bf16 v[104:107], v[176:179], v[196:199], v[104:107]
	v_mfma_f32_16x16x32_bf16 v[120:123], v[176:179], v[188:191], v[120:123]
	v_mfma_f32_16x16x32_bf16 v[124:127], v[172:175], v[192:195], v[124:127]
	v_mfma_f32_16x16x32_bf16 v[108:111], v[172:175], v[200:203], v[108:111]
	v_mfma_f32_16x16x32_bf16 v[92:95], v[172:175], v[230:233], v[92:95]
	v_mfma_f32_16x16x32_bf16 v[76:79], v[172:175], v[238:241], v[76:79]
	v_mfma_f32_16x16x32_bf16 v[72:75], v[184:187], v[238:241], v[72:75]
	v_mfma_f32_16x16x32_bf16 v[88:91], v[184:187], v[230:233], v[88:91]
	v_mfma_f32_16x16x32_bf16 v[104:107], v[184:187], v[200:203], v[104:107]
	v_mfma_f32_16x16x32_bf16 v[120:123], v[184:187], v[192:195], v[120:123]
	s_setprio 0
	s_barrier
	s_add_i32 s82, s19, s20
	v_lshl_add_u64 v[2:3], s[80:81], 0, v[140:141]
	s_mov_b32 m0, s82
	ds_read_b128 v[188:191], v151 offset:16384
	ds_read_b128 v[192:195], v151 offset:17408
	ds_read_b128 v[196:199], v151 offset:18432
	ds_read_b128 v[200:203], v151 offset:19456
	ds_read_b128 v[204:207], v151 offset:20480
	ds_read_b128 v[230:233], v151 offset:21504
	ds_read_b128 v[234:237], v151 offset:22528
	ds_read_b128 v[238:241], v151 offset:23552
	global_load_lds_dwordx4 v[2:3], off
	s_add_i32 m0, s82, 0x2000
	v_lshl_add_u64 v[180:181], s[80:81], 0, v[136:137]
	s_add_u32 s80, s80, s48
	s_addc_u32 s81, s81, s49
	s_add_i32 s79, s79, s20
	global_load_lds_dwordx4 v[180:181], off
	v_lshl_add_u64 v[208:209], s[80:81], 0, v[140:141]
	s_mov_b32 m0, s79
	v_lshl_add_u64 v[216:217], s[80:81], 0, v[136:137]
	global_load_lds_dwordx4 v[208:209], off
	s_add_i32 m0, s79, 0x2000
	v_lshl_add_u64 v[224:225], s[38:39], 0, v[142:143]
	global_load_lds_dwordx4 v[216:217], off
	s_mov_b32 m0, s42
	v_lshl_add_u64 v[226:227], s[38:39], 0, v[138:139]
	global_load_lds_dwordx4 v[224:225], off
	s_mov_b32 m0, s45
	s_nop 0
	global_load_lds_dwordx4 v[226:227], off
	s_waitcnt vmcnt(8)
	s_waitcnt lgkmcnt(0)
	s_barrier
; #define PG8_STAGE(bufoff, gbase, voff) do { _Pragma("unroll") for (int _i = 0; _i < 2; ++_i) \
;         __builtin_amdgcn_global_load_lds((const unsigned*)((const char*)(gbase) + (voff)[_i]), (PG8_LAS unsigned*)(lds + (bufoff) + ldsw + _i * 8192), 16, 0, 0); } while (0)
; #define PG8_LDA(dst, b, h) do { _Pragma("unroll") for (int m = 0; m < 4; ++m) _Pragma("unroll") for (int k = 0; k < 2; ++k) dst[m][k] = *(const PG8_LAS bf16x8*)(lds + PG8_SA(b, h) + aoff + m * 2048 + k * 1024); } while (0)
; #define PG8_LDB(dst, b, h) do { _Pragma("unroll") for (int n = 0; n < 2; ++n) _Pragma("unroll") for (int k = 0; k < 2; ++k) dst[n][k] = *(const PG8_LAS bf16x8*)(lds + PG8_SB(b, h) + boff + n * 2048 + k * 1024); } while (0)
; #define PG8_MMA(ai, bj, At, Bt) do { __builtin_amdgcn_s_setprio(1); _Pragma("unroll") for (int m = 0; m < 4; ++m) _Pragma("unroll") for (int n = 0; n < 2; ++n) _Pragma("unroll") for (int k = 0; k < 2; ++k) \
;         acc[ai][bj][m][n] = __builtin_amdgcn_mfma_f32_16x16x32_bf16(Bt[n][k], At[m][k], acc[ai][bj][m][n], 0, 0, 0); __builtin_amdgcn_s_setprio(0); } while (0)
; #define PG8_WAIT_V(n) asm volatile("s_waitcnt vmcnt(" #n ")" ::: "memory")
; #define PG8_WAIT_L(n) asm volatile("s_waitcnt lgkmcnt(" #n ")" ::: "memory")
; #define PG8_BAR __builtin_amdgcn_s_barrier()
; #define PG8_SCHED __builtin_amdgcn_sched_barrier(0)
; template <class Epi, class Sched, bool ALIGN_EPI = false, bool SP2 = false>
; __device__ __forceinline__ void gemm_phase(PG8_LAS unsigned char* lds, const Gemm g, const Sched& S, const Epi& E) {
;     ...
;             PG8_WAIT_V(8); PG8_WAIT_L(0); PG8_BAR; PG8_MMA(1, 0, At, B0); PG8_MMA(1, 1, At, B1); PG8_BAR; PG8_SCHED;
;             PG8_LDB(B0, 1, 0); PG8_LDB(B1, 1, 1); PG8_SCHED; PG8_LDA(At, 1, 0); PG8_STAGE(PG8_SA(0, 1), a2 + hstep, voffA);
;             PG8_WAIT_V(8); PG8_WAIT_L(0); PG8_BAR; PG8_MMA(0, 0, At, B0); PG8_MMA(0, 1, At, B1); PG8_BAR; PG8_SCHED;
	s_setprio 1
	s_waitcnt lgkmcnt(0)
	v_mfma_f32_16x16x32_bf16 v[68:71], v[152:155], v[188:191], v[68:71]
	v_mfma_f32_16x16x32_bf16 v[52:55], v[152:155], v[196:199], v[52:55]
	v_mfma_f32_16x16x32_bf16 v[36:39], v[152:155], v[204:207], v[36:39]
	v_mfma_f32_16x16x32_bf16 v[20:23], v[152:155], v[234:237], v[20:23]
	v_mfma_f32_16x16x32_bf16 v[16:19], v[160:163], v[234:237], v[16:19]
	v_mfma_f32_16x16x32_bf16 v[32:35], v[160:163], v[204:207], v[32:35]
	v_mfma_f32_16x16x32_bf16 v[48:51], v[160:163], v[196:199], v[48:51]
	v_mfma_f32_16x16x32_bf16 v[64:67], v[160:163], v[188:191], v[64:67]
	v_mfma_f32_16x16x32_bf16 v[68:71], v[156:159], v[192:195], v[68:71]
	v_mfma_f32_16x16x32_bf16 v[52:55], v[156:159], v[200:203], v[52:55]
	v_mfma_f32_16x16x32_bf16 v[36:39], v[156:159], v[230:233], v[36:39]
	v_mfma_f32_16x16x32_bf16 v[20:23], v[156:159], v[238:241], v[20:23]
	v_mfma_f32_16x16x32_bf16 v[16:19], v[164:167], v[238:241], v[16:19]
	v_mfma_f32_16x16x32_bf16 v[32:35], v[164:167], v[230:233], v[32:35]
	v_mfma_f32_16x16x32_bf16 v[48:51], v[164:167], v[200:203], v[48:51]
	v_mfma_f32_16x16x32_bf16 v[64:67], v[164:167], v[192:195], v[64:67]
	s_setprio 0
	s_setprio 1
	v_mfma_f32_16x16x32_bf16 v[60:63], v[168:171], v[188:191], v[60:63]
	v_mfma_f32_16x16x32_bf16 v[44:47], v[168:171], v[196:199], v[44:47]
	v_mfma_f32_16x16x32_bf16 v[28:31], v[168:171], v[204:207], v[28:31]
	v_mfma_f32_16x16x32_bf16 v[12:15], v[168:171], v[234:237], v[12:15]
	v_mfma_f32_16x16x32_bf16 v[8:11], v[176:179], v[234:237], v[8:11]
	v_mfma_f32_16x16x32_bf16 v[24:27], v[176:179], v[204:207], v[24:27]
	v_mfma_f32_16x16x32_bf16 v[40:43], v[176:179], v[196:199], v[40:43]
	v_mfma_f32_16x16x32_bf16 v[56:59], v[176:179], v[188:191], v[56:59]
	v_mfma_f32_16x16x32_bf16 v[60:63], v[172:175], v[192:195], v[60:63]
	v_mfma_f32_16x16x32_bf16 v[44:47], v[172:175], v[200:203], v[44:47]
	v_mfma_f32_16x16x32_bf16 v[28:31], v[172:175], v[230:233], v[28:31]
	v_mfma_f32_16x16x32_bf16 v[12:15], v[172:175], v[238:241], v[12:15]
	v_mfma_f32_16x16x32_bf16 v[8:11], v[184:187], v[238:241], v[8:11]
	v_mfma_f32_16x16x32_bf16 v[24:27], v[184:187], v[230:233], v[24:27]
	v_mfma_f32_16x16x32_bf16 v[40:43], v[184:187], v[200:203], v[40:43]
	v_mfma_f32_16x16x32_bf16 v[56:59], v[184:187], v[192:195], v[56:59]
	s_setprio 0
	s_barrier
	v_add_u32_e32 v0, s91, v150
	s_add_i32 s79, 0, 0x1c000
	ds_read_b128 v[152:155], v0
	ds_read_b128 v[156:159], v0 offset:1024
	ds_read_b128 v[160:163], v0 offset:2048
	ds_read_b128 v[164:167], v0 offset:3072
	v_add_u32_e32 v0, s79, v150
	ds_read_b128 v[168:171], v0
	ds_read_b128 v[172:175], v0 offset:1024
	ds_read_b128 v[176:179], v0 offset:2048
	ds_read_b128 v[184:187], v0 offset:3072
	s_add_u32 s38, s38, s48
	s_addc_u32 s39, s39, s49
	s_mov_b32 m0, s46
	v_lshl_add_u64 v[228:229], s[38:39], 0, v[142:143]
	ds_read_b128 v[188:191], v151 offset:32768
	ds_read_b128 v[192:195], v151 offset:33792
	ds_read_b128 v[196:199], v151 offset:34816
	ds_read_b128 v[200:203], v151 offset:35840
	ds_read_b128 v[204:207], v151 offset:36864
	ds_read_b128 v[230:233], v151 offset:37888
	ds_read_b128 v[234:237], v151 offset:38912
	ds_read_b128 v[238:241], v151 offset:39936
	global_load_lds_dwordx4 v[228:229], off
	v_lshl_add_u64 v[228:229], s[38:39], 0, v[138:139]
	s_mov_b32 m0, s47
	s_nop 0
	global_load_lds_dwordx4 v[228:229], off
	s_waitcnt vmcnt(8)
	s_waitcnt lgkmcnt(0)
	s_barrier
	s_setprio 1
	s_waitcnt lgkmcnt(0)
	v_mfma_f32_16x16x32_bf16 v[132:135], v[152:155], v[188:191], v[132:135]
	v_mfma_f32_16x16x32_bf16 v[116:119], v[152:155], v[196:199], v[116:119]
	v_mfma_f32_16x16x32_bf16 v[100:103], v[152:155], v[204:207], v[100:103]
	v_mfma_f32_16x16x32_bf16 v[84:87], v[152:155], v[234:237], v[84:87]
	v_mfma_f32_16x16x32_bf16 v[80:83], v[160:163], v[234:237], v[80:83]
	v_mfma_f32_16x16x32_bf16 v[96:99], v[160:163], v[204:207], v[96:99]
	v_mfma_f32_16x16x32_bf16 v[112:115], v[160:163], v[196:199], v[112:115]
	v_mfma_f32_16x16x32_bf16 v[128:131], v[160:163], v[188:191], v[128:131]
	v_mfma_f32_16x16x32_bf16 v[132:135], v[156:159], v[192:195], v[132:135]
	v_mfma_f32_16x16x32_bf16 v[116:119], v[156:159], v[200:203], v[116:119]
	v_mfma_f32_16x16x32_bf16 v[100:103], v[156:159], v[230:233], v[100:103]
	v_mfma_f32_16x16x32_bf16 v[84:87], v[156:159], v[238:241], v[84:87]
	v_mfma_f32_16x16x32_bf16 v[80:83], v[164:167], v[238:241], v[80:83]
	v_mfma_f32_16x16x32_bf16 v[96:99], v[164:167], v[230:233], v[96:99]
	v_mfma_f32_16x16x32_bf16 v[112:115], v[164:167], v[200:203], v[112:115]
	v_mfma_f32_16x16x32_bf16 v[128:131], v[164:167], v[192:195], v[128:131]
	s_setprio 0
	s_setprio 1
	v_mfma_f32_16x16x32_bf16 v[124:127], v[168:171], v[188:191], v[124:127]
	v_mfma_f32_16x16x32_bf16 v[108:111], v[168:171], v[196:199], v[108:111]
	v_mfma_f32_16x16x32_bf16 v[92:95], v[168:171], v[204:207], v[92:95]
	v_mfma_f32_16x16x32_bf16 v[76:79], v[168:171], v[234:237], v[76:79]
	v_mfma_f32_16x16x32_bf16 v[72:75], v[176:179], v[234:237], v[72:75]
	v_mfma_f32_16x16x32_bf16 v[88:91], v[176:179], v[204:207], v[88:91]
	v_mfma_f32_16x16x32_bf16 v[104:107], v[176:179], v[196:199], v[104:107]
	v_mfma_f32_16x16x32_bf16 v[120:123], v[176:179], v[188:191], v[120:123]
	v_mfma_f32_16x16x32_bf16 v[124:127], v[172:175], v[192:195], v[124:127]
	v_mfma_f32_16x16x32_bf16 v[108:111], v[172:175], v[200:203], v[108:111]
	v_mfma_f32_16x16x32_bf16 v[92:95], v[172:175], v[230:233], v[92:95]
	v_mfma_f32_16x16x32_bf16 v[76:79], v[172:175], v[238:241], v[76:79]
	v_mfma_f32_16x16x32_bf16 v[72:75], v[184:187], v[238:241], v[72:75]
	v_mfma_f32_16x16x32_bf16 v[88:91], v[184:187], v[230:233], v[88:91]
	v_mfma_f32_16x16x32_bf16 v[104:107], v[184:187], v[200:203], v[104:107]
	v_mfma_f32_16x16x32_bf16 v[120:123], v[184:187], v[192:195], v[120:123]
	s_setprio 0
	s_barrier
; #define PG8_STAGE(bufoff, gbase, voff) do { _Pragma("unroll") for (int _i = 0; _i < 2; ++_i) \
;         __builtin_amdgcn_global_load_lds((const unsigned*)((const char*)(gbase) + (voff)[_i]), (PG8_LAS unsigned*)(lds + (bufoff) + ldsw + _i * 8192), 16, 0, 0); } while (0)
; #define PG8_LDA(dst, b, h) do { _Pragma("unroll") for (int m = 0; m < 4; ++m) _Pragma("unroll") for (int k = 0; k < 2; ++k) dst[m][k] = *(const PG8_LAS bf16x8*)(lds + PG8_SA(b, h) + aoff + m * 2048 + k * 1024); } while (0)
; #define PG8_MMA(ai, bj, At, Bt) do { __builtin_amdgcn_s_setprio(1); _Pragma("unroll") for (int m = 0; m < 4; ++m) _Pragma("unroll") for (int n = 0; n < 2; ++n) _Pragma("unroll") for (int k = 0; k < 2; ++k) \
;         acc[ai][bj][m][n] = __builtin_amdgcn_mfma_f32_16x16x32_bf16(Bt[n][k], At[m][k], acc[ai][bj][m][n], 0, 0, 0); __builtin_amdgcn_s_setprio(0); } while (0)
; #define PG8_WAIT_V(n) asm volatile("s_waitcnt vmcnt(" #n ")" ::: "memory")
; #define PG8_WAIT_L(n) asm volatile("s_waitcnt lgkmcnt(" #n ")" ::: "memory")
; #define PG8_BAR __builtin_amdgcn_s_barrier()
; #define PG8_SCHED __builtin_amdgcn_sched_barrier(0)
; template <class Epi, class Sched, bool ALIGN_EPI = false, bool SP2 = false>
; __device__ __forceinline__ void gemm_phase(PG8_LAS unsigned char* lds, const Gemm g, const Sched& S, const Epi& E) {
;     ...
;             PG8_LDA(At, 1, 1); PG8_STAGE(PG8_SB(1, 0), b3, voffB); PG8_STAGE(PG8_SB(1, 1), b3 + hstep, voffB); PG8_STAGE(PG8_SA(1, 0), a3, voffA);
;             PG8_WAIT_V(8); PG8_WAIT_L(0); PG8_BAR; PG8_MMA(1, 0, At, B0); PG8_MMA(1, 1, At, B1); PG8_BAR; PG8_SCHED;
	s_add_i32 s38, s91, s20
	v_lshl_add_u64 v[2:3], v[2:3], 0, s[24:25]
	s_mov_b32 m0, s38
	ds_read_b128 v[188:191], v151 offset:49152
	ds_read_b128 v[192:195], v151 offset:50176
	ds_read_b128 v[196:199], v151 offset:51200
	ds_read_b128 v[200:203], v151 offset:52224
	ds_read_b128 v[204:207], v151 offset:53248
	ds_read_b128 v[230:233], v151 offset:54272
	ds_read_b128 v[234:237], v151 offset:55296
	ds_read_b128 v[238:241], v151 offset:56320
	global_load_lds_dwordx4 v[2:3], off
	v_lshl_add_u64 v[2:3], v[180:181], 0, s[24:25]
	s_add_i32 m0, s38, 0x2000
	s_add_i32 s38, s79, s20
	global_load_lds_dwordx4 v[2:3], off
	v_lshl_add_u64 v[2:3], v[208:209], 0, s[24:25]
	s_mov_b32 m0, s38
	s_nop 0
	global_load_lds_dwordx4 v[2:3], off
	v_lshl_add_u64 v[2:3], v[216:217], 0, s[24:25]
	s_add_i32 m0, s38, 0x2000
	s_nop 0
	global_load_lds_dwordx4 v[2:3], off
	v_lshl_add_u64 v[2:3], v[224:225], 0, s[24:25]
	s_mov_b32 m0, s52
	s_nop 0
	global_load_lds_dwordx4 v[2:3], off
	v_lshl_add_u64 v[2:3], v[226:227], 0, s[24:25]
	s_mov_b32 m0, s53
	s_nop 0
	global_load_lds_dwordx4 v[2:3], off
	s_waitcnt vmcnt(8)
	s_waitcnt lgkmcnt(0)
	s_barrier
	s_setprio 1
	s_waitcnt lgkmcnt(0)
	v_mfma_f32_16x16x32_bf16 v[68:71], v[152:155], v[188:191], v[68:71]
	v_mfma_f32_16x16x32_bf16 v[52:55], v[152:155], v[196:199], v[52:55]
	v_mfma_f32_16x16x32_bf16 v[36:39], v[152:155], v[204:207], v[36:39]
	v_mfma_f32_16x16x32_bf16 v[20:23], v[152:155], v[234:237], v[20:23]
	v_mfma_f32_16x16x32_bf16 v[16:19], v[160:163], v[234:237], v[16:19]
	v_mfma_f32_16x16x32_bf16 v[32:35], v[160:163], v[204:207], v[32:35]
	v_mfma_f32_16x16x32_bf16 v[48:51], v[160:163], v[196:199], v[48:51]
	v_mfma_f32_16x16x32_bf16 v[64:67], v[160:163], v[188:191], v[64:67]
	v_mfma_f32_16x16x32_bf16 v[68:71], v[156:159], v[192:195], v[68:71]
	v_mfma_f32_16x16x32_bf16 v[52:55], v[156:159], v[200:203], v[52:55]
	v_mfma_f32_16x16x32_bf16 v[36:39], v[156:159], v[230:233], v[36:39]
	v_mfma_f32_16x16x32_bf16 v[20:23], v[156:159], v[238:241], v[20:23]
	v_mfma_f32_16x16x32_bf16 v[16:19], v[164:167], v[238:241], v[16:19]
	v_mfma_f32_16x16x32_bf16 v[32:35], v[164:167], v[230:233], v[32:35]
	v_mfma_f32_16x16x32_bf16 v[48:51], v[164:167], v[200:203], v[48:51]
	v_mfma_f32_16x16x32_bf16 v[64:67], v[164:167], v[192:195], v[64:67]
	s_setprio 0
	s_setprio 1
	v_mfma_f32_16x16x32_bf16 v[60:63], v[168:171], v[188:191], v[60:63]
	v_mfma_f32_16x16x32_bf16 v[44:47], v[168:171], v[196:199], v[44:47]
	v_mfma_f32_16x16x32_bf16 v[28:31], v[168:171], v[204:207], v[28:31]
	v_mfma_f32_16x16x32_bf16 v[12:15], v[168:171], v[234:237], v[12:15]
	v_mfma_f32_16x16x32_bf16 v[8:11], v[176:179], v[234:237], v[8:11]
	v_mfma_f32_16x16x32_bf16 v[24:27], v[176:179], v[204:207], v[24:27]
	v_mfma_f32_16x16x32_bf16 v[40:43], v[176:179], v[196:199], v[40:43]
	v_mfma_f32_16x16x32_bf16 v[56:59], v[176:179], v[188:191], v[56:59]
	v_mfma_f32_16x16x32_bf16 v[60:63], v[172:175], v[192:195], v[60:63]
	v_mfma_f32_16x16x32_bf16 v[44:47], v[172:175], v[200:203], v[44:47]
	v_mfma_f32_16x16x32_bf16 v[28:31], v[172:175], v[230:233], v[28:31]
	v_mfma_f32_16x16x32_bf16 v[12:15], v[172:175], v[238:241], v[12:15]
	v_mfma_f32_16x16x32_bf16 v[8:11], v[184:187], v[238:241], v[8:11]
	v_mfma_f32_16x16x32_bf16 v[24:27], v[184:187], v[230:233], v[24:27]
	v_mfma_f32_16x16x32_bf16 v[40:43], v[184:187], v[200:203], v[40:43]
	v_mfma_f32_16x16x32_bf16 v[56:59], v[184:187], v[192:195], v[56:59]
	s_setprio 0
	s_barrier
	s_add_u32 s22, s22, 0x100
	s_addc_u32 s23, s23, 0
	s_add_u32 s76, s76, 0x100
	s_addc_u32 s77, s77, 0
	s_cmp_ge_u32 s78, s9
	s_mov_b32 s38, s78
	s_cbranch_scc0 .LBB0_202

; #define PG8_STAGE(bufoff, gbase, voff) do { _Pragma("unroll") for (int _i = 0; _i < 2; ++_i) \
;         __builtin_amdgcn_global_load_lds((const unsigned*)((const char*)(gbase) + (voff)[_i]), (PG8_LAS unsigned*)(lds + (bufoff) + ldsw + _i * 8192), 16, 0, 0); } while (0)
; #define PG8_LDA(dst, b, h) do { _Pragma("unroll") for (int m = 0; m < 4; ++m) _Pragma("unroll") for (int k = 0; k < 2; ++k) dst[m][k] = *(const PG8_LAS bf16x8*)(lds + PG8_SA(b, h) + aoff + m * 2048 + k * 1024); } while (0)
; #define PG8_LDB(dst, b, h) do { _Pragma("unroll") for (int n = 0; n < 2; ++n) _Pragma("unroll") for (int k = 0; k < 2; ++k) dst[n][k] = *(const PG8_LAS bf16x8*)(lds + PG8_SB(b, h) + boff + n * 2048 + k * 1024); } while (0)
; #define PG8_MMA(ai, bj, At, Bt) do { __builtin_amdgcn_s_setprio(1); _Pragma("unroll") for (int m = 0; m < 4; ++m) _Pragma("unroll") for (int n = 0; n < 2; ++n) _Pragma("unroll") for (int k = 0; k < 2; ++k) \
;         acc[ai][bj][m][n] = __builtin_amdgcn_mfma_f32_16x16x32_bf16(Bt[n][k], At[m][k], acc[ai][bj][m][n], 0, 0, 0); __builtin_amdgcn_s_setprio(0); } while (0)
; #define PG8_WAIT_V(n) asm volatile("s_waitcnt vmcnt(" #n ")" ::: "memory")
; #define PG8_WAIT_L(n) asm volatile("s_waitcnt lgkmcnt(" #n ")" ::: "memory")
; #define PG8_BAR __builtin_amdgcn_s_barrier()
; #define PG8_SCHED __builtin_amdgcn_sched_barrier(0)
; template <class Epi, class Sched, bool ALIGN_EPI = false, bool SP2 = false>
; __device__ __forceinline__ void gemm_phase(PG8_LAS unsigned char* lds, const Gemm g, const Sched& S, const Epi& E) {
;     ...
;             PG8_LDB(B0, 0, 0); PG8_LDB(B1, 0, 1); PG8_SCHED; PG8_LDA(At, 0, 0); PG8_STAGE(PG8_SA(1, 1), a1 + hstep, voffA);
;             PG8_WAIT_V(8); PG8_WAIT_L(0); PG8_BAR; PG8_MMA(0, 0, At, B0); PG8_MMA(0, 1, At, B1); PG8_BAR; PG8_SCHED;
;             PG8_LDA(At, 0, 1); PG8_STAGE(PG8_SB(0, 0), b2, voffB); PG8_STAGE(PG8_SB(0, 1), b2 + hstep, voffB); PG8_STAGE(PG8_SA(0, 0), a2, voffA);
;             PG8_WAIT_V(8); PG8_WAIT_L(0); PG8_BAR; PG8_MMA(1, 0, At, B0); PG8_MMA(1, 1, At, B1); PG8_BAR; PG8_SCHED;
.LBB0_245:
	v_readlane_b32 s22, v252, 59
	v_readlane_b32 s23, v252, 60
	s_andn2_b64 vcc, exec, s[22:23]
	s_cbranch_vccnz .LBB0_252
	s_add_u32 s40, s6, s48
	s_addc_u32 s41, s7, s49
	s_add_u32 s37, s6, 0x100
	s_addc_u32 s80, s7, 0
	s_and_b64 s[22:23], s[12:13], exec
	s_cselect_b32 s23, s5, s80
	s_cselect_b32 s22, s4, s37
	s_add_u32 s37, s10, 0x100
	s_addc_u32 s82, s11, 0
	s_and_b64 s[80:81], s[12:13], exec
	s_cselect_b32 s85, s17, s82
	s_cselect_b32 s84, s16, s37
	s_add_i32 s83, 0, 0x14000
	v_add_u32_e32 v150, s19, v147
	v_add_u32_e32 v151, s83, v147
	ds_read_b128 v[152:155], v150
	ds_read_b128 v[156:159], v150 offset:1024
	ds_read_b128 v[160:163], v150 offset:2048
	ds_read_b128 v[164:167], v150 offset:3072
	ds_read_b128 v[168:171], v151
	ds_read_b128 v[172:175], v151 offset:1024
	ds_read_b128 v[176:179], v151 offset:2048
	ds_read_b128 v[184:187], v151 offset:3072
	v_lshl_add_u64 v[180:181], s[40:41], 0, v[2:3]
	s_add_i32 s37, s47, 0xc000
	v_lshl_add_u64 v[180:181], v[180:181], 0, s[24:25]
	s_mov_b32 m0, s37
	ds_read_b128 v[188:191], v149
	ds_read_b128 v[192:195], v149 offset:1024
	ds_read_b128 v[196:199], v149 offset:2048
	ds_read_b128 v[200:203], v149 offset:3072
	ds_read_b128 v[204:207], v149 offset:4096
	ds_read_b128 v[230:233], v149 offset:5120
	ds_read_b128 v[234:237], v149 offset:6144
	ds_read_b128 v[238:241], v149 offset:7168
	global_load_lds_dwordx4 v[180:181], off
	v_lshl_add_u64 v[180:181], s[40:41], 0, v[136:137]
	s_add_i32 s80, s47, 0xe000
	v_lshl_add_u64 v[180:181], v[180:181], 0, s[24:25]
	s_mov_b32 m0, s80
	s_nop 0
	global_load_lds_dwordx4 v[180:181], off
	s_waitcnt vmcnt(8)
	s_waitcnt lgkmcnt(0)
	s_barrier
	s_setprio 1
	s_waitcnt lgkmcnt(0)
	v_mfma_f32_16x16x32_bf16 v[132:135], v[152:155], v[188:191], v[132:135]
	v_mfma_f32_16x16x32_bf16 v[116:119], v[152:155], v[196:199], v[116:119]
	v_mfma_f32_16x16x32_bf16 v[100:103], v[152:155], v[204:207], v[100:103]
	v_mfma_f32_16x16x32_bf16 v[84:87], v[152:155], v[234:237], v[84:87]
	v_mfma_f32_16x16x32_bf16 v[80:83], v[160:163], v[234:237], v[80:83]
	v_mfma_f32_16x16x32_bf16 v[96:99], v[160:163], v[204:207], v[96:99]
	v_mfma_f32_16x16x32_bf16 v[112:115], v[160:163], v[196:199], v[112:115]
	v_mfma_f32_16x16x32_bf16 v[128:131], v[160:163], v[188:191], v[128:131]
	v_mfma_f32_16x16x32_bf16 v[132:135], v[156:159], v[192:195], v[132:135]
	v_mfma_f32_16x16x32_bf16 v[116:119], v[156:159], v[200:203], v[116:119]
	v_mfma_f32_16x16x32_bf16 v[100:103], v[156:159], v[230:233], v[100:103]
	v_mfma_f32_16x16x32_bf16 v[84:87], v[156:159], v[238:241], v[84:87]
	v_mfma_f32_16x16x32_bf16 v[80:83], v[164:167], v[238:241], v[80:83]
	v_mfma_f32_16x16x32_bf16 v[96:99], v[164:167], v[230:233], v[96:99]
	v_mfma_f32_16x16x32_bf16 v[112:115], v[164:167], v[200:203], v[112:115]
	v_mfma_f32_16x16x32_bf16 v[128:131], v[164:167], v[192:195], v[128:131]
	s_setprio 0
	s_setprio 1
	v_mfma_f32_16x16x32_bf16 v[124:127], v[168:171], v[188:191], v[124:127]
	v_mfma_f32_16x16x32_bf16 v[108:111], v[168:171], v[196:199], v[108:111]
	v_mfma_f32_16x16x32_bf16 v[92:95], v[168:171], v[204:207], v[92:95]
	v_mfma_f32_16x16x32_bf16 v[76:79], v[168:171], v[234:237], v[76:79]
	v_mfma_f32_16x16x32_bf16 v[72:75], v[176:179], v[234:237], v[72:75]
	v_mfma_f32_16x16x32_bf16 v[88:91], v[176:179], v[204:207], v[88:91]
	v_mfma_f32_16x16x32_bf16 v[104:107], v[176:179], v[196:199], v[104:107]
	v_mfma_f32_16x16x32_bf16 v[120:123], v[176:179], v[188:191], v[120:123]
	v_mfma_f32_16x16x32_bf16 v[124:127], v[172:175], v[192:195], v[124:127]
	v_mfma_f32_16x16x32_bf16 v[108:111], v[172:175], v[200:203], v[108:111]
	v_mfma_f32_16x16x32_bf16 v[92:95], v[172:175], v[230:233], v[92:95]
	v_mfma_f32_16x16x32_bf16 v[76:79], v[172:175], v[238:241], v[76:79]
	v_mfma_f32_16x16x32_bf16 v[72:75], v[184:187], v[238:241], v[72:75]
	v_mfma_f32_16x16x32_bf16 v[88:91], v[184:187], v[230:233], v[88:91]
	v_mfma_f32_16x16x32_bf16 v[104:107], v[184:187], v[200:203], v[104:107]
	v_mfma_f32_16x16x32_bf16 v[120:123], v[184:187], v[192:195], v[120:123]
	s_setprio 0
	s_barrier
	s_add_i32 s81, s19, s46
	s_add_i32 s82, s81, 0x2000
	v_lshl_add_u64 v[208:209], s[84:85], 0, v[0:1]
	s_mov_b32 m0, s81
	s_add_u32 s40, s84, s48
	ds_read_b128 v[188:191], v149 offset:16384
	ds_read_b128 v[192:195], v149 offset:17408
	ds_read_b128 v[196:199], v149 offset:18432
	ds_read_b128 v[200:203], v149 offset:19456
	ds_read_b128 v[204:207], v149 offset:20480
	ds_read_b128 v[230:233], v149 offset:21504
	ds_read_b128 v[234:237], v149 offset:22528
	ds_read_b128 v[238:241], v149 offset:23552
	global_load_lds_dwordx4 v[208:209], off
	v_lshl_add_u64 v[216:217], s[84:85], 0, v[138:139]
	s_mov_b32 m0, s82
	s_addc_u32 s41, s85, s49
	s_add_i32 s83, s83, s46
	global_load_lds_dwordx4 v[216:217], off
	v_lshl_add_u64 v[224:225], s[40:41], 0, v[0:1]
	s_mov_b32 m0, s83
	s_add_i32 s84, s83, 0x2000
	global_load_lds_dwordx4 v[224:225], off
	v_lshl_add_u64 v[226:227], s[40:41], 0, v[138:139]
	s_mov_b32 m0, s84
	v_lshl_add_u64 v[228:229], s[22:23], 0, v[2:3]
	global_load_lds_dwordx4 v[226:227], off
	s_mov_b32 m0, s47
	v_lshl_add_u64 v[242:243], s[22:23], 0, v[136:137]
	global_load_lds_dwordx4 v[228:229], off
	s_mov_b32 m0, s52
	s_nop 0
	global_load_lds_dwordx4 v[242:243], off
	s_waitcnt vmcnt(8)
	s_waitcnt lgkmcnt(0)
	s_barrier
; #define PG8_STAGE(bufoff, gbase, voff) do { _Pragma("unroll") for (int _i = 0; _i < 2; ++_i) \
;         __builtin_amdgcn_global_load_lds((const unsigned*)((const char*)(gbase) + (voff)[_i]), (PG8_LAS unsigned*)(lds + (bufoff) + ldsw + _i * 8192), 16, 0, 0); } while (0)
; #define PG8_LDA(dst, b, h) do { _Pragma("unroll") for (int m = 0; m < 4; ++m) _Pragma("unroll") for (int k = 0; k < 2; ++k) dst[m][k] = *(const PG8_LAS bf16x8*)(lds + PG8_SA(b, h) + aoff + m * 2048 + k * 1024); } while (0)
; #define PG8_LDB(dst, b, h) do { _Pragma("unroll") for (int n = 0; n < 2; ++n) _Pragma("unroll") for (int k = 0; k < 2; ++k) dst[n][k] = *(const PG8_LAS bf16x8*)(lds + PG8_SB(b, h) + boff + n * 2048 + k * 1024); } while (0)
; #define PG8_MMA(ai, bj, At, Bt) do { __builtin_amdgcn_s_setprio(1); _Pragma("unroll") for (int m = 0; m < 4; ++m) _Pragma("unroll") for (int n = 0; n < 2; ++n) _Pragma("unroll") for (int k = 0; k < 2; ++k) \
;         acc[ai][bj][m][n] = __builtin_amdgcn_mfma_f32_16x16x32_bf16(Bt[n][k], At[m][k], acc[ai][bj][m][n], 0, 0, 0); __builtin_amdgcn_s_setprio(0); } while (0)
; #define PG8_WAIT_V(n) asm volatile("s_waitcnt vmcnt(" #n ")" ::: "memory")
; template <class Epi, class Sched, bool ALIGN_EPI = false, bool SP2 = false>
; __device__ __forceinline__ void gemm_phase(PG8_LAS unsigned char* lds, const Gemm g, const Sched& S, const Epi& E) {
;     ...
;             PG8_LDB(B0, 0, 0); PG8_LDB(B1, 0, 1); PG8_SCHED; PG8_LDA(At, 0, 0); PG8_STAGE(PG8_SA(1, 1), a1 + hstep, voffA);
;             PG8_WAIT_V(8); PG8_WAIT_L(0); PG8_BAR; PG8_MMA(0, 0, At, B0); PG8_MMA(0, 1, At, B1); PG8_BAR; PG8_SCHED;
;             PG8_LDA(At, 0, 1); PG8_STAGE(PG8_SB(0, 0), b2, voffB); PG8_STAGE(PG8_SB(0, 1), b2 + hstep, voffB); PG8_STAGE(PG8_SA(0, 0), a2, voffA);
;             PG8_WAIT_V(8); PG8_WAIT_L(0); PG8_BAR; PG8_MMA(1, 0, At, B0); PG8_MMA(1, 1, At, B1); PG8_BAR; PG8_SCHED;
;             PG8_LDB(B0, 1, 0); PG8_LDB(B1, 1, 1); PG8_SCHED; PG8_LDA(At, 1, 0); PG8_STAGE(PG8_SA(0, 1), a2 + hstep, voffA);
;             PG8_WAIT_V(8); PG8_WAIT_L(0); PG8_BAR; PG8_MMA(0, 0, At, B0); PG8_MMA(0, 1, At, B1); PG8_BAR; PG8_SCHED;
;             PG8_LDA(At, 1, 1); PG8_STAGE(PG8_SB(1, 0), b3, voffB); PG8_STAGE(PG8_SB(1, 1), b3 + hstep, voffB); PG8_STAGE(PG8_SA(1, 0), a3, voffA);
;             PG8_WAIT_V(8); PG8_WAIT_L(0); PG8_BAR; PG8_MMA(1, 0, At, B0); PG8_MMA(1, 1, At, B1); PG8_BAR; PG8_SCHED;
	s_setprio 1
	s_waitcnt lgkmcnt(0)
	v_mfma_f32_16x16x32_bf16 v[68:71], v[152:155], v[188:191], v[68:71]
	v_mfma_f32_16x16x32_bf16 v[52:55], v[152:155], v[196:199], v[52:55]
	v_mfma_f32_16x16x32_bf16 v[36:39], v[152:155], v[204:207], v[36:39]
	v_mfma_f32_16x16x32_bf16 v[20:23], v[152:155], v[234:237], v[20:23]
	v_mfma_f32_16x16x32_bf16 v[16:19], v[160:163], v[234:237], v[16:19]
	v_mfma_f32_16x16x32_bf16 v[32:35], v[160:163], v[204:207], v[32:35]
	v_mfma_f32_16x16x32_bf16 v[48:51], v[160:163], v[196:199], v[48:51]
	v_mfma_f32_16x16x32_bf16 v[64:67], v[160:163], v[188:191], v[64:67]
	v_mfma_f32_16x16x32_bf16 v[68:71], v[156:159], v[192:195], v[68:71]
	v_mfma_f32_16x16x32_bf16 v[52:55], v[156:159], v[200:203], v[52:55]
	v_mfma_f32_16x16x32_bf16 v[36:39], v[156:159], v[230:233], v[36:39]
	v_mfma_f32_16x16x32_bf16 v[20:23], v[156:159], v[238:241], v[20:23]
	v_mfma_f32_16x16x32_bf16 v[16:19], v[164:167], v[238:241], v[16:19]
	v_mfma_f32_16x16x32_bf16 v[32:35], v[164:167], v[230:233], v[32:35]
	v_mfma_f32_16x16x32_bf16 v[48:51], v[164:167], v[200:203], v[48:51]
	v_mfma_f32_16x16x32_bf16 v[64:67], v[164:167], v[192:195], v[64:67]
	s_setprio 0
	s_setprio 1
	v_mfma_f32_16x16x32_bf16 v[60:63], v[168:171], v[188:191], v[60:63]
	v_mfma_f32_16x16x32_bf16 v[44:47], v[168:171], v[196:199], v[44:47]
	v_mfma_f32_16x16x32_bf16 v[28:31], v[168:171], v[204:207], v[28:31]
	v_mfma_f32_16x16x32_bf16 v[12:15], v[168:171], v[234:237], v[12:15]
	v_mfma_f32_16x16x32_bf16 v[8:11], v[176:179], v[234:237], v[8:11]
	v_mfma_f32_16x16x32_bf16 v[24:27], v[176:179], v[204:207], v[24:27]
	v_mfma_f32_16x16x32_bf16 v[40:43], v[176:179], v[196:199], v[40:43]
	v_mfma_f32_16x16x32_bf16 v[56:59], v[176:179], v[188:191], v[56:59]
	v_mfma_f32_16x16x32_bf16 v[60:63], v[172:175], v[192:195], v[60:63]
	v_mfma_f32_16x16x32_bf16 v[44:47], v[172:175], v[200:203], v[44:47]
	v_mfma_f32_16x16x32_bf16 v[28:31], v[172:175], v[230:233], v[28:31]
	v_mfma_f32_16x16x32_bf16 v[12:15], v[172:175], v[238:241], v[12:15]
	v_mfma_f32_16x16x32_bf16 v[8:11], v[184:187], v[238:241], v[8:11]
	v_mfma_f32_16x16x32_bf16 v[24:27], v[184:187], v[230:233], v[24:27]
	v_mfma_f32_16x16x32_bf16 v[40:43], v[184:187], v[200:203], v[40:43]
	v_mfma_f32_16x16x32_bf16 v[56:59], v[184:187], v[192:195], v[56:59]
	s_setprio 0
	s_barrier
	s_add_i32 s87, 0, 0x1c000
	v_add_u32_e32 v152, s91, v147
	v_add_u32_e32 v153, s87, v147
	ds_read_b128 v[154:157], v152
	ds_read_b128 v[158:161], v152 offset:1024
	ds_read_b128 v[162:165], v152 offset:2048
	ds_read_b128 v[166:169], v152 offset:3072
	ds_read_b128 v[170:173], v153
	ds_read_b128 v[174:177], v153 offset:1024
	ds_read_b128 v[178:181], v153 offset:2048
	ds_read_b128 v[184:187], v153 offset:3072
	s_add_u32 s22, s22, s48
	s_addc_u32 s23, s23, s49
	s_mov_b32 m0, s53
	v_lshl_add_u64 v[244:245], s[22:23], 0, v[2:3]
	ds_read_b128 v[188:191], v149 offset:32768
	ds_read_b128 v[192:195], v149 offset:33792
	ds_read_b128 v[196:199], v149 offset:34816
	ds_read_b128 v[200:203], v149 offset:35840
	ds_read_b128 v[204:207], v149 offset:36864
	ds_read_b128 v[230:233], v149 offset:37888
	ds_read_b128 v[234:237], v149 offset:38912
	ds_read_b128 v[238:241], v149 offset:39936
	global_load_lds_dwordx4 v[244:245], off
	v_lshl_add_u64 v[244:245], s[22:23], 0, v[136:137]
	s_mov_b32 m0, s72
	s_nop 0
	global_load_lds_dwordx4 v[244:245], off
	s_waitcnt vmcnt(8)
	s_waitcnt lgkmcnt(0)
	s_barrier
	s_setprio 1
	s_waitcnt lgkmcnt(0)
	v_mfma_f32_16x16x32_bf16 v[132:135], v[154:157], v[188:191], v[132:135]
	v_mfma_f32_16x16x32_bf16 v[116:119], v[154:157], v[196:199], v[116:119]
	v_mfma_f32_16x16x32_bf16 v[100:103], v[154:157], v[204:207], v[100:103]
	v_mfma_f32_16x16x32_bf16 v[84:87], v[154:157], v[234:237], v[84:87]
	v_mfma_f32_16x16x32_bf16 v[80:83], v[162:165], v[234:237], v[80:83]
	v_mfma_f32_16x16x32_bf16 v[96:99], v[162:165], v[204:207], v[96:99]
	v_mfma_f32_16x16x32_bf16 v[112:115], v[162:165], v[196:199], v[112:115]
	v_mfma_f32_16x16x32_bf16 v[128:131], v[162:165], v[188:191], v[128:131]
	v_mfma_f32_16x16x32_bf16 v[132:135], v[158:161], v[192:195], v[132:135]
	v_mfma_f32_16x16x32_bf16 v[116:119], v[158:161], v[200:203], v[116:119]
	v_mfma_f32_16x16x32_bf16 v[100:103], v[158:161], v[230:233], v[100:103]
	v_mfma_f32_16x16x32_bf16 v[84:87], v[158:161], v[238:241], v[84:87]
	v_mfma_f32_16x16x32_bf16 v[80:83], v[166:169], v[238:241], v[80:83]
	v_mfma_f32_16x16x32_bf16 v[96:99], v[166:169], v[230:233], v[96:99]
	v_mfma_f32_16x16x32_bf16 v[112:115], v[166:169], v[200:203], v[112:115]
	v_mfma_f32_16x16x32_bf16 v[128:131], v[166:169], v[192:195], v[128:131]
	s_setprio 0
	s_setprio 1
	v_mfma_f32_16x16x32_bf16 v[124:127], v[170:173], v[188:191], v[124:127]
	v_mfma_f32_16x16x32_bf16 v[108:111], v[170:173], v[196:199], v[108:111]
	v_mfma_f32_16x16x32_bf16 v[92:95], v[170:173], v[204:207], v[92:95]
	v_mfma_f32_16x16x32_bf16 v[76:79], v[170:173], v[234:237], v[76:79]
	v_mfma_f32_16x16x32_bf16 v[72:75], v[178:181], v[234:237], v[72:75]
	v_mfma_f32_16x16x32_bf16 v[88:91], v[178:181], v[204:207], v[88:91]
	v_mfma_f32_16x16x32_bf16 v[104:107], v[178:181], v[196:199], v[104:107]
	v_mfma_f32_16x16x32_bf16 v[120:123], v[178:181], v[188:191], v[120:123]
	v_mfma_f32_16x16x32_bf16 v[124:127], v[174:177], v[192:195], v[124:127]
	v_mfma_f32_16x16x32_bf16 v[108:111], v[174:177], v[200:203], v[108:111]
	v_mfma_f32_16x16x32_bf16 v[92:95], v[174:177], v[230:233], v[92:95]
	v_mfma_f32_16x16x32_bf16 v[76:79], v[174:177], v[238:241], v[76:79]
	v_mfma_f32_16x16x32_bf16 v[72:75], v[184:187], v[238:241], v[72:75]
	v_mfma_f32_16x16x32_bf16 v[88:91], v[184:187], v[230:233], v[88:91]
	v_mfma_f32_16x16x32_bf16 v[104:107], v[184:187], v[200:203], v[104:107]
	v_mfma_f32_16x16x32_bf16 v[120:123], v[184:187], v[192:195], v[120:123]
	s_setprio 0
	s_barrier
; #define PG8_STAGE(bufoff, gbase, voff) do { _Pragma("unroll") for (int _i = 0; _i < 2; ++_i) \
;         __builtin_amdgcn_global_load_lds((const unsigned*)((const char*)(gbase) + (voff)[_i]), (PG8_LAS unsigned*)(lds + (bufoff) + ldsw + _i * 8192), 16, 0, 0); } while (0)
; #define PG8_LDA(dst, b, h) do { _Pragma("unroll") for (int m = 0; m < 4; ++m) _Pragma("unroll") for (int k = 0; k < 2; ++k) dst[m][k] = *(const PG8_LAS bf16x8*)(lds + PG8_SA(b, h) + aoff + m * 2048 + k * 1024); } while (0)
; #define PG8_LDB(dst, b, h) do { _Pragma("unroll") for (int n = 0; n < 2; ++n) _Pragma("unroll") for (int k = 0; k < 2; ++k) dst[n][k] = *(const PG8_LAS bf16x8*)(lds + PG8_SB(b, h) + boff + n * 2048 + k * 1024); } while (0)
; #define PG8_MMA(ai, bj, At, Bt) do { __builtin_amdgcn_s_setprio(1); _Pragma("unroll") for (int m = 0; m < 4; ++m) _Pragma("unroll") for (int n = 0; n < 2; ++n) _Pragma("unroll") for (int k = 0; k < 2; ++k) \
;         acc[ai][bj][m][n] = __builtin_amdgcn_mfma_f32_16x16x32_bf16(Bt[n][k], At[m][k], acc[ai][bj][m][n], 0, 0, 0); __builtin_amdgcn_s_setprio(0); } while (0)
; #define PG8_WAIT_V(n) asm volatile("s_waitcnt vmcnt(" #n ")" ::: "memory")
; template <class Epi, class Sched, bool ALIGN_EPI = false, bool SP2 = false>
; __device__ __forceinline__ void gemm_phase(PG8_LAS unsigned char* lds, const Gemm g, const Sched& S, const Epi& E) {
;     ...
;             PG8_LDB(B0, 0, 0); PG8_LDB(B1, 0, 1); PG8_SCHED; PG8_LDA(At, 0, 0); PG8_STAGE(PG8_SA(1, 1), a1 + hstep, voffA);
;             PG8_WAIT_V(8); PG8_WAIT_L(0); PG8_BAR; PG8_MMA(0, 0, At, B0); PG8_MMA(0, 1, At, B1); PG8_BAR; PG8_SCHED;
;             PG8_LDA(At, 0, 1); PG8_STAGE(PG8_SB(0, 0), b2, voffB); PG8_STAGE(PG8_SB(0, 1), b2 + hstep, voffB); PG8_STAGE(PG8_SA(0, 0), a2, voffA);
;             PG8_WAIT_V(8); PG8_WAIT_L(0); PG8_BAR; PG8_MMA(1, 0, At, B0); PG8_MMA(1, 1, At, B1); PG8_BAR; PG8_SCHED;
;             PG8_LDB(B0, 1, 0); PG8_LDB(B1, 1, 1); PG8_SCHED; PG8_LDA(At, 1, 0); PG8_STAGE(PG8_SA(0, 1), a2 + hstep, voffA);
;             PG8_WAIT_V(8); PG8_WAIT_L(0); PG8_BAR; PG8_MMA(0, 0, At, B0); PG8_MMA(0, 1, At, B1); PG8_BAR; PG8_SCHED;
;             PG8_LDA(At, 1, 1); PG8_STAGE(PG8_SB(1, 0), b3, voffB); PG8_STAGE(PG8_SB(1, 1), b3 + hstep, voffB); PG8_STAGE(PG8_SA(1, 0), a3, voffA);
;             PG8_WAIT_V(8); PG8_WAIT_L(0); PG8_BAR; PG8_MMA(1, 0, At, B0); PG8_MMA(1, 1, At, B1); PG8_BAR; PG8_SCHED;
	s_add_i32 s85, s91, s46
	v_lshl_add_u64 v[208:209], v[208:209], 0, s[24:25]
	s_mov_b32 m0, s85
	s_add_i32 s86, s85, 0x2000
	ds_read_b128 v[188:191], v149 offset:49152
	ds_read_b128 v[192:195], v149 offset:50176
	ds_read_b128 v[196:199], v149 offset:51200
	ds_read_b128 v[200:203], v149 offset:52224
	ds_read_b128 v[204:207], v149 offset:53248
	ds_read_b128 v[230:233], v149 offset:54272
	ds_read_b128 v[234:237], v149 offset:55296
	ds_read_b128 v[238:241], v149 offset:56320
	global_load_lds_dwordx4 v[208:209], off
	v_lshl_add_u64 v[208:209], v[216:217], 0, s[24:25]
	s_mov_b32 m0, s86
	s_add_i32 s87, s87, s46
	global_load_lds_dwordx4 v[208:209], off
	v_lshl_add_u64 v[208:209], v[224:225], 0, s[24:25]
	s_mov_b32 m0, s87
	s_add_i32 s88, s87, 0x2000
	global_load_lds_dwordx4 v[208:209], off
	v_lshl_add_u64 v[208:209], v[226:227], 0, s[24:25]
	s_mov_b32 m0, s88
	s_nop 0
	global_load_lds_dwordx4 v[208:209], off
	v_lshl_add_u64 v[208:209], v[228:229], 0, s[24:25]
	s_mov_b32 m0, s75
	s_nop 0
	global_load_lds_dwordx4 v[208:209], off
	v_lshl_add_u64 v[208:209], v[242:243], 0, s[24:25]
	s_mov_b32 m0, s76
	s_nop 0
	global_load_lds_dwordx4 v[208:209], off
	s_waitcnt vmcnt(8)
	s_waitcnt lgkmcnt(0)
	s_barrier
	s_setprio 1
	s_waitcnt lgkmcnt(0)
	v_mfma_f32_16x16x32_bf16 v[68:71], v[154:157], v[188:191], v[68:71]
	v_mfma_f32_16x16x32_bf16 v[52:55], v[154:157], v[196:199], v[52:55]
	v_mfma_f32_16x16x32_bf16 v[36:39], v[154:157], v[204:207], v[36:39]
	v_mfma_f32_16x16x32_bf16 v[20:23], v[154:157], v[234:237], v[20:23]
	v_mfma_f32_16x16x32_bf16 v[16:19], v[162:165], v[234:237], v[16:19]
	v_mfma_f32_16x16x32_bf16 v[32:35], v[162:165], v[204:207], v[32:35]
	v_mfma_f32_16x16x32_bf16 v[48:51], v[162:165], v[196:199], v[48:51]
	v_mfma_f32_16x16x32_bf16 v[64:67], v[162:165], v[188:191], v[64:67]
	v_mfma_f32_16x16x32_bf16 v[68:71], v[158:161], v[192:195], v[68:71]
	v_mfma_f32_16x16x32_bf16 v[52:55], v[158:161], v[200:203], v[52:55]
	v_mfma_f32_16x16x32_bf16 v[36:39], v[158:161], v[230:233], v[36:39]
	v_mfma_f32_16x16x32_bf16 v[20:23], v[158:161], v[238:241], v[20:23]
	v_mfma_f32_16x16x32_bf16 v[16:19], v[166:169], v[238:241], v[16:19]
	v_mfma_f32_16x16x32_bf16 v[32:35], v[166:169], v[230:233], v[32:35]
	v_mfma_f32_16x16x32_bf16 v[48:51], v[166:169], v[200:203], v[48:51]
	v_mfma_f32_16x16x32_bf16 v[64:67], v[166:169], v[192:195], v[64:67]
	s_setprio 0
	s_setprio 1
	v_mfma_f32_16x16x32_bf16 v[60:63], v[170:173], v[188:191], v[60:63]
	v_mfma_f32_16x16x32_bf16 v[44:47], v[170:173], v[196:199], v[44:47]
	v_mfma_f32_16x16x32_bf16 v[28:31], v[170:173], v[204:207], v[28:31]
	v_mfma_f32_16x16x32_bf16 v[12:15], v[170:173], v[234:237], v[12:15]
	v_mfma_f32_16x16x32_bf16 v[8:11], v[178:181], v[234:237], v[8:11]
	v_mfma_f32_16x16x32_bf16 v[24:27], v[178:181], v[204:207], v[24:27]
	v_mfma_f32_16x16x32_bf16 v[40:43], v[178:181], v[196:199], v[40:43]
	v_mfma_f32_16x16x32_bf16 v[56:59], v[178:181], v[188:191], v[56:59]
	v_mfma_f32_16x16x32_bf16 v[60:63], v[174:177], v[192:195], v[60:63]
	v_mfma_f32_16x16x32_bf16 v[44:47], v[174:177], v[200:203], v[44:47]
	v_mfma_f32_16x16x32_bf16 v[28:31], v[174:177], v[230:233], v[28:31]
	v_mfma_f32_16x16x32_bf16 v[12:15], v[174:177], v[238:241], v[12:15]
	v_mfma_f32_16x16x32_bf16 v[8:11], v[184:187], v[238:241], v[8:11]
	v_mfma_f32_16x16x32_bf16 v[24:27], v[184:187], v[230:233], v[24:27]
	v_mfma_f32_16x16x32_bf16 v[40:43], v[184:187], v[200:203], v[40:43]
	v_mfma_f32_16x16x32_bf16 v[56:59], v[184:187], v[192:195], v[56:59]
	s_setprio 0
	s_barrier
	v_readlane_b32 s22, v252, 42
	v_readlane_b32 s23, v252, 43
	s_andn2_b64 vcc, exec, s[22:23]
	s_cbranch_vccnz .LBB0_251
	s_add_u32 s22, s6, 0x180
	s_addc_u32 s23, s7, 0
	s_add_u32 s89, s10, 0x200
	s_addc_u32 s92, s11, 0
	s_mov_b32 s93, 4
	v_mov_b32_e32 v154, v148
	s_add_i32 s40, s93, -2
	s_and_b32 s40, s40, 6
	s_cmp_lg_u32 s40, 0
	s_cbranch_scc1 .LBB0_250
	s_branch .LBB0_249

; #define PG8_STAGE(bufoff, gbase, voff) do { _Pragma("unroll") for (int _i = 0; _i < 2; ++_i) \
;         __builtin_amdgcn_global_load_lds((const unsigned*)((const char*)(gbase) + (voff)[_i]), (PG8_LAS unsigned*)(lds + (bufoff) + ldsw + _i * 8192), 16, 0, 0); } while (0)
; #define PG8_LDA(dst, b, h) do { _Pragma("unroll") for (int m = 0; m < 4; ++m) _Pragma("unroll") for (int k = 0; k < 2; ++k) dst[m][k] = *(const PG8_LAS bf16x8*)(lds + PG8_SA(b, h) + aoff + m * 2048 + k * 1024); } while (0)
; #define PG8_LDB(dst, b, h) do { _Pragma("unroll") for (int n = 0; n < 2; ++n) _Pragma("unroll") for (int k = 0; k < 2; ++k) dst[n][k] = *(const PG8_LAS bf16x8*)(lds + PG8_SB(b, h) + boff + n * 2048 + k * 1024); } while (0)
; #define PG8_MMA(ai, bj, At, Bt) do { __builtin_amdgcn_s_setprio(1); _Pragma("unroll") for (int m = 0; m < 4; ++m) _Pragma("unroll") for (int n = 0; n < 2; ++n) _Pragma("unroll") for (int k = 0; k < 2; ++k) \
;         acc[ai][bj][m][n] = __builtin_amdgcn_mfma_f32_16x16x32_bf16(Bt[n][k], At[m][k], acc[ai][bj][m][n], 0, 0, 0); __builtin_amdgcn_s_setprio(0); } while (0)
; #define PG8_WAIT_V(n) asm volatile("s_waitcnt vmcnt(" #n ")" ::: "memory")
; template <class Epi, class Sched, bool ALIGN_EPI = false, bool SP2 = false>
; __device__ __forceinline__ void gemm_phase(PG8_LAS unsigned char* lds, const Gemm g, const Sched& S, const Epi& E) {
;     ...
;             PG8_LDB(B0, 0, 0); PG8_LDB(B1, 0, 1); PG8_SCHED; PG8_LDA(At, 0, 0); PG8_STAGE(PG8_SA(1, 1), a1 + hstep, voffA);
;             PG8_WAIT_V(8); PG8_WAIT_L(0); PG8_BAR; PG8_MMA(0, 0, At, B0); PG8_MMA(0, 1, At, B1); PG8_BAR; PG8_SCHED;
;             PG8_LDA(At, 0, 1); PG8_STAGE(PG8_SB(0, 0), b2, voffB); PG8_STAGE(PG8_SB(0, 1), b2 + hstep, voffB); PG8_STAGE(PG8_SA(0, 0), a2, voffA);
;             PG8_WAIT_V(8); PG8_WAIT_L(0); PG8_BAR; PG8_MMA(1, 0, At, B0); PG8_MMA(1, 1, At, B1); PG8_BAR; PG8_SCHED;
;             PG8_LDB(B0, 1, 0); PG8_LDB(B1, 1, 1); PG8_SCHED; PG8_LDA(At, 1, 0); PG8_STAGE(PG8_SA(0, 1), a2 + hstep, voffA);
;             PG8_WAIT_V(8); PG8_WAIT_L(0); PG8_BAR; PG8_MMA(0, 0, At, B0); PG8_MMA(0, 1, At, B1); PG8_BAR; PG8_SCHED;
;             PG8_LDA(At, 1, 1); PG8_STAGE(PG8_SB(1, 0), b3, voffB); PG8_STAGE(PG8_SB(1, 1), b3 + hstep, voffB); PG8_STAGE(PG8_SA(1, 0), a3, voffA);
;             PG8_WAIT_V(8); PG8_WAIT_L(0); PG8_BAR; PG8_MMA(1, 0, At, B0); PG8_MMA(1, 1, At, B1); PG8_BAR; PG8_SCHED;
.LBB0_250:
	ds_read_b128 v[156:159], v150
	ds_read_b128 v[160:163], v150 offset:1024
	ds_read_b128 v[164:167], v150 offset:2048
	ds_read_b128 v[168:171], v150 offset:3072
	ds_read_b128 v[172:175], v151
	ds_read_b128 v[176:179], v151 offset:1024
	ds_read_b128 v[184:187], v151 offset:2048
	ds_read_b128 v[188:191], v151 offset:3072
	s_add_u32 s40, s22, 0x80
	s_addc_u32 s41, s23, 0
	s_cmp_eq_u32 s9, s93
	s_cselect_b32 s40, s4, s40
	s_cselect_b32 s41, s5, s41
	s_cselect_b32 s95, s17, s92
	s_cselect_b32 s94, s16, s89
	s_mov_b32 m0, s37
	v_lshl_add_u64 v[180:181], s[22:23], 0, v[140:141]
	ds_read_b128 v[192:195], v149
	ds_read_b128 v[196:199], v149 offset:1024
	ds_read_b128 v[200:203], v149 offset:2048
	ds_read_b128 v[204:207], v149 offset:3072
	ds_read_b128 v[230:233], v149 offset:4096
	ds_read_b128 v[234:237], v149 offset:5120
	ds_read_b128 v[238:241], v149 offset:6144
	ds_read_b128 v[242:245], v149 offset:7168
	global_load_lds_dwordx4 v[180:181], off
	v_lshl_add_u64 v[180:181], s[22:23], 0, v[142:143]
	s_mov_b32 m0, s80
	s_nop 0
	global_load_lds_dwordx4 v[180:181], off
	s_waitcnt vmcnt(8)
	s_waitcnt lgkmcnt(0)
	s_barrier
	s_setprio 1
	s_waitcnt lgkmcnt(0)
	v_mfma_f32_16x16x32_bf16 v[132:135], v[156:159], v[192:195], v[132:135]
	v_mfma_f32_16x16x32_bf16 v[116:119], v[156:159], v[200:203], v[116:119]
	v_mfma_f32_16x16x32_bf16 v[100:103], v[156:159], v[230:233], v[100:103]
	v_mfma_f32_16x16x32_bf16 v[84:87], v[156:159], v[238:241], v[84:87]
	v_mfma_f32_16x16x32_bf16 v[80:83], v[164:167], v[238:241], v[80:83]
	v_mfma_f32_16x16x32_bf16 v[96:99], v[164:167], v[230:233], v[96:99]
	v_mfma_f32_16x16x32_bf16 v[112:115], v[164:167], v[200:203], v[112:115]
	v_mfma_f32_16x16x32_bf16 v[128:131], v[164:167], v[192:195], v[128:131]
	v_mfma_f32_16x16x32_bf16 v[132:135], v[160:163], v[196:199], v[132:135]
	v_mfma_f32_16x16x32_bf16 v[116:119], v[160:163], v[204:207], v[116:119]
	v_mfma_f32_16x16x32_bf16 v[100:103], v[160:163], v[234:237], v[100:103]
	v_mfma_f32_16x16x32_bf16 v[84:87], v[160:163], v[242:245], v[84:87]
	v_mfma_f32_16x16x32_bf16 v[80:83], v[168:171], v[242:245], v[80:83]
	v_mfma_f32_16x16x32_bf16 v[96:99], v[168:171], v[234:237], v[96:99]
	v_mfma_f32_16x16x32_bf16 v[112:115], v[168:171], v[204:207], v[112:115]
	v_mfma_f32_16x16x32_bf16 v[128:131], v[168:171], v[196:199], v[128:131]
	s_setprio 0
	s_setprio 1
	v_mfma_f32_16x16x32_bf16 v[124:127], v[172:175], v[192:195], v[124:127]
	v_mfma_f32_16x16x32_bf16 v[108:111], v[172:175], v[200:203], v[108:111]
	v_mfma_f32_16x16x32_bf16 v[92:95], v[172:175], v[230:233], v[92:95]
	v_mfma_f32_16x16x32_bf16 v[76:79], v[172:175], v[238:241], v[76:79]
	v_mfma_f32_16x16x32_bf16 v[72:75], v[184:187], v[238:241], v[72:75]
	v_mfma_f32_16x16x32_bf16 v[88:91], v[184:187], v[230:233], v[88:91]
	v_mfma_f32_16x16x32_bf16 v[104:107], v[184:187], v[200:203], v[104:107]
	v_mfma_f32_16x16x32_bf16 v[120:123], v[184:187], v[192:195], v[120:123]
	v_mfma_f32_16x16x32_bf16 v[124:127], v[176:179], v[196:199], v[124:127]
	v_mfma_f32_16x16x32_bf16 v[108:111], v[176:179], v[204:207], v[108:111]
	v_mfma_f32_16x16x32_bf16 v[92:95], v[176:179], v[234:237], v[92:95]
	v_mfma_f32_16x16x32_bf16 v[76:79], v[176:179], v[242:245], v[76:79]
	v_mfma_f32_16x16x32_bf16 v[72:75], v[188:191], v[242:245], v[72:75]
	v_mfma_f32_16x16x32_bf16 v[88:91], v[188:191], v[234:237], v[88:91]
	v_mfma_f32_16x16x32_bf16 v[104:107], v[188:191], v[204:207], v[104:107]
	v_mfma_f32_16x16x32_bf16 v[120:123], v[188:191], v[196:199], v[120:123]
	s_setprio 0
	s_barrier
	s_mov_b32 m0, s81
	v_lshl_add_u64 v[180:181], s[94:95], 0, v[0:1]
	v_lshl_add_u64 v[208:209], s[94:95], 0, v[138:139]
	s_add_u32 s94, s94, s48
	ds_read_b128 v[192:195], v149 offset:16384
	ds_read_b128 v[196:199], v149 offset:17408
	ds_read_b128 v[200:203], v149 offset:18432
	ds_read_b128 v[204:207], v149 offset:19456
	ds_read_b128 v[230:233], v149 offset:20480
	ds_read_b128 v[234:237], v149 offset:21504
	ds_read_b128 v[238:241], v149 offset:22528
	ds_read_b128 v[242:245], v149 offset:23552
	global_load_lds_dwordx4 v[180:181], off
	s_mov_b32 m0, s82
	s_addc_u32 s95, s95, s49
	global_load_lds_dwordx4 v[208:209], off
	v_lshl_add_u64 v[216:217], s[94:95], 0, v[0:1]
	s_mov_b32 m0, s83
	v_lshl_add_u64 v[224:225], s[94:95], 0, v[138:139]
	global_load_lds_dwordx4 v[216:217], off
	s_mov_b32 m0, s84
	v_lshl_add_u64 v[226:227], s[40:41], 0, v[2:3]
	global_load_lds_dwordx4 v[224:225], off
	s_mov_b32 m0, s47
	v_lshl_add_u64 v[228:229], s[40:41], 0, v[136:137]
	global_load_lds_dwordx4 v[226:227], off
	s_mov_b32 m0, s52
	s_nop 0
	global_load_lds_dwordx4 v[228:229], off
	s_waitcnt vmcnt(8)
	s_waitcnt lgkmcnt(0)
	s_barrier
; #define PG8_STAGE(bufoff, gbase, voff) do { _Pragma("unroll") for (int _i = 0; _i < 2; ++_i) \
;         __builtin_amdgcn_global_load_lds((const unsigned*)((const char*)(gbase) + (voff)[_i]), (PG8_LAS unsigned*)(lds + (bufoff) + ldsw + _i * 8192), 16, 0, 0); } while (0)
; #define PG8_LDA(dst, b, h) do { _Pragma("unroll") for (int m = 0; m < 4; ++m) _Pragma("unroll") for (int k = 0; k < 2; ++k) dst[m][k] = *(const PG8_LAS bf16x8*)(lds + PG8_SA(b, h) + aoff + m * 2048 + k * 1024); } while (0)
; #define PG8_LDB(dst, b, h) do { _Pragma("unroll") for (int n = 0; n < 2; ++n) _Pragma("unroll") for (int k = 0; k < 2; ++k) dst[n][k] = *(const PG8_LAS bf16x8*)(lds + PG8_SB(b, h) + boff + n * 2048 + k * 1024); } while (0)
; #define PG8_MMA(ai, bj, At, Bt) do { __builtin_amdgcn_s_setprio(1); _Pragma("unroll") for (int m = 0; m < 4; ++m) _Pragma("unroll") for (int n = 0; n < 2; ++n) _Pragma("unroll") for (int k = 0; k < 2; ++k) \
;         acc[ai][bj][m][n] = __builtin_amdgcn_mfma_f32_16x16x32_bf16(Bt[n][k], At[m][k], acc[ai][bj][m][n], 0, 0, 0); __builtin_amdgcn_s_setprio(0); } while (0)
; #define PG8_WAIT_V(n) asm volatile("s_waitcnt vmcnt(" #n ")" ::: "memory")
; template <class Epi, class Sched, bool ALIGN_EPI = false, bool SP2 = false>
; __device__ __forceinline__ void gemm_phase(PG8_LAS unsigned char* lds, const Gemm g, const Sched& S, const Epi& E) {
;     ...
;             PG8_LDB(B0, 0, 0); PG8_LDB(B1, 0, 1); PG8_SCHED; PG8_LDA(At, 0, 0); PG8_STAGE(PG8_SA(1, 1), a1 + hstep, voffA);
;             PG8_WAIT_V(8); PG8_WAIT_L(0); PG8_BAR; PG8_MMA(0, 0, At, B0); PG8_MMA(0, 1, At, B1); PG8_BAR; PG8_SCHED;
;             PG8_LDA(At, 0, 1); PG8_STAGE(PG8_SB(0, 0), b2, voffB); PG8_STAGE(PG8_SB(0, 1), b2 + hstep, voffB); PG8_STAGE(PG8_SA(0, 0), a2, voffA);
;             PG8_WAIT_V(8); PG8_WAIT_L(0); PG8_BAR; PG8_MMA(1, 0, At, B0); PG8_MMA(1, 1, At, B1); PG8_BAR; PG8_SCHED;
;             PG8_LDB(B0, 1, 0); PG8_LDB(B1, 1, 1); PG8_SCHED; PG8_LDA(At, 1, 0); PG8_STAGE(PG8_SA(0, 1), a2 + hstep, voffA);
;             PG8_WAIT_V(8); PG8_WAIT_L(0); PG8_BAR; PG8_MMA(0, 0, At, B0); PG8_MMA(0, 1, At, B1); PG8_BAR; PG8_SCHED;
;             PG8_LDA(At, 1, 1); PG8_STAGE(PG8_SB(1, 0), b3, voffB); PG8_STAGE(PG8_SB(1, 1), b3 + hstep, voffB); PG8_STAGE(PG8_SA(1, 0), a3, voffA);
;             PG8_WAIT_V(8); PG8_WAIT_L(0); PG8_BAR; PG8_MMA(1, 0, At, B0); PG8_MMA(1, 1, At, B1); PG8_BAR; PG8_SCHED;
	s_setprio 1
	s_waitcnt lgkmcnt(0)
	v_mfma_f32_16x16x32_bf16 v[68:71], v[156:159], v[192:195], v[68:71]
	v_mfma_f32_16x16x32_bf16 v[52:55], v[156:159], v[200:203], v[52:55]
	v_mfma_f32_16x16x32_bf16 v[36:39], v[156:159], v[230:233], v[36:39]
	v_mfma_f32_16x16x32_bf16 v[20:23], v[156:159], v[238:241], v[20:23]
	v_mfma_f32_16x16x32_bf16 v[16:19], v[164:167], v[238:241], v[16:19]
	v_mfma_f32_16x16x32_bf16 v[32:35], v[164:167], v[230:233], v[32:35]
	v_mfma_f32_16x16x32_bf16 v[48:51], v[164:167], v[200:203], v[48:51]
	v_mfma_f32_16x16x32_bf16 v[64:67], v[164:167], v[192:195], v[64:67]
	v_mfma_f32_16x16x32_bf16 v[68:71], v[160:163], v[196:199], v[68:71]
	v_mfma_f32_16x16x32_bf16 v[52:55], v[160:163], v[204:207], v[52:55]
	v_mfma_f32_16x16x32_bf16 v[36:39], v[160:163], v[234:237], v[36:39]
	v_mfma_f32_16x16x32_bf16 v[20:23], v[160:163], v[242:245], v[20:23]
	v_mfma_f32_16x16x32_bf16 v[16:19], v[168:171], v[242:245], v[16:19]
	v_mfma_f32_16x16x32_bf16 v[32:35], v[168:171], v[234:237], v[32:35]
	v_mfma_f32_16x16x32_bf16 v[48:51], v[168:171], v[204:207], v[48:51]
	v_mfma_f32_16x16x32_bf16 v[64:67], v[168:171], v[196:199], v[64:67]
	s_setprio 0
	s_setprio 1
	v_mfma_f32_16x16x32_bf16 v[60:63], v[172:175], v[192:195], v[60:63]
	v_mfma_f32_16x16x32_bf16 v[44:47], v[172:175], v[200:203], v[44:47]
	v_mfma_f32_16x16x32_bf16 v[28:31], v[172:175], v[230:233], v[28:31]
	v_mfma_f32_16x16x32_bf16 v[12:15], v[172:175], v[238:241], v[12:15]
	v_mfma_f32_16x16x32_bf16 v[8:11], v[184:187], v[238:241], v[8:11]
	v_mfma_f32_16x16x32_bf16 v[24:27], v[184:187], v[230:233], v[24:27]
	v_mfma_f32_16x16x32_bf16 v[40:43], v[184:187], v[200:203], v[40:43]
	v_mfma_f32_16x16x32_bf16 v[56:59], v[184:187], v[192:195], v[56:59]
	v_mfma_f32_16x16x32_bf16 v[60:63], v[176:179], v[196:199], v[60:63]
	v_mfma_f32_16x16x32_bf16 v[44:47], v[176:179], v[204:207], v[44:47]
	v_mfma_f32_16x16x32_bf16 v[28:31], v[176:179], v[234:237], v[28:31]
	v_mfma_f32_16x16x32_bf16 v[12:15], v[176:179], v[242:245], v[12:15]
	v_mfma_f32_16x16x32_bf16 v[8:11], v[188:191], v[242:245], v[8:11]
	v_mfma_f32_16x16x32_bf16 v[24:27], v[188:191], v[234:237], v[24:27]
	v_mfma_f32_16x16x32_bf16 v[40:43], v[188:191], v[204:207], v[40:43]
	v_mfma_f32_16x16x32_bf16 v[56:59], v[188:191], v[196:199], v[56:59]
	s_setprio 0
	s_barrier
	ds_read_b128 v[156:159], v152
	ds_read_b128 v[160:163], v152 offset:1024
	ds_read_b128 v[164:167], v152 offset:2048
	ds_read_b128 v[168:171], v152 offset:3072
	ds_read_b128 v[172:175], v153
	ds_read_b128 v[176:179], v153 offset:1024
	ds_read_b128 v[184:187], v153 offset:2048
	ds_read_b128 v[188:191], v153 offset:3072
	s_add_u32 s40, s40, s48
	s_addc_u32 s41, s41, s49
	s_mov_b32 m0, s53
	v_lshl_add_u64 v[246:247], s[40:41], 0, v[2:3]
	ds_read_b128 v[192:195], v149 offset:32768
	ds_read_b128 v[196:199], v149 offset:33792
	ds_read_b128 v[200:203], v149 offset:34816
	ds_read_b128 v[204:207], v149 offset:35840
	ds_read_b128 v[230:233], v149 offset:36864
	ds_read_b128 v[234:237], v149 offset:37888
	ds_read_b128 v[238:241], v149 offset:38912
	ds_read_b128 v[242:245], v149 offset:39936
	global_load_lds_dwordx4 v[246:247], off
	v_lshl_add_u64 v[246:247], s[40:41], 0, v[136:137]
	s_mov_b32 m0, s72
	s_nop 0
	global_load_lds_dwordx4 v[246:247], off
	s_waitcnt vmcnt(8)
	s_waitcnt lgkmcnt(0)
	s_barrier
	s_setprio 1
	s_waitcnt lgkmcnt(0)
	v_mfma_f32_16x16x32_bf16 v[132:135], v[156:159], v[192:195], v[132:135]
	v_mfma_f32_16x16x32_bf16 v[116:119], v[156:159], v[200:203], v[116:119]
	v_mfma_f32_16x16x32_bf16 v[100:103], v[156:159], v[230:233], v[100:103]
	v_mfma_f32_16x16x32_bf16 v[84:87], v[156:159], v[238:241], v[84:87]
	v_mfma_f32_16x16x32_bf16 v[80:83], v[164:167], v[238:241], v[80:83]
	v_mfma_f32_16x16x32_bf16 v[96:99], v[164:167], v[230:233], v[96:99]
	v_mfma_f32_16x16x32_bf16 v[112:115], v[164:167], v[200:203], v[112:115]
	v_mfma_f32_16x16x32_bf16 v[128:131], v[164:167], v[192:195], v[128:131]
	v_mfma_f32_16x16x32_bf16 v[132:135], v[160:163], v[196:199], v[132:135]
	v_mfma_f32_16x16x32_bf16 v[116:119], v[160:163], v[204:207], v[116:119]
	v_mfma_f32_16x16x32_bf16 v[100:103], v[160:163], v[234:237], v[100:103]
	v_mfma_f32_16x16x32_bf16 v[84:87], v[160:163], v[242:245], v[84:87]
	v_mfma_f32_16x16x32_bf16 v[80:83], v[168:171], v[242:245], v[80:83]
	v_mfma_f32_16x16x32_bf16 v[96:99], v[168:171], v[234:237], v[96:99]
	v_mfma_f32_16x16x32_bf16 v[112:115], v[168:171], v[204:207], v[112:115]
	v_mfma_f32_16x16x32_bf16 v[128:131], v[168:171], v[196:199], v[128:131]
	s_setprio 0
	s_setprio 1
	v_mfma_f32_16x16x32_bf16 v[124:127], v[172:175], v[192:195], v[124:127]
	v_mfma_f32_16x16x32_bf16 v[108:111], v[172:175], v[200:203], v[108:111]
	v_mfma_f32_16x16x32_bf16 v[92:95], v[172:175], v[230:233], v[92:95]
	v_mfma_f32_16x16x32_bf16 v[76:79], v[172:175], v[238:241], v[76:79]
	v_mfma_f32_16x16x32_bf16 v[72:75], v[184:187], v[238:241], v[72:75]
	v_mfma_f32_16x16x32_bf16 v[88:91], v[184:187], v[230:233], v[88:91]
	v_mfma_f32_16x16x32_bf16 v[104:107], v[184:187], v[200:203], v[104:107]
	v_mfma_f32_16x16x32_bf16 v[120:123], v[184:187], v[192:195], v[120:123]
	v_mfma_f32_16x16x32_bf16 v[124:127], v[176:179], v[196:199], v[124:127]
	v_mfma_f32_16x16x32_bf16 v[108:111], v[176:179], v[204:207], v[108:111]
	v_mfma_f32_16x16x32_bf16 v[92:95], v[176:179], v[234:237], v[92:95]
	v_mfma_f32_16x16x32_bf16 v[76:79], v[176:179], v[242:245], v[76:79]
	v_mfma_f32_16x16x32_bf16 v[72:75], v[188:191], v[242:245], v[72:75]
	v_mfma_f32_16x16x32_bf16 v[88:91], v[188:191], v[234:237], v[88:91]
	v_mfma_f32_16x16x32_bf16 v[104:107], v[188:191], v[204:207], v[104:107]
	v_mfma_f32_16x16x32_bf16 v[120:123], v[188:191], v[196:199], v[120:123]
	s_setprio 0
	s_barrier
; #define PG8_STAGE(bufoff, gbase, voff) do { _Pragma("unroll") for (int _i = 0; _i < 2; ++_i) \
;         __builtin_amdgcn_global_load_lds((const unsigned*)((const char*)(gbase) + (voff)[_i]), (PG8_LAS unsigned*)(lds + (bufoff) + ldsw + _i * 8192), 16, 0, 0); } while (0)
; #define PG8_LDA(dst, b, h) do { _Pragma("unroll") for (int m = 0; m < 4; ++m) _Pragma("unroll") for (int k = 0; k < 2; ++k) dst[m][k] = *(const PG8_LAS bf16x8*)(lds + PG8_SA(b, h) + aoff + m * 2048 + k * 1024); } while (0)
; #define PG8_WAIT_V(n) asm volatile("s_waitcnt vmcnt(" #n ")" ::: "memory")
; #define PG8_BAR __builtin_amdgcn_s_barrier()
; template <class Epi, class Sched, bool ALIGN_EPI = false, bool SP2 = false>
; __device__ __forceinline__ void gemm_phase(PG8_LAS unsigned char* lds, const Gemm g, const Sched& S, const Epi& E) {
;     ...
;         for (int t = 0; t < nt; t += 2) {
;             if constexpr (Epi::KHOOK) { if ((t & 7) == 0 && t != 0) E.khook(acc, t >> 3, wr, fr, lds); }
;             const bool last = (t == nt - 2);
;             const char* a1 = cA + (size_t)(t + 1) * kstep;
;             const char* a2 = last ? nA : cA + (size_t)(t + 2) * kstep; const char* b2 = last ? nB : cB + (size_t)(t + 2) * kstep;
;             const char* a3 = a2 + kstep; const char* b3 = b2 + kstep;
;             if (last && has_next) S.a_ready(nxt);
;             if constexpr (SP2) {
;             PG8_LDB(B0, 0, 0); PG8_LDB(B1, 0, 1); PG8_SCHED; PG8_LDA(At, 0, 0); PG8_STAGE(PG8_SA(1, 1), a1 + hstep, voffA);
;             PG8_WAIT_V(8); PG8_WAIT_L(0); PG8_BAR; PG8_MMA(0, 0, At, B0); PG8_MMA(0, 1, At, B1); PG8_BAR; PG8_SCHED;
;             PG8_LDA(At, 0, 1); PG8_STAGE(PG8_SB(0, 0), b2, voffB); PG8_STAGE(PG8_SB(0, 1), b2 + hstep, voffB); PG8_STAGE(PG8_SA(0, 0), a2, voffA);
;             PG8_WAIT_V(8); PG8_WAIT_L(0); PG8_BAR; PG8_MMA(1, 0, At, B0); PG8_MMA(1, 1, At, B1); PG8_BAR; PG8_SCHED;
;             PG8_LDB(B0, 1, 0); PG8_LDB(B1, 1, 1); PG8_SCHED; PG8_LDA(At, 1, 0); PG8_STAGE(PG8_SA(0, 1), a2 + hstep, voffA);
;             PG8_WAIT_V(8); PG8_WAIT_L(0); PG8_BAR; PG8_MMA(0, 0, At, B0); PG8_MMA(0, 1, At, B1); PG8_BAR; PG8_SCHED;
;             PG8_LDA(At, 1, 1); PG8_STAGE(PG8_SB(1, 0), b3, voffB); PG8_STAGE(PG8_SB(1, 1), b3 + hstep, voffB); PG8_STAGE(PG8_SA(1, 0), a3, voffA);
;             PG8_WAIT_V(8); PG8_WAIT_L(0); PG8_BAR; PG8_MMA(1, 0, At, B0); PG8_MMA(1, 1, At, B1); PG8_BAR; PG8_SCHED;
	s_mov_b32 m0, s85
	v_lshl_add_u64 v[180:181], v[180:181], 0, s[24:25]
	ds_read_b128 v[192:195], v149 offset:49152
	ds_read_b128 v[196:199], v149 offset:50176
	ds_read_b128 v[200:203], v149 offset:51200
	ds_read_b128 v[204:207], v149 offset:52224
	ds_read_b128 v[230:233], v149 offset:53248
	ds_read_b128 v[234:237], v149 offset:54272
	ds_read_b128 v[238:241], v149 offset:55296
	ds_read_b128 v[242:245], v149 offset:56320
	global_load_lds_dwordx4 v[180:181], off
	v_lshl_add_u64 v[180:181], v[208:209], 0, s[24:25]
	s_mov_b32 m0, s86
	s_nop 0
	global_load_lds_dwordx4 v[180:181], off
	v_lshl_add_u64 v[180:181], v[216:217], 0, s[24:25]
	s_mov_b32 m0, s87
	s_nop 0
	global_load_lds_dwordx4 v[180:181], off
	v_lshl_add_u64 v[180:181], v[224:225], 0, s[24:25]
	s_mov_b32 m0, s88
	s_nop 0
	global_load_lds_dwordx4 v[180:181], off
	v_lshl_add_u64 v[180:181], v[226:227], 0, s[24:25]
	s_mov_b32 m0, s75
	s_nop 0
	global_load_lds_dwordx4 v[180:181], off
	v_lshl_add_u64 v[180:181], v[228:229], 0, s[24:25]
	s_mov_b32 m0, s76
	s_nop 0
	global_load_lds_dwordx4 v[180:181], off
	s_waitcnt vmcnt(8)
	s_waitcnt lgkmcnt(0)
	s_barrier
	s_setprio 1
	s_waitcnt lgkmcnt(0)
	v_mfma_f32_16x16x32_bf16 v[68:71], v[156:159], v[192:195], v[68:71]
	v_mfma_f32_16x16x32_bf16 v[52:55], v[156:159], v[200:203], v[52:55]
	v_mfma_f32_16x16x32_bf16 v[36:39], v[156:159], v[230:233], v[36:39]
	v_mfma_f32_16x16x32_bf16 v[20:23], v[156:159], v[238:241], v[20:23]
	v_mfma_f32_16x16x32_bf16 v[16:19], v[164:167], v[238:241], v[16:19]
	v_mfma_f32_16x16x32_bf16 v[32:35], v[164:167], v[230:233], v[32:35]
	v_mfma_f32_16x16x32_bf16 v[48:51], v[164:167], v[200:203], v[48:51]
	v_mfma_f32_16x16x32_bf16 v[64:67], v[164:167], v[192:195], v[64:67]
	v_mfma_f32_16x16x32_bf16 v[68:71], v[160:163], v[196:199], v[68:71]
	v_mfma_f32_16x16x32_bf16 v[52:55], v[160:163], v[204:207], v[52:55]
	v_mfma_f32_16x16x32_bf16 v[36:39], v[160:163], v[234:237], v[36:39]
	v_mfma_f32_16x16x32_bf16 v[20:23], v[160:163], v[242:245], v[20:23]
	v_mfma_f32_16x16x32_bf16 v[16:19], v[168:171], v[242:245], v[16:19]
	v_mfma_f32_16x16x32_bf16 v[32:35], v[168:171], v[234:237], v[32:35]
	v_mfma_f32_16x16x32_bf16 v[48:51], v[168:171], v[204:207], v[48:51]
	v_mfma_f32_16x16x32_bf16 v[64:67], v[168:171], v[196:199], v[64:67]
	s_setprio 0
	s_setprio 1
	v_mfma_f32_16x16x32_bf16 v[60:63], v[172:175], v[192:195], v[60:63]
	v_mfma_f32_16x16x32_bf16 v[44:47], v[172:175], v[200:203], v[44:47]
	v_mfma_f32_16x16x32_bf16 v[28:31], v[172:175], v[230:233], v[28:31]
	v_mfma_f32_16x16x32_bf16 v[12:15], v[172:175], v[238:241], v[12:15]
	v_mfma_f32_16x16x32_bf16 v[8:11], v[184:187], v[238:241], v[8:11]
	v_mfma_f32_16x16x32_bf16 v[24:27], v[184:187], v[230:233], v[24:27]
	v_mfma_f32_16x16x32_bf16 v[40:43], v[184:187], v[200:203], v[40:43]
	v_mfma_f32_16x16x32_bf16 v[56:59], v[184:187], v[192:195], v[56:59]
	v_mfma_f32_16x16x32_bf16 v[60:63], v[176:179], v[196:199], v[60:63]
	v_mfma_f32_16x16x32_bf16 v[44:47], v[176:179], v[204:207], v[44:47]
	v_mfma_f32_16x16x32_bf16 v[28:31], v[176:179], v[234:237], v[28:31]
	v_mfma_f32_16x16x32_bf16 v[12:15], v[176:179], v[242:245], v[12:15]
	v_mfma_f32_16x16x32_bf16 v[8:11], v[188:191], v[242:245], v[8:11]
	v_mfma_f32_16x16x32_bf16 v[24:27], v[188:191], v[234:237], v[24:27]
	v_mfma_f32_16x16x32_bf16 v[40:43], v[188:191], v[204:207], v[40:43]
	v_mfma_f32_16x16x32_bf16 v[56:59], v[188:191], v[196:199], v[56:59]
	s_setprio 0
	s_barrier
	s_add_i32 s40, s93, 2
	s_add_u32 s22, s22, 0x100
	s_addc_u32 s23, s23, 0
	s_add_u32 s89, s89, 0x100
	s_addc_u32 s92, s92, 0
	s_cmp_ge_u32 s93, s9
	v_add_u32_e32 v154, 0x100, v154
	s_cbranch_scc0 .LBB0_248

; #define PG8_STAGE(bufoff, gbase, voff) do { _Pragma("unroll") for (int _i = 0; _i < 2; ++_i) \
;         __builtin_amdgcn_global_load_lds((const unsigned*)((const char*)(gbase) + (voff)[_i]), (PG8_LAS unsigned*)(lds + (bufoff) + ldsw + _i * 8192), 16, 0, 0); } while (0)
; #define PG8_LDA(dst, b, h) do { _Pragma("unroll") for (int m = 0; m < 4; ++m) _Pragma("unroll") for (int k = 0; k < 2; ++k) dst[m][k] = *(const PG8_LAS bf16x8*)(lds + PG8_SA(b, h) + aoff + m * 2048 + k * 1024); } while (0)
; #define PG8_LDB(dst, b, h) do { _Pragma("unroll") for (int n = 0; n < 2; ++n) _Pragma("unroll") for (int k = 0; k < 2; ++k) dst[n][k] = *(const PG8_LAS bf16x8*)(lds + PG8_SB(b, h) + boff + n * 2048 + k * 1024); } while (0)
; #define PG8_MMA(ai, bj, At, Bt) do { __builtin_amdgcn_s_setprio(1); _Pragma("unroll") for (int m = 0; m < 4; ++m) _Pragma("unroll") for (int n = 0; n < 2; ++n) _Pragma("unroll") for (int k = 0; k < 2; ++k) \
;         acc[ai][bj][m][n] = __builtin_amdgcn_mfma_f32_16x16x32_bf16(Bt[n][k], At[m][k], acc[ai][bj][m][n], 0, 0, 0); __builtin_amdgcn_s_setprio(0); } while (0)
; #define PG8_WAIT_V(n) asm volatile("s_waitcnt vmcnt(" #n ")" ::: "memory")
; template <class Epi, class Sched, bool ALIGN_EPI = false, bool SP2 = false>
; __device__ __forceinline__ void gemm_phase(PG8_LAS unsigned char* lds, const Gemm g, const Sched& S, const Epi& E) {
;     ...
;             PG8_LDB(B0, 0, 0); PG8_LDB(B1, 0, 1); PG8_SCHED; PG8_LDA(At, 0, 0); PG8_STAGE(PG8_SA(1, 1), a1 + hstep, voffA);
;             PG8_WAIT_V(8); PG8_WAIT_L(0); PG8_BAR; PG8_MMA(0, 0, At, B0); PG8_MMA(0, 1, At, B1); PG8_BAR; PG8_SCHED;
;             PG8_LDA(At, 0, 1); PG8_STAGE(PG8_SB(0, 0), b2, voffB); PG8_STAGE(PG8_SB(0, 1), b2 + hstep, voffB); PG8_STAGE(PG8_SA(0, 0), a2, voffA);
;             PG8_WAIT_V(8); PG8_WAIT_L(0); PG8_BAR; PG8_MMA(1, 0, At, B0); PG8_MMA(1, 1, At, B1); PG8_BAR; PG8_SCHED;
;             PG8_LDB(B0, 1, 0); PG8_LDB(B1, 1, 1); PG8_SCHED; PG8_LDA(At, 1, 0); PG8_STAGE(PG8_SA(0, 1), a2 + hstep, voffA);
;             PG8_WAIT_V(8); PG8_WAIT_L(0); PG8_BAR; PG8_MMA(0, 0, At, B0); PG8_MMA(0, 1, At, B1); PG8_BAR; PG8_SCHED;
;             PG8_LDA(At, 1, 1); PG8_STAGE(PG8_SB(1, 0), b3, voffB); PG8_STAGE(PG8_SB(1, 1), b3 + hstep, voffB); PG8_STAGE(PG8_SA(1, 0), a3, voffA);
;             PG8_WAIT_V(8); PG8_WAIT_L(0); PG8_BAR; PG8_MMA(1, 0, At, B0); PG8_MMA(1, 1, At, B1); PG8_BAR; PG8_SCHED;
.LBB0_294:
	s_add_i32 s81, s40, 2
	s_add_u32 s82, s38, 0x80
	s_addc_u32 s41, s39, 0
	s_cmp_eq_u32 s33, s40
	s_cselect_b32 s41, s7, s41
	s_cselect_b32 s40, s6, s82
	v_add_u32_e32 v0, s19, v151
	s_cselect_b32 s83, s23, s80
	s_cselect_b32 s82, s22, s79
	s_add_i32 s84, 0, 0x14000
	ds_read_b128 v[154:157], v0
	ds_read_b128 v[158:161], v0 offset:1024
	ds_read_b128 v[162:165], v0 offset:2048
	ds_read_b128 v[166:169], v0 offset:3072
	v_add_u32_e32 v0, s84, v151
	ds_read_b128 v[170:173], v0
	ds_read_b128 v[174:177], v0 offset:1024
	ds_read_b128 v[178:181], v0 offset:2048
	ds_read_b128 v[184:187], v0 offset:3072
	v_lshl_add_u64 v[2:3], s[38:39], 0, v[144:145]
	s_add_i32 m0, s46, 0xc000
	ds_read_b128 v[188:191], v152
	ds_read_b128 v[192:195], v152 offset:1024
	ds_read_b128 v[196:199], v152 offset:2048
	ds_read_b128 v[200:203], v152 offset:3072
	ds_read_b128 v[204:207], v152 offset:4096
	ds_read_b128 v[230:233], v152 offset:5120
	ds_read_b128 v[234:237], v152 offset:6144
	ds_read_b128 v[238:241], v152 offset:7168
	global_load_lds_dwordx4 v[2:3], off
	v_lshl_add_u64 v[2:3], s[38:39], 0, v[146:147]
	s_add_i32 m0, s46, 0xe000
	s_nop 0
	global_load_lds_dwordx4 v[2:3], off
	s_waitcnt vmcnt(8)
	s_waitcnt lgkmcnt(0)
	s_barrier
	s_setprio 1
	s_waitcnt lgkmcnt(0)
	v_mfma_f32_16x16x32_bf16 v[8:11], v[154:157], v[188:191], v[8:11]
	v_mfma_f32_16x16x32_bf16 v[48:51], v[154:157], v[196:199], v[48:51]
	v_mfma_f32_16x16x32_bf16 v[96:99], v[154:157], v[204:207], v[96:99]
	v_mfma_f32_16x16x32_bf16 v[120:123], v[154:157], v[234:237], v[120:123]
	v_mfma_f32_16x16x32_bf16 v[124:127], v[162:165], v[234:237], v[124:127]
	v_mfma_f32_16x16x32_bf16 v[100:103], v[162:165], v[204:207], v[100:103]
	v_mfma_f32_16x16x32_bf16 v[52:55], v[162:165], v[196:199], v[52:55]
	v_mfma_f32_16x16x32_bf16 v[12:15], v[162:165], v[188:191], v[12:15]
	v_mfma_f32_16x16x32_bf16 v[8:11], v[158:161], v[192:195], v[8:11]
	v_mfma_f32_16x16x32_bf16 v[48:51], v[158:161], v[200:203], v[48:51]
	v_mfma_f32_16x16x32_bf16 v[96:99], v[158:161], v[230:233], v[96:99]
	v_mfma_f32_16x16x32_bf16 v[120:123], v[158:161], v[238:241], v[120:123]
	v_mfma_f32_16x16x32_bf16 v[124:127], v[166:169], v[238:241], v[124:127]
	v_mfma_f32_16x16x32_bf16 v[100:103], v[166:169], v[230:233], v[100:103]
	v_mfma_f32_16x16x32_bf16 v[52:55], v[166:169], v[200:203], v[52:55]
	v_mfma_f32_16x16x32_bf16 v[12:15], v[166:169], v[192:195], v[12:15]
	s_setprio 0
	s_setprio 1
	v_mfma_f32_16x16x32_bf16 v[24:27], v[170:173], v[188:191], v[24:27]
	v_mfma_f32_16x16x32_bf16 v[72:75], v[170:173], v[196:199], v[72:75]
	v_mfma_f32_16x16x32_bf16 v[112:115], v[170:173], v[204:207], v[112:115]
	v_mfma_f32_16x16x32_bf16 v[128:131], v[170:173], v[234:237], v[128:131]
	v_mfma_f32_16x16x32_bf16 v[132:135], v[178:181], v[234:237], v[132:135]
	v_mfma_f32_16x16x32_bf16 v[116:119], v[178:181], v[204:207], v[116:119]
	v_mfma_f32_16x16x32_bf16 v[76:79], v[178:181], v[196:199], v[76:79]
	v_mfma_f32_16x16x32_bf16 v[28:31], v[178:181], v[188:191], v[28:31]
	v_mfma_f32_16x16x32_bf16 v[24:27], v[174:177], v[192:195], v[24:27]
	v_mfma_f32_16x16x32_bf16 v[72:75], v[174:177], v[200:203], v[72:75]
	v_mfma_f32_16x16x32_bf16 v[112:115], v[174:177], v[230:233], v[112:115]
	v_mfma_f32_16x16x32_bf16 v[128:131], v[174:177], v[238:241], v[128:131]
	v_mfma_f32_16x16x32_bf16 v[132:135], v[184:187], v[238:241], v[132:135]
	v_mfma_f32_16x16x32_bf16 v[116:119], v[184:187], v[230:233], v[116:119]
	v_mfma_f32_16x16x32_bf16 v[76:79], v[184:187], v[200:203], v[76:79]
	v_mfma_f32_16x16x32_bf16 v[28:31], v[184:187], v[192:195], v[28:31]
	s_setprio 0
	s_barrier
	s_add_i32 s85, s19, s37
	v_lshl_add_u64 v[2:3], s[82:83], 0, v[140:141]
	s_mov_b32 m0, s85
	ds_read_b128 v[188:191], v152 offset:16384
	ds_read_b128 v[192:195], v152 offset:17408
	ds_read_b128 v[196:199], v152 offset:18432
	ds_read_b128 v[200:203], v152 offset:19456
	ds_read_b128 v[204:207], v152 offset:20480
	ds_read_b128 v[230:233], v152 offset:21504
	ds_read_b128 v[234:237], v152 offset:22528
	ds_read_b128 v[238:241], v152 offset:23552
	global_load_lds_dwordx4 v[2:3], off
	s_add_i32 m0, s85, 0x2000
	v_lshl_add_u64 v[208:209], s[82:83], 0, v[136:137]
	s_add_u32 s82, s82, s48
	s_addc_u32 s83, s83, s49
	s_add_i32 s84, s84, s37
	global_load_lds_dwordx4 v[208:209], off
	v_lshl_add_u64 v[216:217], s[82:83], 0, v[140:141]
	s_mov_b32 m0, s84
	v_lshl_add_u64 v[224:225], s[82:83], 0, v[136:137]
	global_load_lds_dwordx4 v[216:217], off
	s_add_i32 m0, s84, 0x2000
	v_lshl_add_u64 v[226:227], s[40:41], 0, v[142:143]
	global_load_lds_dwordx4 v[224:225], off
	s_mov_b32 m0, s46
	v_lshl_add_u64 v[228:229], s[40:41], 0, v[138:139]
	global_load_lds_dwordx4 v[226:227], off
	s_mov_b32 m0, s47
	s_nop 0
	global_load_lds_dwordx4 v[228:229], off
	s_waitcnt vmcnt(8)
	s_waitcnt lgkmcnt(0)
	s_barrier
; #define PG8_STAGE(bufoff, gbase, voff) do { _Pragma("unroll") for (int _i = 0; _i < 2; ++_i) \
;         __builtin_amdgcn_global_load_lds((const unsigned*)((const char*)(gbase) + (voff)[_i]), (PG8_LAS unsigned*)(lds + (bufoff) + ldsw + _i * 8192), 16, 0, 0); } while (0)
; #define PG8_LDA(dst, b, h) do { _Pragma("unroll") for (int m = 0; m < 4; ++m) _Pragma("unroll") for (int k = 0; k < 2; ++k) dst[m][k] = *(const PG8_LAS bf16x8*)(lds + PG8_SA(b, h) + aoff + m * 2048 + k * 1024); } while (0)
; #define PG8_LDB(dst, b, h) do { _Pragma("unroll") for (int n = 0; n < 2; ++n) _Pragma("unroll") for (int k = 0; k < 2; ++k) dst[n][k] = *(const PG8_LAS bf16x8*)(lds + PG8_SB(b, h) + boff + n * 2048 + k * 1024); } while (0)
; #define PG8_MMA(ai, bj, At, Bt) do { __builtin_amdgcn_s_setprio(1); _Pragma("unroll") for (int m = 0; m < 4; ++m) _Pragma("unroll") for (int n = 0; n < 2; ++n) _Pragma("unroll") for (int k = 0; k < 2; ++k) \
;         acc[ai][bj][m][n] = __builtin_amdgcn_mfma_f32_16x16x32_bf16(Bt[n][k], At[m][k], acc[ai][bj][m][n], 0, 0, 0); __builtin_amdgcn_s_setprio(0); } while (0)
; #define PG8_WAIT_V(n) asm volatile("s_waitcnt vmcnt(" #n ")" ::: "memory")
; template <class Epi, class Sched, bool ALIGN_EPI = false, bool SP2 = false>
; __device__ __forceinline__ void gemm_phase(PG8_LAS unsigned char* lds, const Gemm g, const Sched& S, const Epi& E) {
;     ...
;             PG8_LDB(B0, 0, 0); PG8_LDB(B1, 0, 1); PG8_SCHED; PG8_LDA(At, 0, 0); PG8_STAGE(PG8_SA(1, 1), a1 + hstep, voffA);
;             PG8_WAIT_V(8); PG8_WAIT_L(0); PG8_BAR; PG8_MMA(0, 0, At, B0); PG8_MMA(0, 1, At, B1); PG8_BAR; PG8_SCHED;
;             PG8_LDA(At, 0, 1); PG8_STAGE(PG8_SB(0, 0), b2, voffB); PG8_STAGE(PG8_SB(0, 1), b2 + hstep, voffB); PG8_STAGE(PG8_SA(0, 0), a2, voffA);
;             PG8_WAIT_V(8); PG8_WAIT_L(0); PG8_BAR; PG8_MMA(1, 0, At, B0); PG8_MMA(1, 1, At, B1); PG8_BAR; PG8_SCHED;
;             PG8_LDB(B0, 1, 0); PG8_LDB(B1, 1, 1); PG8_SCHED; PG8_LDA(At, 1, 0); PG8_STAGE(PG8_SA(0, 1), a2 + hstep, voffA);
;             PG8_WAIT_V(8); PG8_WAIT_L(0); PG8_BAR; PG8_MMA(0, 0, At, B0); PG8_MMA(0, 1, At, B1); PG8_BAR; PG8_SCHED;
;             PG8_LDA(At, 1, 1); PG8_STAGE(PG8_SB(1, 0), b3, voffB); PG8_STAGE(PG8_SB(1, 1), b3 + hstep, voffB); PG8_STAGE(PG8_SA(1, 0), a3, voffA);
;             PG8_WAIT_V(8); PG8_WAIT_L(0); PG8_BAR; PG8_MMA(1, 0, At, B0); PG8_MMA(1, 1, At, B1); PG8_BAR; PG8_SCHED;
	s_setprio 1
	s_waitcnt lgkmcnt(0)
	v_mfma_f32_16x16x32_bf16 v[16:19], v[154:157], v[188:191], v[16:19]
	v_mfma_f32_16x16x32_bf16 v[56:59], v[154:157], v[196:199], v[56:59]
	v_mfma_f32_16x16x32_bf16 v[104:107], v[154:157], v[204:207], v[104:107]
	v_mfma_f32_16x16x32_bf16 v[68:71], v[154:157], v[234:237], v[68:71]
	v_mfma_f32_16x16x32_bf16 v[64:67], v[162:165], v[234:237], v[64:67]
	v_mfma_f32_16x16x32_bf16 v[108:111], v[162:165], v[204:207], v[108:111]
	v_mfma_f32_16x16x32_bf16 v[60:63], v[162:165], v[196:199], v[60:63]
	v_mfma_f32_16x16x32_bf16 v[20:23], v[162:165], v[188:191], v[20:23]
	v_mfma_f32_16x16x32_bf16 v[16:19], v[158:161], v[192:195], v[16:19]
	v_mfma_f32_16x16x32_bf16 v[56:59], v[158:161], v[200:203], v[56:59]
	v_mfma_f32_16x16x32_bf16 v[104:107], v[158:161], v[230:233], v[104:107]
	v_mfma_f32_16x16x32_bf16 v[68:71], v[158:161], v[238:241], v[68:71]
	v_mfma_f32_16x16x32_bf16 v[64:67], v[166:169], v[238:241], v[64:67]
	v_mfma_f32_16x16x32_bf16 v[108:111], v[166:169], v[230:233], v[108:111]
	v_mfma_f32_16x16x32_bf16 v[60:63], v[166:169], v[200:203], v[60:63]
	v_mfma_f32_16x16x32_bf16 v[20:23], v[166:169], v[192:195], v[20:23]
	s_setprio 0
	s_setprio 1
	v_mfma_f32_16x16x32_bf16 v[40:43], v[170:173], v[188:191], v[40:43]
	v_mfma_f32_16x16x32_bf16 v[88:91], v[170:173], v[196:199], v[88:91]
	v_mfma_f32_16x16x32_bf16 v[84:87], v[170:173], v[204:207], v[84:87]
	v_mfma_f32_16x16x32_bf16 v[36:39], v[170:173], v[234:237], v[36:39]
	v_mfma_f32_16x16x32_bf16 v[32:35], v[178:181], v[234:237], v[32:35]
	v_mfma_f32_16x16x32_bf16 v[80:83], v[178:181], v[204:207], v[80:83]
	v_mfma_f32_16x16x32_bf16 v[92:95], v[178:181], v[196:199], v[92:95]
	v_mfma_f32_16x16x32_bf16 v[44:47], v[178:181], v[188:191], v[44:47]
	v_mfma_f32_16x16x32_bf16 v[40:43], v[174:177], v[192:195], v[40:43]
	v_mfma_f32_16x16x32_bf16 v[88:91], v[174:177], v[200:203], v[88:91]
	v_mfma_f32_16x16x32_bf16 v[84:87], v[174:177], v[230:233], v[84:87]
	v_mfma_f32_16x16x32_bf16 v[36:39], v[174:177], v[238:241], v[36:39]
	v_mfma_f32_16x16x32_bf16 v[32:35], v[184:187], v[238:241], v[32:35]
	v_mfma_f32_16x16x32_bf16 v[80:83], v[184:187], v[230:233], v[80:83]
	v_mfma_f32_16x16x32_bf16 v[92:95], v[184:187], v[200:203], v[92:95]
	v_mfma_f32_16x16x32_bf16 v[44:47], v[184:187], v[192:195], v[44:47]
	s_setprio 0
	s_barrier
	v_add_u32_e32 v0, s91, v151
	s_add_i32 s82, 0, 0x1c000
	ds_read_b128 v[154:157], v0
	ds_read_b128 v[158:161], v0 offset:1024
	ds_read_b128 v[162:165], v0 offset:2048
	ds_read_b128 v[166:169], v0 offset:3072
	v_add_u32_e32 v0, s82, v151
	ds_read_b128 v[170:173], v0
	ds_read_b128 v[174:177], v0 offset:1024
	ds_read_b128 v[178:181], v0 offset:2048
	ds_read_b128 v[184:187], v0 offset:3072
	s_add_u32 s40, s40, s48
	s_addc_u32 s41, s41, s49
	s_mov_b32 m0, s52
	v_lshl_add_u64 v[242:243], s[40:41], 0, v[142:143]
	ds_read_b128 v[188:191], v152 offset:32768
	ds_read_b128 v[192:195], v152 offset:33792
	ds_read_b128 v[196:199], v152 offset:34816
	ds_read_b128 v[200:203], v152 offset:35840
	ds_read_b128 v[204:207], v152 offset:36864
	ds_read_b128 v[230:233], v152 offset:37888
	ds_read_b128 v[234:237], v152 offset:38912
	ds_read_b128 v[238:241], v152 offset:39936
	global_load_lds_dwordx4 v[242:243], off
	v_lshl_add_u64 v[242:243], s[40:41], 0, v[138:139]
	s_mov_b32 m0, s53
	s_nop 0
	global_load_lds_dwordx4 v[242:243], off
	s_waitcnt vmcnt(8)
	s_waitcnt lgkmcnt(0)
	s_barrier
	s_setprio 1
	s_waitcnt lgkmcnt(0)
	v_mfma_f32_16x16x32_bf16 v[8:11], v[154:157], v[188:191], v[8:11]
	v_mfma_f32_16x16x32_bf16 v[48:51], v[154:157], v[196:199], v[48:51]
	v_mfma_f32_16x16x32_bf16 v[96:99], v[154:157], v[204:207], v[96:99]
	v_mfma_f32_16x16x32_bf16 v[120:123], v[154:157], v[234:237], v[120:123]
	v_mfma_f32_16x16x32_bf16 v[124:127], v[162:165], v[234:237], v[124:127]
	v_mfma_f32_16x16x32_bf16 v[100:103], v[162:165], v[204:207], v[100:103]
	v_mfma_f32_16x16x32_bf16 v[52:55], v[162:165], v[196:199], v[52:55]
	v_mfma_f32_16x16x32_bf16 v[12:15], v[162:165], v[188:191], v[12:15]
	v_mfma_f32_16x16x32_bf16 v[8:11], v[158:161], v[192:195], v[8:11]
	v_mfma_f32_16x16x32_bf16 v[48:51], v[158:161], v[200:203], v[48:51]
	v_mfma_f32_16x16x32_bf16 v[96:99], v[158:161], v[230:233], v[96:99]
	v_mfma_f32_16x16x32_bf16 v[120:123], v[158:161], v[238:241], v[120:123]
	v_mfma_f32_16x16x32_bf16 v[124:127], v[166:169], v[238:241], v[124:127]
	v_mfma_f32_16x16x32_bf16 v[100:103], v[166:169], v[230:233], v[100:103]
	v_mfma_f32_16x16x32_bf16 v[52:55], v[166:169], v[200:203], v[52:55]
	v_mfma_f32_16x16x32_bf16 v[12:15], v[166:169], v[192:195], v[12:15]
	s_setprio 0
	s_setprio 1
	v_mfma_f32_16x16x32_bf16 v[24:27], v[170:173], v[188:191], v[24:27]
	v_mfma_f32_16x16x32_bf16 v[72:75], v[170:173], v[196:199], v[72:75]
	v_mfma_f32_16x16x32_bf16 v[112:115], v[170:173], v[204:207], v[112:115]
	v_mfma_f32_16x16x32_bf16 v[128:131], v[170:173], v[234:237], v[128:131]
	v_mfma_f32_16x16x32_bf16 v[132:135], v[178:181], v[234:237], v[132:135]
	v_mfma_f32_16x16x32_bf16 v[116:119], v[178:181], v[204:207], v[116:119]
	v_mfma_f32_16x16x32_bf16 v[76:79], v[178:181], v[196:199], v[76:79]
	v_mfma_f32_16x16x32_bf16 v[28:31], v[178:181], v[188:191], v[28:31]
	v_mfma_f32_16x16x32_bf16 v[24:27], v[174:177], v[192:195], v[24:27]
	v_mfma_f32_16x16x32_bf16 v[72:75], v[174:177], v[200:203], v[72:75]
	v_mfma_f32_16x16x32_bf16 v[112:115], v[174:177], v[230:233], v[112:115]
	v_mfma_f32_16x16x32_bf16 v[128:131], v[174:177], v[238:241], v[128:131]
	v_mfma_f32_16x16x32_bf16 v[132:135], v[184:187], v[238:241], v[132:135]
	v_mfma_f32_16x16x32_bf16 v[116:119], v[184:187], v[230:233], v[116:119]
	v_mfma_f32_16x16x32_bf16 v[76:79], v[184:187], v[200:203], v[76:79]
	v_mfma_f32_16x16x32_bf16 v[28:31], v[184:187], v[192:195], v[28:31]
	s_setprio 0
	s_barrier
; #define PG8_STAGE(bufoff, gbase, voff) do { _Pragma("unroll") for (int _i = 0; _i < 2; ++_i) \
;         __builtin_amdgcn_global_load_lds((const unsigned*)((const char*)(gbase) + (voff)[_i]), (PG8_LAS unsigned*)(lds + (bufoff) + ldsw + _i * 8192), 16, 0, 0); } while (0)
; #define PG8_LDA(dst, b, h) do { _Pragma("unroll") for (int m = 0; m < 4; ++m) _Pragma("unroll") for (int k = 0; k < 2; ++k) dst[m][k] = *(const PG8_LAS bf16x8*)(lds + PG8_SA(b, h) + aoff + m * 2048 + k * 1024); } while (0)
; #define PG8_WAIT_V(n) asm volatile("s_waitcnt vmcnt(" #n ")" ::: "memory")
; #define PG8_BAR __builtin_amdgcn_s_barrier()
; template <class Epi, class Sched, bool ALIGN_EPI = false, bool SP2 = false>
; __device__ __forceinline__ void gemm_phase(PG8_LAS unsigned char* lds, const Gemm g, const Sched& S, const Epi& E) {
;     ...
;         for (int t = 0; t < nt; t += 2) {
;             if constexpr (Epi::KHOOK) { if ((t & 7) == 0 && t != 0) E.khook(acc, t >> 3, wr, fr, lds); }
;             const bool last = (t == nt - 2);
;             const char* a1 = cA + (size_t)(t + 1) * kstep;
;             const char* a2 = last ? nA : cA + (size_t)(t + 2) * kstep; const char* b2 = last ? nB : cB + (size_t)(t + 2) * kstep;
;             const char* a3 = a2 + kstep; const char* b3 = b2 + kstep;
;             if (last && has_next) S.a_ready(nxt);
;             if constexpr (SP2) {
;             PG8_LDB(B0, 0, 0); PG8_LDB(B1, 0, 1); PG8_SCHED; PG8_LDA(At, 0, 0); PG8_STAGE(PG8_SA(1, 1), a1 + hstep, voffA);
;             PG8_WAIT_V(8); PG8_WAIT_L(0); PG8_BAR; PG8_MMA(0, 0, At, B0); PG8_MMA(0, 1, At, B1); PG8_BAR; PG8_SCHED;
;             PG8_LDA(At, 0, 1); PG8_STAGE(PG8_SB(0, 0), b2, voffB); PG8_STAGE(PG8_SB(0, 1), b2 + hstep, voffB); PG8_STAGE(PG8_SA(0, 0), a2, voffA);
;             PG8_WAIT_V(8); PG8_WAIT_L(0); PG8_BAR; PG8_MMA(1, 0, At, B0); PG8_MMA(1, 1, At, B1); PG8_BAR; PG8_SCHED;
;             PG8_LDB(B0, 1, 0); PG8_LDB(B1, 1, 1); PG8_SCHED; PG8_LDA(At, 1, 0); PG8_STAGE(PG8_SA(0, 1), a2 + hstep, voffA);
;             PG8_WAIT_V(8); PG8_WAIT_L(0); PG8_BAR; PG8_MMA(0, 0, At, B0); PG8_MMA(0, 1, At, B1); PG8_BAR; PG8_SCHED;
;             PG8_LDA(At, 1, 1); PG8_STAGE(PG8_SB(1, 0), b3, voffB); PG8_STAGE(PG8_SB(1, 1), b3 + hstep, voffB); PG8_STAGE(PG8_SA(1, 0), a3, voffA);
;             PG8_WAIT_V(8); PG8_WAIT_L(0); PG8_BAR; PG8_MMA(1, 0, At, B0); PG8_MMA(1, 1, At, B1); PG8_BAR; PG8_SCHED;
	s_add_i32 s40, s91, s37
	v_lshl_add_u64 v[2:3], v[2:3], 0, s[24:25]
	s_mov_b32 m0, s40
	ds_read_b128 v[188:191], v152 offset:49152
	ds_read_b128 v[192:195], v152 offset:50176
	ds_read_b128 v[196:199], v152 offset:51200
	ds_read_b128 v[200:203], v152 offset:52224
	ds_read_b128 v[204:207], v152 offset:53248
	ds_read_b128 v[230:233], v152 offset:54272
	ds_read_b128 v[234:237], v152 offset:55296
	ds_read_b128 v[238:241], v152 offset:56320
	global_load_lds_dwordx4 v[2:3], off
	v_lshl_add_u64 v[2:3], v[208:209], 0, s[24:25]
	s_add_i32 m0, s40, 0x2000
	s_add_i32 s40, s82, s37
	global_load_lds_dwordx4 v[2:3], off
	v_lshl_add_u64 v[2:3], v[216:217], 0, s[24:25]
	s_mov_b32 m0, s40
	s_nop 0
	global_load_lds_dwordx4 v[2:3], off
	v_lshl_add_u64 v[2:3], v[224:225], 0, s[24:25]
	s_add_i32 m0, s40, 0x2000
	s_nop 0
	global_load_lds_dwordx4 v[2:3], off
	v_lshl_add_u64 v[2:3], v[226:227], 0, s[24:25]
	s_mov_b32 m0, s73
	s_nop 0
	global_load_lds_dwordx4 v[2:3], off
	v_lshl_add_u64 v[2:3], v[228:229], 0, s[24:25]
	s_mov_b32 m0, s74
	s_nop 0
	global_load_lds_dwordx4 v[2:3], off
	s_waitcnt vmcnt(8)
	s_waitcnt lgkmcnt(0)
	s_barrier
	s_setprio 1
	s_waitcnt lgkmcnt(0)
	v_mfma_f32_16x16x32_bf16 v[16:19], v[154:157], v[188:191], v[16:19]
	v_mfma_f32_16x16x32_bf16 v[56:59], v[154:157], v[196:199], v[56:59]
	v_mfma_f32_16x16x32_bf16 v[104:107], v[154:157], v[204:207], v[104:107]
	v_mfma_f32_16x16x32_bf16 v[68:71], v[154:157], v[234:237], v[68:71]
	v_mfma_f32_16x16x32_bf16 v[64:67], v[162:165], v[234:237], v[64:67]
	v_mfma_f32_16x16x32_bf16 v[108:111], v[162:165], v[204:207], v[108:111]
	v_mfma_f32_16x16x32_bf16 v[60:63], v[162:165], v[196:199], v[60:63]
	v_mfma_f32_16x16x32_bf16 v[20:23], v[162:165], v[188:191], v[20:23]
	v_mfma_f32_16x16x32_bf16 v[16:19], v[158:161], v[192:195], v[16:19]
	v_mfma_f32_16x16x32_bf16 v[56:59], v[158:161], v[200:203], v[56:59]
	v_mfma_f32_16x16x32_bf16 v[104:107], v[158:161], v[230:233], v[104:107]
	v_mfma_f32_16x16x32_bf16 v[68:71], v[158:161], v[238:241], v[68:71]
	v_mfma_f32_16x16x32_bf16 v[64:67], v[166:169], v[238:241], v[64:67]
	v_mfma_f32_16x16x32_bf16 v[108:111], v[166:169], v[230:233], v[108:111]
	v_mfma_f32_16x16x32_bf16 v[60:63], v[166:169], v[200:203], v[60:63]
	v_mfma_f32_16x16x32_bf16 v[20:23], v[166:169], v[192:195], v[20:23]
	s_setprio 0
	s_setprio 1
	v_mfma_f32_16x16x32_bf16 v[40:43], v[170:173], v[188:191], v[40:43]
	v_mfma_f32_16x16x32_bf16 v[88:91], v[170:173], v[196:199], v[88:91]
	v_mfma_f32_16x16x32_bf16 v[84:87], v[170:173], v[204:207], v[84:87]
	v_mfma_f32_16x16x32_bf16 v[36:39], v[170:173], v[234:237], v[36:39]
	v_mfma_f32_16x16x32_bf16 v[32:35], v[178:181], v[234:237], v[32:35]
	v_mfma_f32_16x16x32_bf16 v[80:83], v[178:181], v[204:207], v[80:83]
	v_mfma_f32_16x16x32_bf16 v[92:95], v[178:181], v[196:199], v[92:95]
	v_mfma_f32_16x16x32_bf16 v[44:47], v[178:181], v[188:191], v[44:47]
	v_mfma_f32_16x16x32_bf16 v[40:43], v[174:177], v[192:195], v[40:43]
	v_mfma_f32_16x16x32_bf16 v[88:91], v[174:177], v[200:203], v[88:91]
	v_mfma_f32_16x16x32_bf16 v[84:87], v[174:177], v[230:233], v[84:87]
	v_mfma_f32_16x16x32_bf16 v[36:39], v[174:177], v[238:241], v[36:39]
	v_mfma_f32_16x16x32_bf16 v[32:35], v[184:187], v[238:241], v[32:35]
	v_mfma_f32_16x16x32_bf16 v[80:83], v[184:187], v[230:233], v[80:83]
	v_mfma_f32_16x16x32_bf16 v[92:95], v[184:187], v[200:203], v[92:95]
	v_mfma_f32_16x16x32_bf16 v[44:47], v[184:187], v[192:195], v[44:47]
	s_setprio 0
	s_barrier
	s_add_u32 s38, s38, 0x100
	s_addc_u32 s39, s39, 0
	s_add_u32 s79, s79, 0x100
	s_addc_u32 s80, s80, 0
	s_cmp_ge_u32 s81, s9
	s_mov_b32 s40, s81
	s_cbranch_scc0 .LBB0_294

; #define PG8_STAGE(bufoff, gbase, voff) do { _Pragma("unroll") for (int _i = 0; _i < 2; ++_i) \
;         __builtin_amdgcn_global_load_lds((const unsigned*)((const char*)(gbase) + (voff)[_i]), (PG8_LAS unsigned*)(lds + (bufoff) + ldsw + _i * 8192), 16, 0, 0); } while (0)
; #define PG8_LDA(dst, b, h) do { _Pragma("unroll") for (int m = 0; m < 4; ++m) _Pragma("unroll") for (int k = 0; k < 2; ++k) dst[m][k] = *(const PG8_LAS bf16x8*)(lds + PG8_SA(b, h) + aoff + m * 2048 + k * 1024); } while (0)
; #define PG8_LDB(dst, b, h) do { _Pragma("unroll") for (int n = 0; n < 2; ++n) _Pragma("unroll") for (int k = 0; k < 2; ++k) dst[n][k] = *(const PG8_LAS bf16x8*)(lds + PG8_SB(b, h) + boff + n * 2048 + k * 1024); } while (0)
; #define PG8_MMA(ai, bj, At, Bt) do { __builtin_amdgcn_s_setprio(1); _Pragma("unroll") for (int m = 0; m < 4; ++m) _Pragma("unroll") for (int n = 0; n < 2; ++n) _Pragma("unroll") for (int k = 0; k < 2; ++k) \
;         acc[ai][bj][m][n] = __builtin_amdgcn_mfma_f32_16x16x32_bf16(Bt[n][k], At[m][k], acc[ai][bj][m][n], 0, 0, 0); __builtin_amdgcn_s_setprio(0); } while (0)
; #define PG8_WAIT_V(n) asm volatile("s_waitcnt vmcnt(" #n ")" ::: "memory")
; template <class Epi, class Sched, bool ALIGN_EPI = false, bool SP2 = false>
; __device__ __forceinline__ void gemm_phase(PG8_LAS unsigned char* lds, const Gemm g, const Sched& S, const Epi& E) {
;     ...
;             PG8_LDB(B0, 0, 0); PG8_LDB(B1, 0, 1); PG8_SCHED; PG8_LDA(At, 0, 0); PG8_STAGE(PG8_SA(1, 1), a1 + hstep, voffA);
;             PG8_WAIT_V(8); PG8_WAIT_L(0); PG8_BAR; PG8_MMA(0, 0, At, B0); PG8_MMA(0, 1, At, B1); PG8_BAR; PG8_SCHED;
;             PG8_LDA(At, 0, 1); PG8_STAGE(PG8_SB(0, 0), b2, voffB); PG8_STAGE(PG8_SB(0, 1), b2 + hstep, voffB); PG8_STAGE(PG8_SA(0, 0), a2, voffA);
;             PG8_WAIT_V(8); PG8_WAIT_L(0); PG8_BAR; PG8_MMA(1, 0, At, B0); PG8_MMA(1, 1, At, B1); PG8_BAR; PG8_SCHED;
;             PG8_LDB(B0, 1, 0); PG8_LDB(B1, 1, 1); PG8_SCHED; PG8_LDA(At, 1, 0); PG8_STAGE(PG8_SA(0, 1), a2 + hstep, voffA);
;             PG8_WAIT_V(8); PG8_WAIT_L(0); PG8_BAR; PG8_MMA(0, 0, At, B0); PG8_MMA(0, 1, At, B1); PG8_BAR; PG8_SCHED;
;             PG8_LDA(At, 1, 1); PG8_STAGE(PG8_SB(1, 0), b3, voffB); PG8_STAGE(PG8_SB(1, 1), b3 + hstep, voffB); PG8_STAGE(PG8_SA(1, 0), a3, voffA);
;             PG8_WAIT_V(8); PG8_WAIT_L(0); PG8_BAR; PG8_MMA(1, 0, At, B0); PG8_MMA(1, 1, At, B1); PG8_BAR; PG8_SCHED;
.LBB0_365:
	s_add_i32 s88, s86, 2
	s_add_u32 s89, s0, 0x80
	s_addc_u32 s87, s1, 0
	s_cmp_eq_u32 s33, s86
	s_cselect_b32 s87, s3, s87
	s_cselect_b32 s86, s2, s89
	v_add_u32_e32 v0, s19, v230
	s_cselect_b32 vcc_hi, s85, s73
	s_cselect_b32 vcc_lo, s84, s72
	s_add_i32 s89, 0, 0x14000
	ds_read_b128 v[120:123], v0
	ds_read_b128 v[124:127], v0 offset:1024
	ds_read_b128 v[128:131], v0 offset:2048
	ds_read_b128 v[132:135], v0 offset:3072
	v_add_u32_e32 v0, s89, v230
	ds_read_b128 v[136:139], v0
	ds_read_b128 v[140:143], v0 offset:1024
	ds_read_b128 v[162:165], v0 offset:2048
	ds_read_b128 v[166:169], v0 offset:3072
	v_lshl_add_u64 v[144:145], s[0:1], 0, v[184:185]
	s_add_i32 m0, s93, 0xc000
	ds_read_b128 v[170:173], v238
	ds_read_b128 v[188:191], v238 offset:1024
	ds_read_b128 v[192:195], v238 offset:2048
	ds_read_b128 v[196:199], v238 offset:3072
	ds_read_b128 v[200:203], v238 offset:4096
	ds_read_b128 v[204:207], v238 offset:5120
	ds_read_b128 v[242:245], v238 offset:6144
	ds_read_b128 v[246:249], v238 offset:7168
	global_load_lds_dwordx4 v[144:145], off
	v_lshl_add_u64 v[144:145], s[0:1], 0, v[186:187]
	s_add_i32 m0, s93, 0xe000
	s_nop 0
	global_load_lds_dwordx4 v[144:145], off
	s_waitcnt vmcnt(8)
	s_waitcnt lgkmcnt(0)
	s_barrier
	s_setprio 1
	s_waitcnt lgkmcnt(0)
	v_mfma_f32_16x16x32_bf16 v[158:161], v[120:123], v[170:173], v[158:161]
	v_mfma_f32_16x16x32_bf16 v[150:153], v[120:123], v[192:195], v[150:153]
	v_mfma_f32_16x16x32_bf16 v[100:103], v[120:123], v[200:203], v[100:103]
	v_mfma_f32_16x16x32_bf16 v[116:119], v[120:123], v[242:245], v[116:119]
	v_mfma_f32_16x16x32_bf16 v[68:71], v[128:131], v[242:245], v[68:71]
	v_mfma_f32_16x16x32_bf16 v[36:39], v[128:131], v[200:203], v[36:39]
	v_mfma_f32_16x16x32_bf16 v[52:55], v[128:131], v[192:195], v[52:55]
	v_mfma_f32_16x16x32_bf16 v[60:63], v[128:131], v[170:173], v[60:63]
	v_mfma_f32_16x16x32_bf16 v[158:161], v[124:127], v[188:191], v[158:161]
	v_mfma_f32_16x16x32_bf16 v[150:153], v[124:127], v[196:199], v[150:153]
	v_mfma_f32_16x16x32_bf16 v[100:103], v[124:127], v[204:207], v[100:103]
	v_mfma_f32_16x16x32_bf16 v[116:119], v[124:127], v[246:249], v[116:119]
	v_mfma_f32_16x16x32_bf16 v[68:71], v[132:135], v[246:249], v[68:71]
	v_mfma_f32_16x16x32_bf16 v[36:39], v[132:135], v[204:207], v[36:39]
	v_mfma_f32_16x16x32_bf16 v[52:55], v[132:135], v[196:199], v[52:55]
	v_mfma_f32_16x16x32_bf16 v[60:63], v[132:135], v[188:191], v[60:63]
	s_setprio 0
	s_setprio 1
	v_mfma_f32_16x16x32_bf16 v[154:157], v[136:139], v[170:173], v[154:157]
	v_mfma_f32_16x16x32_bf16 v[144:147], v[136:139], v[192:195], v[146:149]
	v_mfma_f32_16x16x32_bf16 v[96:99], v[136:139], v[200:203], v[96:99]
	v_mfma_f32_16x16x32_bf16 v[112:115], v[136:139], v[242:245], v[112:115]
	v_mfma_f32_16x16x32_bf16 v[64:67], v[162:165], v[242:245], v[64:67]
	v_mfma_f32_16x16x32_bf16 v[32:35], v[162:165], v[200:203], v[32:35]
	v_mfma_f32_16x16x32_bf16 v[48:51], v[162:165], v[192:195], v[48:51]
	v_mfma_f32_16x16x32_bf16 v[56:59], v[162:165], v[170:173], v[56:59]
	v_mfma_f32_16x16x32_bf16 v[154:157], v[140:143], v[188:191], v[154:157]
	v_mfma_f32_16x16x32_bf16 v[144:147], v[140:143], v[196:199], v[144:147]
	v_mfma_f32_16x16x32_bf16 v[96:99], v[140:143], v[204:207], v[96:99]
	v_mfma_f32_16x16x32_bf16 v[112:115], v[140:143], v[246:249], v[112:115]
	v_mfma_f32_16x16x32_bf16 v[64:67], v[166:169], v[246:249], v[64:67]
	v_mfma_f32_16x16x32_bf16 v[32:35], v[166:169], v[204:207], v[32:35]
	v_mfma_f32_16x16x32_bf16 v[48:51], v[166:169], v[196:199], v[48:51]
	v_mfma_f32_16x16x32_bf16 v[56:59], v[166:169], v[188:191], v[56:59]
	s_setprio 0
	s_barrier
	s_add_i32 s38, s19, s92
	v_lshl_add_u64 v[174:175], vcc, 0, v[176:177]
	s_mov_b32 m0, s38
	ds_read_b128 v[170:173], v238 offset:16384
	ds_read_b128 v[188:191], v238 offset:17408
	ds_read_b128 v[192:195], v238 offset:18432
	ds_read_b128 v[196:199], v238 offset:19456
	ds_read_b128 v[200:203], v238 offset:20480
	ds_read_b128 v[204:207], v238 offset:21504
	ds_read_b128 v[242:245], v238 offset:22528
	ds_read_b128 v[246:249], v238 offset:23552
	global_load_lds_dwordx4 v[174:175], off
	s_add_i32 m0, s38, 0x2000
	v_lshl_add_u64 v[208:209], vcc, 0, v[180:181]
	s_add_u32 vcc_lo, vcc_lo, s48
	s_addc_u32 vcc_hi, vcc_hi, s49
	s_add_i32 s38, s89, s92
	global_load_lds_dwordx4 v[208:209], off
	v_lshl_add_u64 v[216:217], vcc, 0, v[176:177]
	s_mov_b32 m0, s38
	v_lshl_add_u64 v[224:225], vcc, 0, v[180:181]
	global_load_lds_dwordx4 v[216:217], off
	s_add_i32 m0, s38, 0x2000
	v_lshl_add_u64 v[226:227], s[86:87], 0, v[2:3]
	global_load_lds_dwordx4 v[224:225], off
	s_mov_b32 m0, s93
	v_lshl_add_u64 v[228:229], s[86:87], 0, v[178:179]
	global_load_lds_dwordx4 v[226:227], off
	s_mov_b32 m0, s94
	s_nop 0
	global_load_lds_dwordx4 v[228:229], off
	s_waitcnt vmcnt(8)
	s_waitcnt lgkmcnt(0)
	s_barrier
; #define PG8_STAGE(bufoff, gbase, voff) do { _Pragma("unroll") for (int _i = 0; _i < 2; ++_i) \
;         __builtin_amdgcn_global_load_lds((const unsigned*)((const char*)(gbase) + (voff)[_i]), (PG8_LAS unsigned*)(lds + (bufoff) + ldsw + _i * 8192), 16, 0, 0); } while (0)
; #define PG8_LDA(dst, b, h) do { _Pragma("unroll") for (int m = 0; m < 4; ++m) _Pragma("unroll") for (int k = 0; k < 2; ++k) dst[m][k] = *(const PG8_LAS bf16x8*)(lds + PG8_SA(b, h) + aoff + m * 2048 + k * 1024); } while (0)
; #define PG8_LDB(dst, b, h) do { _Pragma("unroll") for (int n = 0; n < 2; ++n) _Pragma("unroll") for (int k = 0; k < 2; ++k) dst[n][k] = *(const PG8_LAS bf16x8*)(lds + PG8_SB(b, h) + boff + n * 2048 + k * 1024); } while (0)
; #define PG8_MMA(ai, bj, At, Bt) do { __builtin_amdgcn_s_setprio(1); _Pragma("unroll") for (int m = 0; m < 4; ++m) _Pragma("unroll") for (int n = 0; n < 2; ++n) _Pragma("unroll") for (int k = 0; k < 2; ++k) \
;         acc[ai][bj][m][n] = __builtin_amdgcn_mfma_f32_16x16x32_bf16(Bt[n][k], At[m][k], acc[ai][bj][m][n], 0, 0, 0); __builtin_amdgcn_s_setprio(0); } while (0)
; #define PG8_WAIT_V(n) asm volatile("s_waitcnt vmcnt(" #n ")" ::: "memory")
; template <class Epi, class Sched, bool ALIGN_EPI = false, bool SP2 = false>
; __device__ __forceinline__ void gemm_phase(PG8_LAS unsigned char* lds, const Gemm g, const Sched& S, const Epi& E) {
;     ...
;             PG8_LDB(B0, 0, 0); PG8_LDB(B1, 0, 1); PG8_SCHED; PG8_LDA(At, 0, 0); PG8_STAGE(PG8_SA(1, 1), a1 + hstep, voffA);
;             PG8_WAIT_V(8); PG8_WAIT_L(0); PG8_BAR; PG8_MMA(0, 0, At, B0); PG8_MMA(0, 1, At, B1); PG8_BAR; PG8_SCHED;
;             PG8_LDA(At, 0, 1); PG8_STAGE(PG8_SB(0, 0), b2, voffB); PG8_STAGE(PG8_SB(0, 1), b2 + hstep, voffB); PG8_STAGE(PG8_SA(0, 0), a2, voffA);
;             PG8_WAIT_V(8); PG8_WAIT_L(0); PG8_BAR; PG8_MMA(1, 0, At, B0); PG8_MMA(1, 1, At, B1); PG8_BAR; PG8_SCHED;
;             PG8_LDB(B0, 1, 0); PG8_LDB(B1, 1, 1); PG8_SCHED; PG8_LDA(At, 1, 0); PG8_STAGE(PG8_SA(0, 1), a2 + hstep, voffA);
;             PG8_WAIT_V(8); PG8_WAIT_L(0); PG8_BAR; PG8_MMA(0, 0, At, B0); PG8_MMA(0, 1, At, B1); PG8_BAR; PG8_SCHED;
;             PG8_LDA(At, 1, 1); PG8_STAGE(PG8_SB(1, 0), b3, voffB); PG8_STAGE(PG8_SB(1, 1), b3 + hstep, voffB); PG8_STAGE(PG8_SA(1, 0), a3, voffA);
;             PG8_WAIT_V(8); PG8_WAIT_L(0); PG8_BAR; PG8_MMA(1, 0, At, B0); PG8_MMA(1, 1, At, B1); PG8_BAR; PG8_SCHED;
	s_setprio 1
	s_waitcnt lgkmcnt(0)
	v_mfma_f32_16x16x32_bf16 v[92:95], v[120:123], v[170:173], v[92:95]
	v_mfma_f32_16x16x32_bf16 v[84:87], v[120:123], v[192:195], v[84:87]
	v_mfma_f32_16x16x32_bf16 v[76:79], v[120:123], v[200:203], v[76:79]
	v_mfma_f32_16x16x32_bf16 v[108:111], v[120:123], v[242:245], v[108:111]
	v_mfma_f32_16x16x32_bf16 v[44:47], v[128:131], v[242:245], v[44:47]
	v_mfma_f32_16x16x32_bf16 v[12:15], v[128:131], v[200:203], v[12:15]
	v_mfma_f32_16x16x32_bf16 v[20:23], v[128:131], v[192:195], v[20:23]
	v_mfma_f32_16x16x32_bf16 v[28:31], v[128:131], v[170:173], v[28:31]
	v_mfma_f32_16x16x32_bf16 v[92:95], v[124:127], v[188:191], v[92:95]
	v_mfma_f32_16x16x32_bf16 v[84:87], v[124:127], v[196:199], v[84:87]
	v_mfma_f32_16x16x32_bf16 v[76:79], v[124:127], v[204:207], v[76:79]
	v_mfma_f32_16x16x32_bf16 v[108:111], v[124:127], v[246:249], v[108:111]
	v_mfma_f32_16x16x32_bf16 v[44:47], v[132:135], v[246:249], v[44:47]
	v_mfma_f32_16x16x32_bf16 v[12:15], v[132:135], v[204:207], v[12:15]
	v_mfma_f32_16x16x32_bf16 v[20:23], v[132:135], v[196:199], v[20:23]
	v_mfma_f32_16x16x32_bf16 v[28:31], v[132:135], v[188:191], v[28:31]
	s_setprio 0
	s_setprio 1
	v_mfma_f32_16x16x32_bf16 v[88:91], v[136:139], v[170:173], v[88:91]
	v_mfma_f32_16x16x32_bf16 v[80:83], v[136:139], v[192:195], v[80:83]
	v_mfma_f32_16x16x32_bf16 v[72:75], v[136:139], v[200:203], v[72:75]
	v_mfma_f32_16x16x32_bf16 v[104:107], v[136:139], v[242:245], v[104:107]
	v_mfma_f32_16x16x32_bf16 v[40:43], v[162:165], v[242:245], v[40:43]
	v_mfma_f32_16x16x32_bf16 v[8:11], v[162:165], v[200:203], v[8:11]
	v_mfma_f32_16x16x32_bf16 v[16:19], v[162:165], v[192:195], v[16:19]
	v_mfma_f32_16x16x32_bf16 v[24:27], v[162:165], v[170:173], v[24:27]
	v_mfma_f32_16x16x32_bf16 v[88:91], v[140:143], v[188:191], v[88:91]
	v_mfma_f32_16x16x32_bf16 v[80:83], v[140:143], v[196:199], v[80:83]
	v_mfma_f32_16x16x32_bf16 v[72:75], v[140:143], v[204:207], v[72:75]
	v_mfma_f32_16x16x32_bf16 v[104:107], v[140:143], v[246:249], v[104:107]
	v_mfma_f32_16x16x32_bf16 v[40:43], v[166:169], v[246:249], v[40:43]
	v_mfma_f32_16x16x32_bf16 v[8:11], v[166:169], v[204:207], v[8:11]
	v_mfma_f32_16x16x32_bf16 v[16:19], v[166:169], v[196:199], v[16:19]
	v_mfma_f32_16x16x32_bf16 v[24:27], v[166:169], v[188:191], v[24:27]
	s_setprio 0
	s_barrier
	v_add_u32_e32 v0, s91, v230
	s_add_i32 s38, 0, 0x1c000
	ds_read_b128 v[120:123], v0
	ds_read_b128 v[124:127], v0 offset:1024
	ds_read_b128 v[128:131], v0 offset:2048
	ds_read_b128 v[132:135], v0 offset:3072
	v_add_u32_e32 v0, s38, v230
	ds_read_b128 v[136:139], v0
	ds_read_b128 v[140:143], v0 offset:1024
	ds_read_b128 v[162:165], v0 offset:2048
	ds_read_b128 v[166:169], v0 offset:3072
	s_add_u32 s86, s86, s48
	s_addc_u32 s87, s87, s49
	s_mov_b32 m0, s95
	v_lshl_add_u64 v[148:149], s[86:87], 0, v[2:3]
	ds_read_b128 v[170:173], v238 offset:32768
	ds_read_b128 v[188:191], v238 offset:33792
	ds_read_b128 v[192:195], v238 offset:34816
	ds_read_b128 v[196:199], v238 offset:35840
	ds_read_b128 v[200:203], v238 offset:36864
	ds_read_b128 v[204:207], v238 offset:37888
	ds_read_b128 v[242:245], v238 offset:38912
	ds_read_b128 v[246:249], v238 offset:39936
	global_load_lds_dwordx4 v[148:149], off
	v_lshl_add_u64 v[148:149], s[86:87], 0, v[178:179]
	s_mov_b32 m0, s96
	s_nop 0
	global_load_lds_dwordx4 v[148:149], off
	s_waitcnt vmcnt(8)
	s_waitcnt lgkmcnt(0)
	s_barrier
	s_setprio 1
	s_waitcnt lgkmcnt(0)
	v_mfma_f32_16x16x32_bf16 v[158:161], v[120:123], v[170:173], v[158:161]
	v_mfma_f32_16x16x32_bf16 v[148:151], v[120:123], v[192:195], v[150:153]
	v_mfma_f32_16x16x32_bf16 v[100:103], v[120:123], v[200:203], v[100:103]
	v_mfma_f32_16x16x32_bf16 v[116:119], v[120:123], v[242:245], v[116:119]
	v_mfma_f32_16x16x32_bf16 v[68:71], v[128:131], v[242:245], v[68:71]
	v_mfma_f32_16x16x32_bf16 v[36:39], v[128:131], v[200:203], v[36:39]
	v_mfma_f32_16x16x32_bf16 v[52:55], v[128:131], v[192:195], v[52:55]
	v_mfma_f32_16x16x32_bf16 v[60:63], v[128:131], v[170:173], v[60:63]
	v_mfma_f32_16x16x32_bf16 v[158:161], v[124:127], v[188:191], v[158:161]
	v_mfma_f32_16x16x32_bf16 v[150:153], v[124:127], v[196:199], v[148:151]
	v_mfma_f32_16x16x32_bf16 v[100:103], v[124:127], v[204:207], v[100:103]
	v_mfma_f32_16x16x32_bf16 v[116:119], v[124:127], v[246:249], v[116:119]
	v_mfma_f32_16x16x32_bf16 v[68:71], v[132:135], v[246:249], v[68:71]
	v_mfma_f32_16x16x32_bf16 v[36:39], v[132:135], v[204:207], v[36:39]
	v_mfma_f32_16x16x32_bf16 v[52:55], v[132:135], v[196:199], v[52:55]
	v_mfma_f32_16x16x32_bf16 v[60:63], v[132:135], v[188:191], v[60:63]
	s_setprio 0
	s_setprio 1
	v_mfma_f32_16x16x32_bf16 v[154:157], v[136:139], v[170:173], v[154:157]
	v_mfma_f32_16x16x32_bf16 v[144:147], v[136:139], v[192:195], v[144:147]
	v_mfma_f32_16x16x32_bf16 v[96:99], v[136:139], v[200:203], v[96:99]
	v_mfma_f32_16x16x32_bf16 v[112:115], v[136:139], v[242:245], v[112:115]
	v_mfma_f32_16x16x32_bf16 v[64:67], v[162:165], v[242:245], v[64:67]
	v_mfma_f32_16x16x32_bf16 v[32:35], v[162:165], v[200:203], v[32:35]
	v_mfma_f32_16x16x32_bf16 v[48:51], v[162:165], v[192:195], v[48:51]
	v_mfma_f32_16x16x32_bf16 v[56:59], v[162:165], v[170:173], v[56:59]
	v_mfma_f32_16x16x32_bf16 v[154:157], v[140:143], v[188:191], v[154:157]
	v_mfma_f32_16x16x32_bf16 v[146:149], v[140:143], v[196:199], v[144:147]
	v_mfma_f32_16x16x32_bf16 v[96:99], v[140:143], v[204:207], v[96:99]
	v_mfma_f32_16x16x32_bf16 v[112:115], v[140:143], v[246:249], v[112:115]
	v_mfma_f32_16x16x32_bf16 v[64:67], v[166:169], v[246:249], v[64:67]
	v_mfma_f32_16x16x32_bf16 v[32:35], v[166:169], v[204:207], v[32:35]
	v_mfma_f32_16x16x32_bf16 v[48:51], v[166:169], v[196:199], v[48:51]
	v_mfma_f32_16x16x32_bf16 v[56:59], v[166:169], v[188:191], v[56:59]
	s_setprio 0
	s_barrier
; #define PG8_STAGE(bufoff, gbase, voff) do { _Pragma("unroll") for (int _i = 0; _i < 2; ++_i) \
;         __builtin_amdgcn_global_load_lds((const unsigned*)((const char*)(gbase) + (voff)[_i]), (PG8_LAS unsigned*)(lds + (bufoff) + ldsw + _i * 8192), 16, 0, 0); } while (0)
; #define PG8_LDA(dst, b, h) do { _Pragma("unroll") for (int m = 0; m < 4; ++m) _Pragma("unroll") for (int k = 0; k < 2; ++k) dst[m][k] = *(const PG8_LAS bf16x8*)(lds + PG8_SA(b, h) + aoff + m * 2048 + k * 1024); } while (0)
; #define PG8_WAIT_V(n) asm volatile("s_waitcnt vmcnt(" #n ")" ::: "memory")
; #define PG8_BAR __builtin_amdgcn_s_barrier()
; template <class Epi, class Sched, bool ALIGN_EPI = false, bool SP2 = false>
; __device__ __forceinline__ void gemm_phase(PG8_LAS unsigned char* lds, const Gemm g, const Sched& S, const Epi& E) {
;     ...
;         for (int t = 0; t < nt; t += 2) {
;             if constexpr (Epi::KHOOK) { if ((t & 7) == 0 && t != 0) E.khook(acc, t >> 3, wr, fr, lds); }
;             const bool last = (t == nt - 2);
;             const char* a1 = cA + (size_t)(t + 1) * kstep;
;             const char* a2 = last ? nA : cA + (size_t)(t + 2) * kstep; const char* b2 = last ? nB : cB + (size_t)(t + 2) * kstep;
;             const char* a3 = a2 + kstep; const char* b3 = b2 + kstep;
;             if (last && has_next) S.a_ready(nxt);
;             if constexpr (SP2) {
;             PG8_LDB(B0, 0, 0); PG8_LDB(B1, 0, 1); PG8_SCHED; PG8_LDA(At, 0, 0); PG8_STAGE(PG8_SA(1, 1), a1 + hstep, voffA);
;             PG8_WAIT_V(8); PG8_WAIT_L(0); PG8_BAR; PG8_MMA(0, 0, At, B0); PG8_MMA(0, 1, At, B1); PG8_BAR; PG8_SCHED;
;             PG8_LDA(At, 0, 1); PG8_STAGE(PG8_SB(0, 0), b2, voffB); PG8_STAGE(PG8_SB(0, 1), b2 + hstep, voffB); PG8_STAGE(PG8_SA(0, 0), a2, voffA);
;             PG8_WAIT_V(8); PG8_WAIT_L(0); PG8_BAR; PG8_MMA(1, 0, At, B0); PG8_MMA(1, 1, At, B1); PG8_BAR; PG8_SCHED;
;             PG8_LDB(B0, 1, 0); PG8_LDB(B1, 1, 1); PG8_SCHED; PG8_LDA(At, 1, 0); PG8_STAGE(PG8_SA(0, 1), a2 + hstep, voffA);
;             PG8_WAIT_V(8); PG8_WAIT_L(0); PG8_BAR; PG8_MMA(0, 0, At, B0); PG8_MMA(0, 1, At, B1); PG8_BAR; PG8_SCHED;
;             PG8_LDA(At, 1, 1); PG8_STAGE(PG8_SB(1, 0), b3, voffB); PG8_STAGE(PG8_SB(1, 1), b3 + hstep, voffB); PG8_STAGE(PG8_SA(1, 0), a3, voffA);
;             PG8_WAIT_V(8); PG8_WAIT_L(0); PG8_BAR; PG8_MMA(1, 0, At, B0); PG8_MMA(1, 1, At, B1); PG8_BAR; PG8_SCHED;
	s_add_i32 s39, s91, s92
	v_lshl_add_u64 v[144:145], v[174:175], 0, s[24:25]
	s_mov_b32 m0, s39
	ds_read_b128 v[170:173], v238 offset:49152
	ds_read_b128 v[188:191], v238 offset:50176
	ds_read_b128 v[192:195], v238 offset:51200
	ds_read_b128 v[196:199], v238 offset:52224
	ds_read_b128 v[200:203], v238 offset:53248
	ds_read_b128 v[204:207], v238 offset:54272
	ds_read_b128 v[242:245], v238 offset:55296
	ds_read_b128 v[246:249], v238 offset:56320
	global_load_lds_dwordx4 v[144:145], off
	v_lshl_add_u64 v[144:145], v[208:209], 0, s[24:25]
	s_add_i32 m0, s39, 0x2000
	s_add_i32 s38, s38, s92
	global_load_lds_dwordx4 v[144:145], off
	v_lshl_add_u64 v[144:145], v[216:217], 0, s[24:25]
	s_mov_b32 m0, s38
	s_nop 0
	global_load_lds_dwordx4 v[144:145], off
	v_lshl_add_u64 v[144:145], v[224:225], 0, s[24:25]
	s_add_i32 m0, s38, 0x2000
	s_nop 0
	global_load_lds_dwordx4 v[144:145], off
	v_lshl_add_u64 v[144:145], v[226:227], 0, s[24:25]
	s_mov_b32 m0, s10
	s_nop 0
	global_load_lds_dwordx4 v[144:145], off
	v_lshl_add_u64 v[144:145], v[228:229], 0, s[24:25]
	s_mov_b32 m0, s11
	s_nop 0
	global_load_lds_dwordx4 v[144:145], off
	s_waitcnt vmcnt(8)
	s_waitcnt lgkmcnt(0)
	s_barrier
	s_setprio 1
	s_waitcnt lgkmcnt(0)
	v_mfma_f32_16x16x32_bf16 v[92:95], v[120:123], v[170:173], v[92:95]
	v_mfma_f32_16x16x32_bf16 v[84:87], v[120:123], v[192:195], v[84:87]
	v_mfma_f32_16x16x32_bf16 v[76:79], v[120:123], v[200:203], v[76:79]
	v_mfma_f32_16x16x32_bf16 v[108:111], v[120:123], v[242:245], v[108:111]
	v_mfma_f32_16x16x32_bf16 v[44:47], v[128:131], v[242:245], v[44:47]
	v_mfma_f32_16x16x32_bf16 v[12:15], v[128:131], v[200:203], v[12:15]
	v_mfma_f32_16x16x32_bf16 v[20:23], v[128:131], v[192:195], v[20:23]
	v_mfma_f32_16x16x32_bf16 v[28:31], v[128:131], v[170:173], v[28:31]
	v_mfma_f32_16x16x32_bf16 v[92:95], v[124:127], v[188:191], v[92:95]
	v_mfma_f32_16x16x32_bf16 v[84:87], v[124:127], v[196:199], v[84:87]
	v_mfma_f32_16x16x32_bf16 v[76:79], v[124:127], v[204:207], v[76:79]
	v_mfma_f32_16x16x32_bf16 v[108:111], v[124:127], v[246:249], v[108:111]
	v_mfma_f32_16x16x32_bf16 v[44:47], v[132:135], v[246:249], v[44:47]
	v_mfma_f32_16x16x32_bf16 v[12:15], v[132:135], v[204:207], v[12:15]
	v_mfma_f32_16x16x32_bf16 v[20:23], v[132:135], v[196:199], v[20:23]
	v_mfma_f32_16x16x32_bf16 v[28:31], v[132:135], v[188:191], v[28:31]
	s_setprio 0
	s_setprio 1
	v_mfma_f32_16x16x32_bf16 v[88:91], v[136:139], v[170:173], v[88:91]
	v_mfma_f32_16x16x32_bf16 v[80:83], v[136:139], v[192:195], v[80:83]
	v_mfma_f32_16x16x32_bf16 v[72:75], v[136:139], v[200:203], v[72:75]
	v_mfma_f32_16x16x32_bf16 v[104:107], v[136:139], v[242:245], v[104:107]
	v_mfma_f32_16x16x32_bf16 v[40:43], v[162:165], v[242:245], v[40:43]
	v_mfma_f32_16x16x32_bf16 v[8:11], v[162:165], v[200:203], v[8:11]
	v_mfma_f32_16x16x32_bf16 v[16:19], v[162:165], v[192:195], v[16:19]
	v_mfma_f32_16x16x32_bf16 v[24:27], v[162:165], v[170:173], v[24:27]
	v_mfma_f32_16x16x32_bf16 v[88:91], v[140:143], v[188:191], v[88:91]
	v_mfma_f32_16x16x32_bf16 v[80:83], v[140:143], v[196:199], v[80:83]
	v_mfma_f32_16x16x32_bf16 v[72:75], v[140:143], v[204:207], v[72:75]
	v_mfma_f32_16x16x32_bf16 v[104:107], v[140:143], v[246:249], v[104:107]
	v_mfma_f32_16x16x32_bf16 v[40:43], v[166:169], v[246:249], v[40:43]
	v_mfma_f32_16x16x32_bf16 v[8:11], v[166:169], v[204:207], v[8:11]
	v_mfma_f32_16x16x32_bf16 v[16:19], v[166:169], v[196:199], v[16:19]
	v_mfma_f32_16x16x32_bf16 v[24:27], v[166:169], v[188:191], v[24:27]
	s_setprio 0
	s_barrier
	s_add_u32 s0, s0, 0x100
	s_addc_u32 s1, s1, 0
	s_add_u32 s72, s72, 0x100
	s_addc_u32 s73, s73, 0
	s_cmp_ge_u32 s88, s9
	s_mov_b32 s86, s88
	s_cbranch_scc0 .LBB0_365

; #define PG8_STAGE(bufoff, gbase, voff) do { _Pragma("unroll") for (int _i = 0; _i < 2; ++_i) \
;         __builtin_amdgcn_global_load_lds((const unsigned*)((const char*)(gbase) + (voff)[_i]), (PG8_LAS unsigned*)(lds + (bufoff) + ldsw + _i * 8192), 16, 0, 0); } while (0)
; #define PG8_LDA(dst, b, h) do { _Pragma("unroll") for (int m = 0; m < 4; ++m) _Pragma("unroll") for (int k = 0; k < 2; ++k) dst[m][k] = *(const PG8_LAS bf16x8*)(lds + PG8_SA(b, h) + aoff + m * 2048 + k * 1024); } while (0)
; #define PG8_LDB(dst, b, h) do { _Pragma("unroll") for (int n = 0; n < 2; ++n) _Pragma("unroll") for (int k = 0; k < 2; ++k) dst[n][k] = *(const PG8_LAS bf16x8*)(lds + PG8_SB(b, h) + boff + n * 2048 + k * 1024); } while (0)
; #define PG8_MMA(ai, bj, At, Bt) do { __builtin_amdgcn_s_setprio(1); _Pragma("unroll") for (int m = 0; m < 4; ++m) _Pragma("unroll") for (int n = 0; n < 2; ++n) _Pragma("unroll") for (int k = 0; k < 2; ++k) \
;         acc[ai][bj][m][n] = __builtin_amdgcn_mfma_f32_16x16x32_bf16(Bt[n][k], At[m][k], acc[ai][bj][m][n], 0, 0, 0); __builtin_amdgcn_s_setprio(0); } while (0)
; #define PG8_WAIT_V(n) asm volatile("s_waitcnt vmcnt(" #n ")" ::: "memory")
; template <class Epi, class Sched, bool ALIGN_EPI = false, bool SP2 = false>
; __device__ __forceinline__ void gemm_phase(PG8_LAS unsigned char* lds, const Gemm g, const Sched& S, const Epi& E) {
;     ...
;             PG8_LDB(B0, 0, 0); PG8_LDB(B1, 0, 1); PG8_SCHED; PG8_LDA(At, 0, 0); PG8_STAGE(PG8_SA(1, 1), a1 + hstep, voffA);
;             PG8_WAIT_V(8); PG8_WAIT_L(0); PG8_BAR; PG8_MMA(0, 0, At, B0); PG8_MMA(0, 1, At, B1); PG8_BAR; PG8_SCHED;
;             PG8_LDA(At, 0, 1); PG8_STAGE(PG8_SB(0, 0), b2, voffB); PG8_STAGE(PG8_SB(0, 1), b2 + hstep, voffB); PG8_STAGE(PG8_SA(0, 0), a2, voffA);
;             PG8_WAIT_V(8); PG8_WAIT_L(0); PG8_BAR; PG8_MMA(1, 0, At, B0); PG8_MMA(1, 1, At, B1); PG8_BAR; PG8_SCHED;
;             PG8_LDB(B0, 1, 0); PG8_LDB(B1, 1, 1); PG8_SCHED; PG8_LDA(At, 1, 0); PG8_STAGE(PG8_SA(0, 1), a2 + hstep, voffA);
;             PG8_WAIT_V(8); PG8_WAIT_L(0); PG8_BAR; PG8_MMA(0, 0, At, B0); PG8_MMA(0, 1, At, B1); PG8_BAR; PG8_SCHED;
;             PG8_LDA(At, 1, 1); PG8_STAGE(PG8_SB(1, 0), b3, voffB); PG8_STAGE(PG8_SB(1, 1), b3 + hstep, voffB); PG8_STAGE(PG8_SA(1, 0), a3, voffA);
;             PG8_WAIT_V(8); PG8_WAIT_L(0); PG8_BAR; PG8_MMA(1, 0, At, B0); PG8_MMA(1, 1, At, B1); PG8_BAR; PG8_SCHED;
.LBB0_468:
	s_add_i32 s78, s38, 2
	s_add_u32 s79, s0, 0x80
	s_addc_u32 s39, s1, 0
	s_cmp_eq_u32 s33, s38
	s_cselect_b32 s39, s7, s39
	s_cselect_b32 s38, s6, s79
	s_cselect_b32 s81, s23, s41
	s_cselect_b32 s80, s22, s40
	s_add_i32 s79, 0, 0x14000
	v_add_u32_e32 v148, s19, v162
	v_add_u32_e32 v171, s79, v162
	ds_read_b128 v[136:139], v148
	ds_read_b128 v[140:143], v148 offset:1024
	ds_read_b128 v[144:147], v148 offset:2048
	ds_read_b128 v[148:151], v148 offset:3072
	ds_read_b128 v[172:175], v171
	ds_read_b128 v[176:179], v171 offset:1024
	ds_read_b128 v[184:187], v171 offset:2048
	ds_read_b128 v[188:191], v171 offset:3072
	v_lshl_add_u64 v[180:181], s[0:1], 0, v[158:159]
	s_add_i32 m0, s46, 0xc000
	ds_read_b128 v[192:195], v167
	ds_read_b128 v[196:199], v167 offset:1024
	ds_read_b128 v[200:203], v167 offset:2048
	ds_read_b128 v[204:207], v167 offset:3072
	ds_read_b128 v[230:233], v167 offset:4096
	ds_read_b128 v[234:237], v167 offset:5120
	ds_read_b128 v[238:241], v167 offset:6144
	ds_read_b128 v[242:245], v167 offset:7168
	global_load_lds_dwordx4 v[180:181], off
	v_lshl_add_u64 v[180:181], s[0:1], 0, v[160:161]
	s_add_i32 m0, s46, 0xe000
	s_nop 0
	global_load_lds_dwordx4 v[180:181], off
	s_waitcnt vmcnt(8)
	s_waitcnt lgkmcnt(0)
	s_barrier
	s_setprio 1
	s_waitcnt lgkmcnt(0)
	v_mfma_f32_16x16x32_bf16 v[132:135], v[136:139], v[192:195], v[132:135]
	v_mfma_f32_16x16x32_bf16 v[116:119], v[136:139], v[200:203], v[116:119]
	v_mfma_f32_16x16x32_bf16 v[100:103], v[136:139], v[230:233], v[100:103]
	v_mfma_f32_16x16x32_bf16 v[84:87], v[136:139], v[238:241], v[84:87]
	v_mfma_f32_16x16x32_bf16 v[80:83], v[144:147], v[238:241], v[80:83]
	v_mfma_f32_16x16x32_bf16 v[96:99], v[144:147], v[230:233], v[96:99]
	v_mfma_f32_16x16x32_bf16 v[112:115], v[144:147], v[200:203], v[112:115]
	v_mfma_f32_16x16x32_bf16 v[128:131], v[144:147], v[192:195], v[128:131]
	v_mfma_f32_16x16x32_bf16 v[132:135], v[140:143], v[196:199], v[132:135]
	v_mfma_f32_16x16x32_bf16 v[116:119], v[140:143], v[204:207], v[116:119]
	v_mfma_f32_16x16x32_bf16 v[100:103], v[140:143], v[234:237], v[100:103]
	v_mfma_f32_16x16x32_bf16 v[84:87], v[140:143], v[242:245], v[84:87]
	v_mfma_f32_16x16x32_bf16 v[80:83], v[148:151], v[242:245], v[80:83]
	v_mfma_f32_16x16x32_bf16 v[96:99], v[148:151], v[234:237], v[96:99]
	v_mfma_f32_16x16x32_bf16 v[112:115], v[148:151], v[204:207], v[112:115]
	v_mfma_f32_16x16x32_bf16 v[128:131], v[148:151], v[196:199], v[128:131]
	s_setprio 0
	s_setprio 1
	v_mfma_f32_16x16x32_bf16 v[124:127], v[172:175], v[192:195], v[124:127]
	v_mfma_f32_16x16x32_bf16 v[108:111], v[172:175], v[200:203], v[108:111]
	v_mfma_f32_16x16x32_bf16 v[92:95], v[172:175], v[230:233], v[92:95]
	v_mfma_f32_16x16x32_bf16 v[76:79], v[172:175], v[238:241], v[76:79]
	v_mfma_f32_16x16x32_bf16 v[72:75], v[184:187], v[238:241], v[72:75]
	v_mfma_f32_16x16x32_bf16 v[88:91], v[184:187], v[230:233], v[88:91]
	v_mfma_f32_16x16x32_bf16 v[104:107], v[184:187], v[200:203], v[104:107]
	v_mfma_f32_16x16x32_bf16 v[120:123], v[184:187], v[192:195], v[120:123]
	v_mfma_f32_16x16x32_bf16 v[124:127], v[176:179], v[196:199], v[124:127]
	v_mfma_f32_16x16x32_bf16 v[108:111], v[176:179], v[204:207], v[108:111]
	v_mfma_f32_16x16x32_bf16 v[92:95], v[176:179], v[234:237], v[92:95]
	v_mfma_f32_16x16x32_bf16 v[76:79], v[176:179], v[242:245], v[76:79]
	v_mfma_f32_16x16x32_bf16 v[72:75], v[188:191], v[242:245], v[72:75]
	v_mfma_f32_16x16x32_bf16 v[88:91], v[188:191], v[234:237], v[88:91]
	v_mfma_f32_16x16x32_bf16 v[104:107], v[188:191], v[204:207], v[104:107]
	v_mfma_f32_16x16x32_bf16 v[120:123], v[188:191], v[196:199], v[120:123]
	s_setprio 0
	s_barrier
	s_add_i32 s82, s19, s42
	v_lshl_add_u64 v[180:181], s[80:81], 0, v[154:155]
	s_mov_b32 m0, s82
	ds_read_b128 v[192:195], v167 offset:16384
	ds_read_b128 v[196:199], v167 offset:17408
	ds_read_b128 v[200:203], v167 offset:18432
	ds_read_b128 v[204:207], v167 offset:19456
	ds_read_b128 v[230:233], v167 offset:20480
	ds_read_b128 v[234:237], v167 offset:21504
	ds_read_b128 v[238:241], v167 offset:22528
	ds_read_b128 v[242:245], v167 offset:23552
	global_load_lds_dwordx4 v[180:181], off
	s_add_i32 m0, s82, 0x2000
	v_lshl_add_u64 v[208:209], s[80:81], 0, v[2:3]
	s_add_u32 s80, s80, s48
	s_addc_u32 s81, s81, s49
	s_add_i32 s79, s79, s42
	global_load_lds_dwordx4 v[208:209], off
	v_lshl_add_u64 v[216:217], s[80:81], 0, v[154:155]
	s_mov_b32 m0, s79
	v_lshl_add_u64 v[224:225], s[80:81], 0, v[2:3]
	global_load_lds_dwordx4 v[216:217], off
	s_add_i32 m0, s79, 0x2000
	v_lshl_add_u64 v[226:227], s[38:39], 0, v[156:157]
	global_load_lds_dwordx4 v[224:225], off
	s_mov_b32 m0, s46
	v_lshl_add_u64 v[246:247], s[38:39], 0, v[152:153]
	global_load_lds_dwordx4 v[226:227], off
	s_mov_b32 m0, s47
	s_nop 0
	global_load_lds_dwordx4 v[246:247], off
	s_waitcnt vmcnt(8)
	s_waitcnt lgkmcnt(0)
	s_barrier
; #define PG8_STAGE(bufoff, gbase, voff) do { _Pragma("unroll") for (int _i = 0; _i < 2; ++_i) \
;         __builtin_amdgcn_global_load_lds((const unsigned*)((const char*)(gbase) + (voff)[_i]), (PG8_LAS unsigned*)(lds + (bufoff) + ldsw + _i * 8192), 16, 0, 0); } while (0)
; #define PG8_LDA(dst, b, h) do { _Pragma("unroll") for (int m = 0; m < 4; ++m) _Pragma("unroll") for (int k = 0; k < 2; ++k) dst[m][k] = *(const PG8_LAS bf16x8*)(lds + PG8_SA(b, h) + aoff + m * 2048 + k * 1024); } while (0)
; #define PG8_LDB(dst, b, h) do { _Pragma("unroll") for (int n = 0; n < 2; ++n) _Pragma("unroll") for (int k = 0; k < 2; ++k) dst[n][k] = *(const PG8_LAS bf16x8*)(lds + PG8_SB(b, h) + boff + n * 2048 + k * 1024); } while (0)
; #define PG8_MMA(ai, bj, At, Bt) do { __builtin_amdgcn_s_setprio(1); _Pragma("unroll") for (int m = 0; m < 4; ++m) _Pragma("unroll") for (int n = 0; n < 2; ++n) _Pragma("unroll") for (int k = 0; k < 2; ++k) \
;         acc[ai][bj][m][n] = __builtin_amdgcn_mfma_f32_16x16x32_bf16(Bt[n][k], At[m][k], acc[ai][bj][m][n], 0, 0, 0); __builtin_amdgcn_s_setprio(0); } while (0)
; #define PG8_WAIT_V(n) asm volatile("s_waitcnt vmcnt(" #n ")" ::: "memory")
; template <class Epi, class Sched, bool ALIGN_EPI = false, bool SP2 = false>
; __device__ __forceinline__ void gemm_phase(PG8_LAS unsigned char* lds, const Gemm g, const Sched& S, const Epi& E) {
;     ...
;             PG8_LDB(B0, 0, 0); PG8_LDB(B1, 0, 1); PG8_SCHED; PG8_LDA(At, 0, 0); PG8_STAGE(PG8_SA(1, 1), a1 + hstep, voffA);
;             PG8_WAIT_V(8); PG8_WAIT_L(0); PG8_BAR; PG8_MMA(0, 0, At, B0); PG8_MMA(0, 1, At, B1); PG8_BAR; PG8_SCHED;
;             PG8_LDA(At, 0, 1); PG8_STAGE(PG8_SB(0, 0), b2, voffB); PG8_STAGE(PG8_SB(0, 1), b2 + hstep, voffB); PG8_STAGE(PG8_SA(0, 0), a2, voffA);
;             PG8_WAIT_V(8); PG8_WAIT_L(0); PG8_BAR; PG8_MMA(1, 0, At, B0); PG8_MMA(1, 1, At, B1); PG8_BAR; PG8_SCHED;
;             PG8_LDB(B0, 1, 0); PG8_LDB(B1, 1, 1); PG8_SCHED; PG8_LDA(At, 1, 0); PG8_STAGE(PG8_SA(0, 1), a2 + hstep, voffA);
;             PG8_WAIT_V(8); PG8_WAIT_L(0); PG8_BAR; PG8_MMA(0, 0, At, B0); PG8_MMA(0, 1, At, B1); PG8_BAR; PG8_SCHED;
;             PG8_LDA(At, 1, 1); PG8_STAGE(PG8_SB(1, 0), b3, voffB); PG8_STAGE(PG8_SB(1, 1), b3 + hstep, voffB); PG8_STAGE(PG8_SA(1, 0), a3, voffA);
;             PG8_WAIT_V(8); PG8_WAIT_L(0); PG8_BAR; PG8_MMA(1, 0, At, B0); PG8_MMA(1, 1, At, B1); PG8_BAR; PG8_SCHED;
	s_setprio 1
	s_waitcnt lgkmcnt(0)
	v_mfma_f32_16x16x32_bf16 v[68:71], v[136:139], v[192:195], v[68:71]
	v_mfma_f32_16x16x32_bf16 v[52:55], v[136:139], v[200:203], v[52:55]
	v_mfma_f32_16x16x32_bf16 v[36:39], v[136:139], v[230:233], v[36:39]
	v_mfma_f32_16x16x32_bf16 v[20:23], v[136:139], v[238:241], v[20:23]
	v_mfma_f32_16x16x32_bf16 v[16:19], v[144:147], v[238:241], v[16:19]
	v_mfma_f32_16x16x32_bf16 v[32:35], v[144:147], v[230:233], v[32:35]
	v_mfma_f32_16x16x32_bf16 v[48:51], v[144:147], v[200:203], v[48:51]
	v_mfma_f32_16x16x32_bf16 v[64:67], v[144:147], v[192:195], v[64:67]
	v_mfma_f32_16x16x32_bf16 v[68:71], v[140:143], v[196:199], v[68:71]
	v_mfma_f32_16x16x32_bf16 v[52:55], v[140:143], v[204:207], v[52:55]
	v_mfma_f32_16x16x32_bf16 v[36:39], v[140:143], v[234:237], v[36:39]
	v_mfma_f32_16x16x32_bf16 v[20:23], v[140:143], v[242:245], v[20:23]
	v_mfma_f32_16x16x32_bf16 v[16:19], v[148:151], v[242:245], v[16:19]
	v_mfma_f32_16x16x32_bf16 v[32:35], v[148:151], v[234:237], v[32:35]
	v_mfma_f32_16x16x32_bf16 v[48:51], v[148:151], v[204:207], v[48:51]
	v_mfma_f32_16x16x32_bf16 v[64:67], v[148:151], v[196:199], v[64:67]
	s_setprio 0
	s_setprio 1
	v_mfma_f32_16x16x32_bf16 v[60:63], v[172:175], v[192:195], v[60:63]
	v_mfma_f32_16x16x32_bf16 v[44:47], v[172:175], v[200:203], v[44:47]
	v_mfma_f32_16x16x32_bf16 v[28:31], v[172:175], v[230:233], v[28:31]
	v_mfma_f32_16x16x32_bf16 v[12:15], v[172:175], v[238:241], v[12:15]
	v_mfma_f32_16x16x32_bf16 v[8:11], v[184:187], v[238:241], v[8:11]
	v_mfma_f32_16x16x32_bf16 v[24:27], v[184:187], v[230:233], v[24:27]
	v_mfma_f32_16x16x32_bf16 v[40:43], v[184:187], v[200:203], v[40:43]
	v_mfma_f32_16x16x32_bf16 v[56:59], v[184:187], v[192:195], v[56:59]
	v_mfma_f32_16x16x32_bf16 v[60:63], v[176:179], v[196:199], v[60:63]
	v_mfma_f32_16x16x32_bf16 v[44:47], v[176:179], v[204:207], v[44:47]
	v_mfma_f32_16x16x32_bf16 v[28:31], v[176:179], v[234:237], v[28:31]
	v_mfma_f32_16x16x32_bf16 v[12:15], v[176:179], v[242:245], v[12:15]
	v_mfma_f32_16x16x32_bf16 v[8:11], v[188:191], v[242:245], v[8:11]
	v_mfma_f32_16x16x32_bf16 v[24:27], v[188:191], v[234:237], v[24:27]
	v_mfma_f32_16x16x32_bf16 v[40:43], v[188:191], v[204:207], v[40:43]
	v_mfma_f32_16x16x32_bf16 v[56:59], v[188:191], v[196:199], v[56:59]
	s_setprio 0
	s_barrier
	s_add_i32 s79, 0, 0x1c000
	v_add_u32_e32 v148, s91, v162
	v_add_u32_e32 v171, s79, v162
	ds_read_b128 v[136:139], v148
	ds_read_b128 v[140:143], v148 offset:1024
	ds_read_b128 v[144:147], v148 offset:2048
	ds_read_b128 v[148:151], v148 offset:3072
	ds_read_b128 v[172:175], v171
	ds_read_b128 v[176:179], v171 offset:1024
	ds_read_b128 v[184:187], v171 offset:2048
	ds_read_b128 v[188:191], v171 offset:3072
	s_add_u32 s38, s38, s48
	s_addc_u32 s39, s39, s49
	s_mov_b32 m0, s52
	v_lshl_add_u64 v[248:249], s[38:39], 0, v[156:157]
	ds_read_b128 v[192:195], v167 offset:32768
	ds_read_b128 v[196:199], v167 offset:33792
	ds_read_b128 v[200:203], v167 offset:34816
	ds_read_b128 v[204:207], v167 offset:35840
	ds_read_b128 v[230:233], v167 offset:36864
	ds_read_b128 v[234:237], v167 offset:37888
	ds_read_b128 v[238:241], v167 offset:38912
	ds_read_b128 v[242:245], v167 offset:39936
	global_load_lds_dwordx4 v[248:249], off
	v_lshl_add_u64 v[248:249], s[38:39], 0, v[152:153]
	s_mov_b32 m0, s53
	s_nop 0
	global_load_lds_dwordx4 v[248:249], off
	s_waitcnt vmcnt(8)
	s_waitcnt lgkmcnt(0)
	s_barrier
	s_setprio 1
	s_waitcnt lgkmcnt(0)
	v_mfma_f32_16x16x32_bf16 v[132:135], v[136:139], v[192:195], v[132:135]
	v_mfma_f32_16x16x32_bf16 v[116:119], v[136:139], v[200:203], v[116:119]
	v_mfma_f32_16x16x32_bf16 v[100:103], v[136:139], v[230:233], v[100:103]
	v_mfma_f32_16x16x32_bf16 v[84:87], v[136:139], v[238:241], v[84:87]
	v_mfma_f32_16x16x32_bf16 v[80:83], v[144:147], v[238:241], v[80:83]
	v_mfma_f32_16x16x32_bf16 v[96:99], v[144:147], v[230:233], v[96:99]
	v_mfma_f32_16x16x32_bf16 v[112:115], v[144:147], v[200:203], v[112:115]
	v_mfma_f32_16x16x32_bf16 v[128:131], v[144:147], v[192:195], v[128:131]
	v_mfma_f32_16x16x32_bf16 v[132:135], v[140:143], v[196:199], v[132:135]
	v_mfma_f32_16x16x32_bf16 v[116:119], v[140:143], v[204:207], v[116:119]
	v_mfma_f32_16x16x32_bf16 v[100:103], v[140:143], v[234:237], v[100:103]
	v_mfma_f32_16x16x32_bf16 v[84:87], v[140:143], v[242:245], v[84:87]
	v_mfma_f32_16x16x32_bf16 v[80:83], v[148:151], v[242:245], v[80:83]
	v_mfma_f32_16x16x32_bf16 v[96:99], v[148:151], v[234:237], v[96:99]
	v_mfma_f32_16x16x32_bf16 v[112:115], v[148:151], v[204:207], v[112:115]
	v_mfma_f32_16x16x32_bf16 v[128:131], v[148:151], v[196:199], v[128:131]
	s_setprio 0
	s_setprio 1
	v_mfma_f32_16x16x32_bf16 v[124:127], v[172:175], v[192:195], v[124:127]
	v_mfma_f32_16x16x32_bf16 v[108:111], v[172:175], v[200:203], v[108:111]
	v_mfma_f32_16x16x32_bf16 v[92:95], v[172:175], v[230:233], v[92:95]
	v_mfma_f32_16x16x32_bf16 v[76:79], v[172:175], v[238:241], v[76:79]
	v_mfma_f32_16x16x32_bf16 v[72:75], v[184:187], v[238:241], v[72:75]
	v_mfma_f32_16x16x32_bf16 v[88:91], v[184:187], v[230:233], v[88:91]
	v_mfma_f32_16x16x32_bf16 v[104:107], v[184:187], v[200:203], v[104:107]
	v_mfma_f32_16x16x32_bf16 v[120:123], v[184:187], v[192:195], v[120:123]
	v_mfma_f32_16x16x32_bf16 v[124:127], v[176:179], v[196:199], v[124:127]
	v_mfma_f32_16x16x32_bf16 v[108:111], v[176:179], v[204:207], v[108:111]
	v_mfma_f32_16x16x32_bf16 v[92:95], v[176:179], v[234:237], v[92:95]
	v_mfma_f32_16x16x32_bf16 v[76:79], v[176:179], v[242:245], v[76:79]
	v_mfma_f32_16x16x32_bf16 v[72:75], v[188:191], v[242:245], v[72:75]
	v_mfma_f32_16x16x32_bf16 v[88:91], v[188:191], v[234:237], v[88:91]
	v_mfma_f32_16x16x32_bf16 v[104:107], v[188:191], v[204:207], v[104:107]
	v_mfma_f32_16x16x32_bf16 v[120:123], v[188:191], v[196:199], v[120:123]
	s_setprio 0
	s_barrier
; #define PG8_STAGE(bufoff, gbase, voff) do { _Pragma("unroll") for (int _i = 0; _i < 2; ++_i) \
;         __builtin_amdgcn_global_load_lds((const unsigned*)((const char*)(gbase) + (voff)[_i]), (PG8_LAS unsigned*)(lds + (bufoff) + ldsw + _i * 8192), 16, 0, 0); } while (0)
; #define PG8_LDA(dst, b, h) do { _Pragma("unroll") for (int m = 0; m < 4; ++m) _Pragma("unroll") for (int k = 0; k < 2; ++k) dst[m][k] = *(const PG8_LAS bf16x8*)(lds + PG8_SA(b, h) + aoff + m * 2048 + k * 1024); } while (0)
; #define PG8_WAIT_V(n) asm volatile("s_waitcnt vmcnt(" #n ")" ::: "memory")
; #define PG8_BAR __builtin_amdgcn_s_barrier()
; template <class Epi, class Sched, bool ALIGN_EPI = false, bool SP2 = false>
; __device__ __forceinline__ void gemm_phase(PG8_LAS unsigned char* lds, const Gemm g, const Sched& S, const Epi& E) {
;     ...
;         for (int t = 0; t < nt; t += 2) {
;             if constexpr (Epi::KHOOK) { if ((t & 7) == 0 && t != 0) E.khook(acc, t >> 3, wr, fr, lds); }
;             const bool last = (t == nt - 2);
;             const char* a1 = cA + (size_t)(t + 1) * kstep;
;             const char* a2 = last ? nA : cA + (size_t)(t + 2) * kstep; const char* b2 = last ? nB : cB + (size_t)(t + 2) * kstep;
;             const char* a3 = a2 + kstep; const char* b3 = b2 + kstep;
;             if (last && has_next) S.a_ready(nxt);
;             if constexpr (SP2) {
;             PG8_LDB(B0, 0, 0); PG8_LDB(B1, 0, 1); PG8_SCHED; PG8_LDA(At, 0, 0); PG8_STAGE(PG8_SA(1, 1), a1 + hstep, voffA);
;             PG8_WAIT_V(8); PG8_WAIT_L(0); PG8_BAR; PG8_MMA(0, 0, At, B0); PG8_MMA(0, 1, At, B1); PG8_BAR; PG8_SCHED;
;             PG8_LDA(At, 0, 1); PG8_STAGE(PG8_SB(0, 0), b2, voffB); PG8_STAGE(PG8_SB(0, 1), b2 + hstep, voffB); PG8_STAGE(PG8_SA(0, 0), a2, voffA);
;             PG8_WAIT_V(8); PG8_WAIT_L(0); PG8_BAR; PG8_MMA(1, 0, At, B0); PG8_MMA(1, 1, At, B1); PG8_BAR; PG8_SCHED;
;             PG8_LDB(B0, 1, 0); PG8_LDB(B1, 1, 1); PG8_SCHED; PG8_LDA(At, 1, 0); PG8_STAGE(PG8_SA(0, 1), a2 + hstep, voffA);
;             PG8_WAIT_V(8); PG8_WAIT_L(0); PG8_BAR; PG8_MMA(0, 0, At, B0); PG8_MMA(0, 1, At, B1); PG8_BAR; PG8_SCHED;
;             PG8_LDA(At, 1, 1); PG8_STAGE(PG8_SB(1, 0), b3, voffB); PG8_STAGE(PG8_SB(1, 1), b3 + hstep, voffB); PG8_STAGE(PG8_SA(1, 0), a3, voffA);
;             PG8_WAIT_V(8); PG8_WAIT_L(0); PG8_BAR; PG8_MMA(1, 0, At, B0); PG8_MMA(1, 1, At, B1); PG8_BAR; PG8_SCHED;
	s_add_i32 s38, s91, s42
	v_lshl_add_u64 v[180:181], v[180:181], 0, s[24:25]
	s_mov_b32 m0, s38
	ds_read_b128 v[192:195], v167 offset:49152
	ds_read_b128 v[196:199], v167 offset:50176
	ds_read_b128 v[200:203], v167 offset:51200
	ds_read_b128 v[204:207], v167 offset:52224
	ds_read_b128 v[230:233], v167 offset:53248
	ds_read_b128 v[234:237], v167 offset:54272
	ds_read_b128 v[238:241], v167 offset:55296
	ds_read_b128 v[242:245], v167 offset:56320
	global_load_lds_dwordx4 v[180:181], off
	v_lshl_add_u64 v[180:181], v[208:209], 0, s[24:25]
	s_add_i32 m0, s38, 0x2000
	s_add_i32 s38, s79, s42
	global_load_lds_dwordx4 v[180:181], off
	v_lshl_add_u64 v[180:181], v[216:217], 0, s[24:25]
	s_mov_b32 m0, s38
	s_nop 0
	global_load_lds_dwordx4 v[180:181], off
	v_lshl_add_u64 v[180:181], v[224:225], 0, s[24:25]
	s_add_i32 m0, s38, 0x2000
	s_nop 0
	global_load_lds_dwordx4 v[180:181], off
	v_lshl_add_u64 v[180:181], v[226:227], 0, s[24:25]
	s_mov_b32 m0, s72
	s_nop 0
	global_load_lds_dwordx4 v[180:181], off
	v_lshl_add_u64 v[180:181], v[246:247], 0, s[24:25]
	s_mov_b32 m0, s73
	s_nop 0
	global_load_lds_dwordx4 v[180:181], off
	s_waitcnt vmcnt(8)
	s_waitcnt lgkmcnt(0)
	s_barrier
	s_setprio 1
	s_waitcnt lgkmcnt(0)
	v_mfma_f32_16x16x32_bf16 v[68:71], v[136:139], v[192:195], v[68:71]
	v_mfma_f32_16x16x32_bf16 v[52:55], v[136:139], v[200:203], v[52:55]
	v_mfma_f32_16x16x32_bf16 v[36:39], v[136:139], v[230:233], v[36:39]
	v_mfma_f32_16x16x32_bf16 v[20:23], v[136:139], v[238:241], v[20:23]
	v_mfma_f32_16x16x32_bf16 v[16:19], v[144:147], v[238:241], v[16:19]
	v_mfma_f32_16x16x32_bf16 v[32:35], v[144:147], v[230:233], v[32:35]
	v_mfma_f32_16x16x32_bf16 v[48:51], v[144:147], v[200:203], v[48:51]
	v_mfma_f32_16x16x32_bf16 v[64:67], v[144:147], v[192:195], v[64:67]
	v_mfma_f32_16x16x32_bf16 v[68:71], v[140:143], v[196:199], v[68:71]
	v_mfma_f32_16x16x32_bf16 v[52:55], v[140:143], v[204:207], v[52:55]
	v_mfma_f32_16x16x32_bf16 v[36:39], v[140:143], v[234:237], v[36:39]
	v_mfma_f32_16x16x32_bf16 v[20:23], v[140:143], v[242:245], v[20:23]
	v_mfma_f32_16x16x32_bf16 v[16:19], v[148:151], v[242:245], v[16:19]
	v_mfma_f32_16x16x32_bf16 v[32:35], v[148:151], v[234:237], v[32:35]
	v_mfma_f32_16x16x32_bf16 v[48:51], v[148:151], v[204:207], v[48:51]
	v_mfma_f32_16x16x32_bf16 v[64:67], v[148:151], v[196:199], v[64:67]
	s_setprio 0
	s_setprio 1
	v_mfma_f32_16x16x32_bf16 v[60:63], v[172:175], v[192:195], v[60:63]
	v_mfma_f32_16x16x32_bf16 v[44:47], v[172:175], v[200:203], v[44:47]
	v_mfma_f32_16x16x32_bf16 v[28:31], v[172:175], v[230:233], v[28:31]
	v_mfma_f32_16x16x32_bf16 v[12:15], v[172:175], v[238:241], v[12:15]
	v_mfma_f32_16x16x32_bf16 v[8:11], v[184:187], v[238:241], v[8:11]
	v_mfma_f32_16x16x32_bf16 v[24:27], v[184:187], v[230:233], v[24:27]
	v_mfma_f32_16x16x32_bf16 v[40:43], v[184:187], v[200:203], v[40:43]
	v_mfma_f32_16x16x32_bf16 v[56:59], v[184:187], v[192:195], v[56:59]
	v_mfma_f32_16x16x32_bf16 v[60:63], v[176:179], v[196:199], v[60:63]
	v_mfma_f32_16x16x32_bf16 v[44:47], v[176:179], v[204:207], v[44:47]
	v_mfma_f32_16x16x32_bf16 v[28:31], v[176:179], v[234:237], v[28:31]
	v_mfma_f32_16x16x32_bf16 v[12:15], v[176:179], v[242:245], v[12:15]
	v_mfma_f32_16x16x32_bf16 v[8:11], v[188:191], v[242:245], v[8:11]
	v_mfma_f32_16x16x32_bf16 v[24:27], v[188:191], v[234:237], v[24:27]
	v_mfma_f32_16x16x32_bf16 v[40:43], v[188:191], v[204:207], v[40:43]
	v_mfma_f32_16x16x32_bf16 v[56:59], v[188:191], v[196:199], v[56:59]
	s_setprio 0
	s_barrier
	s_add_u32 s0, s0, 0x100
	s_addc_u32 s1, s1, 0
	s_add_u32 s40, s40, 0x100
	s_addc_u32 s41, s41, 0
	s_cmp_ge_u32 s78, s9
	s_mov_b32 s38, s78
	s_cbranch_scc0 .LBB0_468

; #define PG8_STAGE(bufoff, gbase, voff) do { _Pragma("unroll") for (int _i = 0; _i < 2; ++_i) \
;         __builtin_amdgcn_global_load_lds((const unsigned*)((const char*)(gbase) + (voff)[_i]), (PG8_LAS unsigned*)(lds + (bufoff) + ldsw + _i * 8192), 16, 0, 0); } while (0)
; #define PG8_LDA(dst, b, h) do { _Pragma("unroll") for (int m = 0; m < 4; ++m) _Pragma("unroll") for (int k = 0; k < 2; ++k) dst[m][k] = *(const PG8_LAS bf16x8*)(lds + PG8_SA(b, h) + aoff + m * 2048 + k * 1024); } while (0)
; #define PG8_LDB(dst, b, h) do { _Pragma("unroll") for (int n = 0; n < 2; ++n) _Pragma("unroll") for (int k = 0; k < 2; ++k) dst[n][k] = *(const PG8_LAS bf16x8*)(lds + PG8_SB(b, h) + boff + n * 2048 + k * 1024); } while (0)
; #define PG8_MMA(ai, bj, At, Bt) do { __builtin_amdgcn_s_setprio(1); _Pragma("unroll") for (int m = 0; m < 4; ++m) _Pragma("unroll") for (int n = 0; n < 2; ++n) _Pragma("unroll") for (int k = 0; k < 2; ++k) \
;         acc[ai][bj][m][n] = __builtin_amdgcn_mfma_f32_16x16x32_bf16(Bt[n][k], At[m][k], acc[ai][bj][m][n], 0, 0, 0); __builtin_amdgcn_s_setprio(0); } while (0)
; #define PG8_WAIT_V(n) asm volatile("s_waitcnt vmcnt(" #n ")" ::: "memory")
; template <class Epi, class Sched, bool ALIGN_EPI = false, bool SP2 = false>
; __device__ __forceinline__ void gemm_phase(PG8_LAS unsigned char* lds, const Gemm g, const Sched& S, const Epi& E) {
;     ...
;             PG8_LDB(B0, 0, 0); PG8_LDB(B1, 0, 1); PG8_SCHED; PG8_LDA(At, 0, 0); PG8_STAGE(PG8_SA(1, 1), a1 + hstep, voffA);
;             PG8_WAIT_V(8); PG8_WAIT_L(0); PG8_BAR; PG8_MMA(0, 0, At, B0); PG8_MMA(0, 1, At, B1); PG8_BAR; PG8_SCHED;
;             PG8_LDA(At, 0, 1); PG8_STAGE(PG8_SB(0, 0), b2, voffB); PG8_STAGE(PG8_SB(0, 1), b2 + hstep, voffB); PG8_STAGE(PG8_SA(0, 0), a2, voffA);
;             PG8_WAIT_V(8); PG8_WAIT_L(0); PG8_BAR; PG8_MMA(1, 0, At, B0); PG8_MMA(1, 1, At, B1); PG8_BAR; PG8_SCHED;
;             PG8_LDB(B0, 1, 0); PG8_LDB(B1, 1, 1); PG8_SCHED; PG8_LDA(At, 1, 0); PG8_STAGE(PG8_SA(0, 1), a2 + hstep, voffA);
;             PG8_WAIT_V(8); PG8_WAIT_L(0); PG8_BAR; PG8_MMA(0, 0, At, B0); PG8_MMA(0, 1, At, B1); PG8_BAR; PG8_SCHED;
;             PG8_LDA(At, 1, 1); PG8_STAGE(PG8_SB(1, 0), b3, voffB); PG8_STAGE(PG8_SB(1, 1), b3 + hstep, voffB); PG8_STAGE(PG8_SA(1, 0), a3, voffA);
;             PG8_WAIT_V(8); PG8_WAIT_L(0); PG8_BAR; PG8_MMA(1, 0, At, B0); PG8_MMA(1, 1, At, B1); PG8_BAR; PG8_SCHED;
.LBB0_501:
	s_add_i32 s80, s4, 2
	s_add_u32 s81, s0, 0x80
	s_addc_u32 s5, s1, 0
	s_cmp_eq_u32 s33, s4
	s_cselect_b32 s5, s23, s5
	s_cselect_b32 s4, s22, s81
	s_cselect_b32 s83, s41, s43
	s_cselect_b32 s82, s40, s42
	s_add_i32 s81, 0, 0x14000
	v_add_u32_e32 v148, s19, v164
	v_add_u32_e32 v162, s81, v164
	ds_read_b128 v[136:139], v148
	ds_read_b128 v[140:143], v148 offset:1024
	ds_read_b128 v[144:147], v148 offset:2048
	ds_read_b128 v[148:151], v148 offset:3072
	ds_read_b128 v[174:177], v162
	ds_read_b128 v[178:181], v162 offset:1024
	ds_read_b128 v[184:187], v162 offset:2048
	ds_read_b128 v[188:191], v162 offset:3072
	v_lshl_add_u64 v[162:163], s[0:1], 0, v[158:159]
	s_add_i32 m0, s45, 0xc000
	ds_read_b128 v[192:195], v170
	ds_read_b128 v[196:199], v170 offset:1024
	ds_read_b128 v[200:203], v170 offset:2048
	ds_read_b128 v[204:207], v170 offset:3072
	ds_read_b128 v[230:233], v170 offset:4096
	ds_read_b128 v[234:237], v170 offset:5120
	ds_read_b128 v[238:241], v170 offset:6144
	ds_read_b128 v[242:245], v170 offset:7168
	global_load_lds_dwordx4 v[162:163], off
	v_lshl_add_u64 v[162:163], s[0:1], 0, v[160:161]
	s_add_i32 m0, s45, 0xe000
	s_nop 0
	global_load_lds_dwordx4 v[162:163], off
	s_waitcnt vmcnt(8)
	s_waitcnt lgkmcnt(0)
	s_barrier
	s_setprio 1
	s_waitcnt lgkmcnt(0)
	v_mfma_f32_16x16x32_bf16 v[132:135], v[136:139], v[192:195], v[132:135]
	v_mfma_f32_16x16x32_bf16 v[116:119], v[136:139], v[200:203], v[116:119]
	v_mfma_f32_16x16x32_bf16 v[100:103], v[136:139], v[230:233], v[100:103]
	v_mfma_f32_16x16x32_bf16 v[84:87], v[136:139], v[238:241], v[84:87]
	v_mfma_f32_16x16x32_bf16 v[80:83], v[144:147], v[238:241], v[80:83]
	v_mfma_f32_16x16x32_bf16 v[96:99], v[144:147], v[230:233], v[96:99]
	v_mfma_f32_16x16x32_bf16 v[112:115], v[144:147], v[200:203], v[112:115]
	v_mfma_f32_16x16x32_bf16 v[128:131], v[144:147], v[192:195], v[128:131]
	v_mfma_f32_16x16x32_bf16 v[132:135], v[140:143], v[196:199], v[132:135]
	v_mfma_f32_16x16x32_bf16 v[116:119], v[140:143], v[204:207], v[116:119]
	v_mfma_f32_16x16x32_bf16 v[100:103], v[140:143], v[234:237], v[100:103]
	v_mfma_f32_16x16x32_bf16 v[84:87], v[140:143], v[242:245], v[84:87]
	v_mfma_f32_16x16x32_bf16 v[80:83], v[148:151], v[242:245], v[80:83]
	v_mfma_f32_16x16x32_bf16 v[96:99], v[148:151], v[234:237], v[96:99]
	v_mfma_f32_16x16x32_bf16 v[112:115], v[148:151], v[204:207], v[112:115]
	v_mfma_f32_16x16x32_bf16 v[128:131], v[148:151], v[196:199], v[128:131]
	s_setprio 0
	s_setprio 1
	v_mfma_f32_16x16x32_bf16 v[124:127], v[174:177], v[192:195], v[124:127]
	v_mfma_f32_16x16x32_bf16 v[108:111], v[174:177], v[200:203], v[108:111]
	v_mfma_f32_16x16x32_bf16 v[92:95], v[174:177], v[230:233], v[92:95]
	v_mfma_f32_16x16x32_bf16 v[76:79], v[174:177], v[238:241], v[76:79]
	v_mfma_f32_16x16x32_bf16 v[72:75], v[184:187], v[238:241], v[72:75]
	v_mfma_f32_16x16x32_bf16 v[88:91], v[184:187], v[230:233], v[88:91]
	v_mfma_f32_16x16x32_bf16 v[104:107], v[184:187], v[200:203], v[104:107]
	v_mfma_f32_16x16x32_bf16 v[120:123], v[184:187], v[192:195], v[120:123]
	v_mfma_f32_16x16x32_bf16 v[124:127], v[178:181], v[196:199], v[124:127]
	v_mfma_f32_16x16x32_bf16 v[108:111], v[178:181], v[204:207], v[108:111]
	v_mfma_f32_16x16x32_bf16 v[92:95], v[178:181], v[234:237], v[92:95]
	v_mfma_f32_16x16x32_bf16 v[76:79], v[178:181], v[242:245], v[76:79]
	v_mfma_f32_16x16x32_bf16 v[72:75], v[188:191], v[242:245], v[72:75]
	v_mfma_f32_16x16x32_bf16 v[88:91], v[188:191], v[234:237], v[88:91]
	v_mfma_f32_16x16x32_bf16 v[104:107], v[188:191], v[204:207], v[104:107]
	v_mfma_f32_16x16x32_bf16 v[120:123], v[188:191], v[196:199], v[120:123]
	s_setprio 0
	s_barrier
	s_add_i32 s84, s19, s44
	v_lshl_add_u64 v[162:163], s[82:83], 0, v[152:153]
	s_mov_b32 m0, s84
	ds_read_b128 v[192:195], v170 offset:16384
	ds_read_b128 v[196:199], v170 offset:17408
	ds_read_b128 v[200:203], v170 offset:18432
	ds_read_b128 v[204:207], v170 offset:19456
	ds_read_b128 v[230:233], v170 offset:20480
	ds_read_b128 v[234:237], v170 offset:21504
	ds_read_b128 v[238:241], v170 offset:22528
	ds_read_b128 v[242:245], v170 offset:23552
	global_load_lds_dwordx4 v[162:163], off
	s_add_i32 m0, s84, 0x2000
	v_lshl_add_u64 v[208:209], s[82:83], 0, v[156:157]
	s_add_u32 s82, s82, s48
	s_addc_u32 s83, s83, s49
	s_add_i32 s81, s81, s44
	global_load_lds_dwordx4 v[208:209], off
	v_lshl_add_u64 v[246:247], s[82:83], 0, v[152:153]
	s_mov_b32 m0, s81
	v_lshl_add_u64 v[248:249], s[82:83], 0, v[156:157]
	global_load_lds_dwordx4 v[246:247], off
	s_add_i32 m0, s81, 0x2000
	v_lshl_add_u64 v[216:217], s[4:5], 0, v[2:3]
	global_load_lds_dwordx4 v[248:249], off
	s_mov_b32 m0, s45
	v_lshl_add_u64 v[224:225], s[4:5], 0, v[154:155]
	global_load_lds_dwordx4 v[216:217], off
	s_mov_b32 m0, s46
	s_nop 0
	global_load_lds_dwordx4 v[224:225], off
	s_waitcnt vmcnt(8)
	s_waitcnt lgkmcnt(0)
	s_barrier
; #define PG8_STAGE(bufoff, gbase, voff) do { _Pragma("unroll") for (int _i = 0; _i < 2; ++_i) \
;         __builtin_amdgcn_global_load_lds((const unsigned*)((const char*)(gbase) + (voff)[_i]), (PG8_LAS unsigned*)(lds + (bufoff) + ldsw + _i * 8192), 16, 0, 0); } while (0)
; #define PG8_LDA(dst, b, h) do { _Pragma("unroll") for (int m = 0; m < 4; ++m) _Pragma("unroll") for (int k = 0; k < 2; ++k) dst[m][k] = *(const PG8_LAS bf16x8*)(lds + PG8_SA(b, h) + aoff + m * 2048 + k * 1024); } while (0)
; #define PG8_LDB(dst, b, h) do { _Pragma("unroll") for (int n = 0; n < 2; ++n) _Pragma("unroll") for (int k = 0; k < 2; ++k) dst[n][k] = *(const PG8_LAS bf16x8*)(lds + PG8_SB(b, h) + boff + n * 2048 + k * 1024); } while (0)
; #define PG8_MMA(ai, bj, At, Bt) do { __builtin_amdgcn_s_setprio(1); _Pragma("unroll") for (int m = 0; m < 4; ++m) _Pragma("unroll") for (int n = 0; n < 2; ++n) _Pragma("unroll") for (int k = 0; k < 2; ++k) \
;         acc[ai][bj][m][n] = __builtin_amdgcn_mfma_f32_16x16x32_bf16(Bt[n][k], At[m][k], acc[ai][bj][m][n], 0, 0, 0); __builtin_amdgcn_s_setprio(0); } while (0)
; #define PG8_WAIT_V(n) asm volatile("s_waitcnt vmcnt(" #n ")" ::: "memory")
; template <class Epi, class Sched, bool ALIGN_EPI = false, bool SP2 = false>
; __device__ __forceinline__ void gemm_phase(PG8_LAS unsigned char* lds, const Gemm g, const Sched& S, const Epi& E) {
;     ...
;             PG8_LDB(B0, 0, 0); PG8_LDB(B1, 0, 1); PG8_SCHED; PG8_LDA(At, 0, 0); PG8_STAGE(PG8_SA(1, 1), a1 + hstep, voffA);
;             PG8_WAIT_V(8); PG8_WAIT_L(0); PG8_BAR; PG8_MMA(0, 0, At, B0); PG8_MMA(0, 1, At, B1); PG8_BAR; PG8_SCHED;
;             PG8_LDA(At, 0, 1); PG8_STAGE(PG8_SB(0, 0), b2, voffB); PG8_STAGE(PG8_SB(0, 1), b2 + hstep, voffB); PG8_STAGE(PG8_SA(0, 0), a2, voffA);
;             PG8_WAIT_V(8); PG8_WAIT_L(0); PG8_BAR; PG8_MMA(1, 0, At, B0); PG8_MMA(1, 1, At, B1); PG8_BAR; PG8_SCHED;
;             PG8_LDB(B0, 1, 0); PG8_LDB(B1, 1, 1); PG8_SCHED; PG8_LDA(At, 1, 0); PG8_STAGE(PG8_SA(0, 1), a2 + hstep, voffA);
;             PG8_WAIT_V(8); PG8_WAIT_L(0); PG8_BAR; PG8_MMA(0, 0, At, B0); PG8_MMA(0, 1, At, B1); PG8_BAR; PG8_SCHED;
;             PG8_LDA(At, 1, 1); PG8_STAGE(PG8_SB(1, 0), b3, voffB); PG8_STAGE(PG8_SB(1, 1), b3 + hstep, voffB); PG8_STAGE(PG8_SA(1, 0), a3, voffA);
;             PG8_WAIT_V(8); PG8_WAIT_L(0); PG8_BAR; PG8_MMA(1, 0, At, B0); PG8_MMA(1, 1, At, B1); PG8_BAR; PG8_SCHED;
	s_setprio 1
	s_waitcnt lgkmcnt(0)
	v_mfma_f32_16x16x32_bf16 v[68:71], v[136:139], v[192:195], v[68:71]
	v_mfma_f32_16x16x32_bf16 v[52:55], v[136:139], v[200:203], v[52:55]
	v_mfma_f32_16x16x32_bf16 v[36:39], v[136:139], v[230:233], v[36:39]
	v_mfma_f32_16x16x32_bf16 v[20:23], v[136:139], v[238:241], v[20:23]
	v_mfma_f32_16x16x32_bf16 v[16:19], v[144:147], v[238:241], v[16:19]
	v_mfma_f32_16x16x32_bf16 v[32:35], v[144:147], v[230:233], v[32:35]
	v_mfma_f32_16x16x32_bf16 v[48:51], v[144:147], v[200:203], v[48:51]
	v_mfma_f32_16x16x32_bf16 v[64:67], v[144:147], v[192:195], v[64:67]
	v_mfma_f32_16x16x32_bf16 v[68:71], v[140:143], v[196:199], v[68:71]
	v_mfma_f32_16x16x32_bf16 v[52:55], v[140:143], v[204:207], v[52:55]
	v_mfma_f32_16x16x32_bf16 v[36:39], v[140:143], v[234:237], v[36:39]
	v_mfma_f32_16x16x32_bf16 v[20:23], v[140:143], v[242:245], v[20:23]
	v_mfma_f32_16x16x32_bf16 v[16:19], v[148:151], v[242:245], v[16:19]
	v_mfma_f32_16x16x32_bf16 v[32:35], v[148:151], v[234:237], v[32:35]
	v_mfma_f32_16x16x32_bf16 v[48:51], v[148:151], v[204:207], v[48:51]
	v_mfma_f32_16x16x32_bf16 v[64:67], v[148:151], v[196:199], v[64:67]
	s_setprio 0
	s_setprio 1
	v_mfma_f32_16x16x32_bf16 v[60:63], v[174:177], v[192:195], v[60:63]
	v_mfma_f32_16x16x32_bf16 v[44:47], v[174:177], v[200:203], v[44:47]
	v_mfma_f32_16x16x32_bf16 v[28:31], v[174:177], v[230:233], v[28:31]
	v_mfma_f32_16x16x32_bf16 v[12:15], v[174:177], v[238:241], v[12:15]
	v_mfma_f32_16x16x32_bf16 v[8:11], v[184:187], v[238:241], v[8:11]
	v_mfma_f32_16x16x32_bf16 v[24:27], v[184:187], v[230:233], v[24:27]
	v_mfma_f32_16x16x32_bf16 v[40:43], v[184:187], v[200:203], v[40:43]
	v_mfma_f32_16x16x32_bf16 v[56:59], v[184:187], v[192:195], v[56:59]
	v_mfma_f32_16x16x32_bf16 v[60:63], v[178:181], v[196:199], v[60:63]
	v_mfma_f32_16x16x32_bf16 v[44:47], v[178:181], v[204:207], v[44:47]
	v_mfma_f32_16x16x32_bf16 v[28:31], v[178:181], v[234:237], v[28:31]
	v_mfma_f32_16x16x32_bf16 v[12:15], v[178:181], v[242:245], v[12:15]
	v_mfma_f32_16x16x32_bf16 v[8:11], v[188:191], v[242:245], v[8:11]
	v_mfma_f32_16x16x32_bf16 v[24:27], v[188:191], v[234:237], v[24:27]
	v_mfma_f32_16x16x32_bf16 v[40:43], v[188:191], v[204:207], v[40:43]
	v_mfma_f32_16x16x32_bf16 v[56:59], v[188:191], v[196:199], v[56:59]
	s_setprio 0
	s_barrier
	s_add_i32 s81, 0, 0x1c000
	v_add_u32_e32 v148, s91, v164
	v_add_u32_e32 v173, s81, v164
	ds_read_b128 v[136:139], v148
	ds_read_b128 v[140:143], v148 offset:1024
	ds_read_b128 v[144:147], v148 offset:2048
	ds_read_b128 v[148:151], v148 offset:3072
	ds_read_b128 v[174:177], v173
	ds_read_b128 v[178:181], v173 offset:1024
	ds_read_b128 v[184:187], v173 offset:2048
	ds_read_b128 v[188:191], v173 offset:3072
	s_add_u32 s4, s4, s48
	s_addc_u32 s5, s5, s49
	s_mov_b32 m0, s47
	v_lshl_add_u64 v[226:227], s[4:5], 0, v[2:3]
	ds_read_b128 v[192:195], v170 offset:32768
	ds_read_b128 v[196:199], v170 offset:33792
	ds_read_b128 v[200:203], v170 offset:34816
	ds_read_b128 v[204:207], v170 offset:35840
	ds_read_b128 v[230:233], v170 offset:36864
	ds_read_b128 v[234:237], v170 offset:37888
	ds_read_b128 v[238:241], v170 offset:38912
	ds_read_b128 v[242:245], v170 offset:39936
	global_load_lds_dwordx4 v[226:227], off
	v_lshl_add_u64 v[226:227], s[4:5], 0, v[154:155]
	s_mov_b32 m0, s52
	s_nop 0
	global_load_lds_dwordx4 v[226:227], off
	s_waitcnt vmcnt(8)
	s_waitcnt lgkmcnt(0)
	s_barrier
	s_setprio 1
	s_waitcnt lgkmcnt(0)
	v_mfma_f32_16x16x32_bf16 v[132:135], v[136:139], v[192:195], v[132:135]
	v_mfma_f32_16x16x32_bf16 v[116:119], v[136:139], v[200:203], v[116:119]
	v_mfma_f32_16x16x32_bf16 v[100:103], v[136:139], v[230:233], v[100:103]
	v_mfma_f32_16x16x32_bf16 v[84:87], v[136:139], v[238:241], v[84:87]
	v_mfma_f32_16x16x32_bf16 v[80:83], v[144:147], v[238:241], v[80:83]
	v_mfma_f32_16x16x32_bf16 v[96:99], v[144:147], v[230:233], v[96:99]
	v_mfma_f32_16x16x32_bf16 v[112:115], v[144:147], v[200:203], v[112:115]
	v_mfma_f32_16x16x32_bf16 v[128:131], v[144:147], v[192:195], v[128:131]
	v_mfma_f32_16x16x32_bf16 v[132:135], v[140:143], v[196:199], v[132:135]
	v_mfma_f32_16x16x32_bf16 v[116:119], v[140:143], v[204:207], v[116:119]
	v_mfma_f32_16x16x32_bf16 v[100:103], v[140:143], v[234:237], v[100:103]
	v_mfma_f32_16x16x32_bf16 v[84:87], v[140:143], v[242:245], v[84:87]
	v_mfma_f32_16x16x32_bf16 v[80:83], v[148:151], v[242:245], v[80:83]
	v_mfma_f32_16x16x32_bf16 v[96:99], v[148:151], v[234:237], v[96:99]
	v_mfma_f32_16x16x32_bf16 v[112:115], v[148:151], v[204:207], v[112:115]
	v_mfma_f32_16x16x32_bf16 v[128:131], v[148:151], v[196:199], v[128:131]
	s_setprio 0
	s_setprio 1
	v_mfma_f32_16x16x32_bf16 v[124:127], v[174:177], v[192:195], v[124:127]
	v_mfma_f32_16x16x32_bf16 v[108:111], v[174:177], v[200:203], v[108:111]
	v_mfma_f32_16x16x32_bf16 v[92:95], v[174:177], v[230:233], v[92:95]
	v_mfma_f32_16x16x32_bf16 v[76:79], v[174:177], v[238:241], v[76:79]
	v_mfma_f32_16x16x32_bf16 v[72:75], v[184:187], v[238:241], v[72:75]
	v_mfma_f32_16x16x32_bf16 v[88:91], v[184:187], v[230:233], v[88:91]
	v_mfma_f32_16x16x32_bf16 v[104:107], v[184:187], v[200:203], v[104:107]
	v_mfma_f32_16x16x32_bf16 v[120:123], v[184:187], v[192:195], v[120:123]
	v_mfma_f32_16x16x32_bf16 v[124:127], v[178:181], v[196:199], v[124:127]
	v_mfma_f32_16x16x32_bf16 v[108:111], v[178:181], v[204:207], v[108:111]
	v_mfma_f32_16x16x32_bf16 v[92:95], v[178:181], v[234:237], v[92:95]
	v_mfma_f32_16x16x32_bf16 v[76:79], v[178:181], v[242:245], v[76:79]
	v_mfma_f32_16x16x32_bf16 v[72:75], v[188:191], v[242:245], v[72:75]
	v_mfma_f32_16x16x32_bf16 v[88:91], v[188:191], v[234:237], v[88:91]
	v_mfma_f32_16x16x32_bf16 v[104:107], v[188:191], v[204:207], v[104:107]
	v_mfma_f32_16x16x32_bf16 v[120:123], v[188:191], v[196:199], v[120:123]
	s_setprio 0
	s_barrier
; #define PG8_STAGE(bufoff, gbase, voff) do { _Pragma("unroll") for (int _i = 0; _i < 2; ++_i) \
;         __builtin_amdgcn_global_load_lds((const unsigned*)((const char*)(gbase) + (voff)[_i]), (PG8_LAS unsigned*)(lds + (bufoff) + ldsw + _i * 8192), 16, 0, 0); } while (0)
; #define PG8_LDA(dst, b, h) do { _Pragma("unroll") for (int m = 0; m < 4; ++m) _Pragma("unroll") for (int k = 0; k < 2; ++k) dst[m][k] = *(const PG8_LAS bf16x8*)(lds + PG8_SA(b, h) + aoff + m * 2048 + k * 1024); } while (0)
; #define PG8_WAIT_V(n) asm volatile("s_waitcnt vmcnt(" #n ")" ::: "memory")
; #define PG8_BAR __builtin_amdgcn_s_barrier()
; template <class Epi, class Sched, bool ALIGN_EPI = false, bool SP2 = false>
; __device__ __forceinline__ void gemm_phase(PG8_LAS unsigned char* lds, const Gemm g, const Sched& S, const Epi& E) {
;     ...
;         for (int t = 0; t < nt; t += 2) {
;             if constexpr (Epi::KHOOK) { if ((t & 7) == 0 && t != 0) E.khook(acc, t >> 3, wr, fr, lds); }
;             const bool last = (t == nt - 2);
;             const char* a1 = cA + (size_t)(t + 1) * kstep;
;             const char* a2 = last ? nA : cA + (size_t)(t + 2) * kstep; const char* b2 = last ? nB : cB + (size_t)(t + 2) * kstep;
;             const char* a3 = a2 + kstep; const char* b3 = b2 + kstep;
;             if (last && has_next) S.a_ready(nxt);
;             if constexpr (SP2) {
;             PG8_LDB(B0, 0, 0); PG8_LDB(B1, 0, 1); PG8_SCHED; PG8_LDA(At, 0, 0); PG8_STAGE(PG8_SA(1, 1), a1 + hstep, voffA);
;             PG8_WAIT_V(8); PG8_WAIT_L(0); PG8_BAR; PG8_MMA(0, 0, At, B0); PG8_MMA(0, 1, At, B1); PG8_BAR; PG8_SCHED;
;             PG8_LDA(At, 0, 1); PG8_STAGE(PG8_SB(0, 0), b2, voffB); PG8_STAGE(PG8_SB(0, 1), b2 + hstep, voffB); PG8_STAGE(PG8_SA(0, 0), a2, voffA);
;             PG8_WAIT_V(8); PG8_WAIT_L(0); PG8_BAR; PG8_MMA(1, 0, At, B0); PG8_MMA(1, 1, At, B1); PG8_BAR; PG8_SCHED;
;             PG8_LDB(B0, 1, 0); PG8_LDB(B1, 1, 1); PG8_SCHED; PG8_LDA(At, 1, 0); PG8_STAGE(PG8_SA(0, 1), a2 + hstep, voffA);
;             PG8_WAIT_V(8); PG8_WAIT_L(0); PG8_BAR; PG8_MMA(0, 0, At, B0); PG8_MMA(0, 1, At, B1); PG8_BAR; PG8_SCHED;
;             PG8_LDA(At, 1, 1); PG8_STAGE(PG8_SB(1, 0), b3, voffB); PG8_STAGE(PG8_SB(1, 1), b3 + hstep, voffB); PG8_STAGE(PG8_SA(1, 0), a3, voffA);
;             PG8_WAIT_V(8); PG8_WAIT_L(0); PG8_BAR; PG8_MMA(1, 0, At, B0); PG8_MMA(1, 1, At, B1); PG8_BAR; PG8_SCHED;
	s_add_i32 s4, s91, s44
	v_lshl_add_u64 v[162:163], v[162:163], 0, s[24:25]
	s_mov_b32 m0, s4
	ds_read_b128 v[192:195], v170 offset:49152
	ds_read_b128 v[196:199], v170 offset:50176
	ds_read_b128 v[200:203], v170 offset:51200
	ds_read_b128 v[204:207], v170 offset:52224
	ds_read_b128 v[230:233], v170 offset:53248
	ds_read_b128 v[234:237], v170 offset:54272
	ds_read_b128 v[238:241], v170 offset:55296
	ds_read_b128 v[242:245], v170 offset:56320
	global_load_lds_dwordx4 v[162:163], off
	v_lshl_add_u64 v[162:163], v[208:209], 0, s[24:25]
	s_add_i32 m0, s4, 0x2000
	s_add_i32 s4, s81, s44
	global_load_lds_dwordx4 v[162:163], off
	v_lshl_add_u64 v[162:163], v[246:247], 0, s[24:25]
	s_mov_b32 m0, s4
	s_nop 0
	global_load_lds_dwordx4 v[162:163], off
	v_lshl_add_u64 v[162:163], v[248:249], 0, s[24:25]
	s_add_i32 m0, s4, 0x2000
	s_nop 0
	global_load_lds_dwordx4 v[162:163], off
	v_lshl_add_u64 v[162:163], v[216:217], 0, s[24:25]
	s_mov_b32 m0, s53
	s_nop 0
	global_load_lds_dwordx4 v[162:163], off
	v_lshl_add_u64 v[162:163], v[224:225], 0, s[24:25]
	s_mov_b32 m0, s72
	s_nop 0
	global_load_lds_dwordx4 v[162:163], off
	s_waitcnt vmcnt(8)
	s_waitcnt lgkmcnt(0)
	s_barrier
	s_setprio 1
	s_waitcnt lgkmcnt(0)
	v_mfma_f32_16x16x32_bf16 v[68:71], v[136:139], v[192:195], v[68:71]
	v_mfma_f32_16x16x32_bf16 v[52:55], v[136:139], v[200:203], v[52:55]
	v_mfma_f32_16x16x32_bf16 v[36:39], v[136:139], v[230:233], v[36:39]
	v_mfma_f32_16x16x32_bf16 v[20:23], v[136:139], v[238:241], v[20:23]
	v_mfma_f32_16x16x32_bf16 v[16:19], v[144:147], v[238:241], v[16:19]
	v_mfma_f32_16x16x32_bf16 v[32:35], v[144:147], v[230:233], v[32:35]
	v_mfma_f32_16x16x32_bf16 v[48:51], v[144:147], v[200:203], v[48:51]
	v_mfma_f32_16x16x32_bf16 v[64:67], v[144:147], v[192:195], v[64:67]
	v_mfma_f32_16x16x32_bf16 v[68:71], v[140:143], v[196:199], v[68:71]
	v_mfma_f32_16x16x32_bf16 v[52:55], v[140:143], v[204:207], v[52:55]
	v_mfma_f32_16x16x32_bf16 v[36:39], v[140:143], v[234:237], v[36:39]
	v_mfma_f32_16x16x32_bf16 v[20:23], v[140:143], v[242:245], v[20:23]
	v_mfma_f32_16x16x32_bf16 v[16:19], v[148:151], v[242:245], v[16:19]
	v_mfma_f32_16x16x32_bf16 v[32:35], v[148:151], v[234:237], v[32:35]
	v_mfma_f32_16x16x32_bf16 v[48:51], v[148:151], v[204:207], v[48:51]
	v_mfma_f32_16x16x32_bf16 v[64:67], v[148:151], v[196:199], v[64:67]
	s_setprio 0
	s_setprio 1
	v_mfma_f32_16x16x32_bf16 v[60:63], v[174:177], v[192:195], v[60:63]
	v_mfma_f32_16x16x32_bf16 v[44:47], v[174:177], v[200:203], v[44:47]
	v_mfma_f32_16x16x32_bf16 v[28:31], v[174:177], v[230:233], v[28:31]
	v_mfma_f32_16x16x32_bf16 v[12:15], v[174:177], v[238:241], v[12:15]
	v_mfma_f32_16x16x32_bf16 v[8:11], v[184:187], v[238:241], v[8:11]
	v_mfma_f32_16x16x32_bf16 v[24:27], v[184:187], v[230:233], v[24:27]
	v_mfma_f32_16x16x32_bf16 v[40:43], v[184:187], v[200:203], v[40:43]
	v_mfma_f32_16x16x32_bf16 v[56:59], v[184:187], v[192:195], v[56:59]
	v_mfma_f32_16x16x32_bf16 v[60:63], v[178:181], v[196:199], v[60:63]
	v_mfma_f32_16x16x32_bf16 v[44:47], v[178:181], v[204:207], v[44:47]
	v_mfma_f32_16x16x32_bf16 v[28:31], v[178:181], v[234:237], v[28:31]
	v_mfma_f32_16x16x32_bf16 v[12:15], v[178:181], v[242:245], v[12:15]
	v_mfma_f32_16x16x32_bf16 v[8:11], v[188:191], v[242:245], v[8:11]
	v_mfma_f32_16x16x32_bf16 v[24:27], v[188:191], v[234:237], v[24:27]
	v_mfma_f32_16x16x32_bf16 v[40:43], v[188:191], v[204:207], v[40:43]
	v_mfma_f32_16x16x32_bf16 v[56:59], v[188:191], v[196:199], v[56:59]
	s_setprio 0
	s_barrier
	s_add_u32 s0, s0, 0x100
	s_addc_u32 s1, s1, 0
	s_add_u32 s42, s42, 0x100
	s_addc_u32 s43, s43, 0
	s_cmp_ge_u32 s80, s9
	s_mov_b32 s4, s80
	s_cbranch_scc0 .LBB0_501
